# static priority raise for the trailing wave half over each GEMM K-loop (no per-block flips, no early barrier); stacked on stack18
# speedup vs baseline: 1.0086x; 1.0017x over previous
; #define PG8_STAGE(bufoff, gbase, voff) do { _Pragma("unroll") for (int _i = 0; _i < 2; ++_i) \
;         __builtin_amdgcn_global_load_lds((const unsigned*)((const char*)(gbase) + (voff)[_i]), (PG8_LAS unsigned*)(lds + (bufoff) + ldsw + _i * 8192), 16, 0, 0); } while (0)
; #define PG8_LDA(dst, b, h) do { _Pragma("unroll") for (int m = 0; m < 4; ++m) _Pragma("unroll") for (int k = 0; k < 2; ++k) dst[m][k] = *(const PG8_LAS bf16x8*)(lds + PG8_SA(b, h) + aoff + m * 2048 + k * 1024); } while (0)
; #define PG8_LDB(dst, b, h) do { _Pragma("unroll") for (int n = 0; n < 2; ++n) _Pragma("unroll") for (int k = 0; k < 2; ++k) dst[n][k] = *(const PG8_LAS bf16x8*)(lds + PG8_SB(b, h) + boff + n * 2048 + k * 1024); } while (0)
; #define PG8_WAIT_V(n) asm volatile("s_waitcnt vmcnt(" #n ")" ::: "memory")
; #define PG8_WAIT_L(n) asm volatile("s_waitcnt lgkmcnt(" #n ")" ::: "memory")
; #define PG8_BAR __builtin_amdgcn_s_barrier()
; template <class Epi, class Sched, bool ALIGN_EPI = false, bool SP2 = false>
; __device__ __forceinline__ void gemm_phase(PG8_LAS unsigned char* lds, const Gemm g, const Sched& S, const Epi& E) {
;     ...
;     for (;;) {
;         const bool has_next = S.next(ui + 1, nxt);
;         const char* nA = has_next ? (const char*)g.A + (size_t)nxt.pm * tstep : cA; const char* nB = has_next ? (const char*)g.Bt + (size_t)nxt.pn * tstep : cB;
;         for (int t = 0; t < nt; t += 2) {
;             const bool last = (t == nt - 2);
;             const char* a1 = cA + (size_t)(t + 1) * kstep;
;             const char* a2 = last ? nA : cA + (size_t)(t + 2) * kstep; const char* b2 = last ? nB : cB + (size_t)(t + 2) * kstep;
;             const char* a3 = a2 + kstep; const char* b3 = b2 + kstep;
;             if (last && has_next) S.a_ready(nxt);
;             if constexpr (SP2) {
;             PG8_LDB(B0, 0, 0); PG8_LDB(B1, 0, 1); PG8_SCHED; PG8_LDA(At, 0, 0); PG8_STAGE(PG8_SA(1, 1), a1 + hstep, voffA);
;             PG8_WAIT_V(8); PG8_WAIT_L(0); PG8_BAR; PG8_MMA(0, 0, At, B0); PG8_MMA(0, 1, At, B1); PG8_BAR; PG8_SCHED;
;     ...
; #pragma unroll
;         for (int a = 0; a < 2; ++a)
; #pragma unroll
;             for (int b = 0; b < 2; ++b)
; #pragma unroll
;                 for (int m = 0; m < 4; ++m)
; #pragma unroll
;                     for (int n = 0; n < 2; ++n) acc[a][b][m][n] = (f32x4){0.f, 0.f, 0.f, 0.f};
;         cur = nxt; cA = nA; cB = nB; ++ui;
.LBB0_163:
	s_ashr_i32 s51, s50, 31
	s_lshl_b64 s[36:37], s[50:51], 19
	s_add_u32 s62, s2, s36
	s_addc_u32 s63, s14, s37
	s_and_b64 s[36:37], s[40:41], exec
	s_cselect_b32 s36, s63, s65
	s_cselect_b32 s37, s62, s64
	s_ashr_i32 s53, s52, 31
	s_lshl_b64 s[66:67], s[52:53], 19
	s_add_u32 s66, s15, s66
	s_addc_u32 s67, s16, s67
	s_and_b64 s[72:73], s[40:41], exec
	s_cselect_b32 s51, s67, s59
	s_cselect_b32 s53, s66, s58
	s_add_u32 s72, s64, 0x40080
	s_addc_u32 s73, s65, 0
	s_add_u32 s92, s58, 0x100
	v_mov_b64_e32 v[0:1], 0
	s_addc_u32 s93, s59, 0
	s_mov_b32 s94, -2
	v_mov_b64_e32 v[2:3], 0
	v_mov_b64_e32 v[4:5], 0
	v_mov_b64_e32 v[6:7], 0
	v_mov_b64_e32 v[8:9], 0
	v_mov_b64_e32 v[10:11], 0
	v_mov_b64_e32 v[12:13], 0
	v_mov_b64_e32 v[14:15], 0
	v_mov_b64_e32 v[16:17], 0
	v_mov_b64_e32 v[18:19], 0
	v_mov_b64_e32 v[20:21], 0
	v_mov_b64_e32 v[22:23], 0
	v_mov_b64_e32 v[24:25], 0
	v_mov_b64_e32 v[26:27], 0
	v_mov_b64_e32 v[28:29], 0
	v_mov_b64_e32 v[30:31], 0
	v_mov_b64_e32 v[32:33], 0
	v_mov_b64_e32 v[34:35], 0
	v_mov_b64_e32 v[36:37], 0
	v_mov_b64_e32 v[38:39], 0
	v_mov_b64_e32 v[40:41], 0
	v_mov_b64_e32 v[42:43], 0
	v_mov_b64_e32 v[44:45], 0
	v_mov_b64_e32 v[46:47], 0
	v_mov_b64_e32 v[48:49], 0
	v_mov_b64_e32 v[50:51], 0
	v_mov_b64_e32 v[52:53], 0
	v_mov_b64_e32 v[54:55], 0
	v_mov_b64_e32 v[56:57], 0
	v_mov_b64_e32 v[58:59], 0
	v_mov_b64_e32 v[60:61], 0
	v_mov_b64_e32 v[62:63], 0
	v_mov_b64_e32 v[64:65], 0
	v_mov_b64_e32 v[66:67], 0
	v_mov_b64_e32 v[68:69], 0
	v_mov_b64_e32 v[70:71], 0
	v_mov_b64_e32 v[72:73], 0
	v_mov_b64_e32 v[74:75], 0
	v_mov_b64_e32 v[76:77], 0
	v_mov_b64_e32 v[78:79], 0
	v_mov_b64_e32 v[80:81], 0
	v_mov_b64_e32 v[82:83], 0
	v_mov_b64_e32 v[84:85], 0
	v_mov_b64_e32 v[86:87], 0
	v_mov_b64_e32 v[88:89], 0
	v_mov_b64_e32 v[90:91], 0
	v_mov_b64_e32 v[92:93], 0
	v_mov_b64_e32 v[94:95], 0
	v_mov_b64_e32 v[96:97], 0
	v_mov_b64_e32 v[98:99], 0
	v_mov_b64_e32 v[100:101], 0
	v_mov_b64_e32 v[102:103], 0
	v_mov_b64_e32 v[104:105], 0
	v_mov_b64_e32 v[106:107], 0
	v_mov_b64_e32 v[108:109], 0
	v_mov_b64_e32 v[110:111], 0
	v_mov_b64_e32 v[112:113], 0
	v_mov_b64_e32 v[114:115], 0
	v_mov_b64_e32 v[116:117], 0
	v_mov_b64_e32 v[118:119], 0
	v_mov_b64_e32 v[120:121], 0
	v_mov_b64_e32 v[122:123], 0
	v_mov_b64_e32 v[124:125], 0
	v_mov_b64_e32 v[126:127], 0
	s_and_b64 s[98:99], exec, s[48:49]
	s_cbranch_scc1 .Lsp_1
	s_setprio 1
.Lsp_1:
.LBB0_164:
	s_add_u32 s58, s72, 0xfffc0080
	s_addc_u32 s59, s73, -1
	s_add_i32 s84, 0, 0x10000
	s_cmp_eq_u32 s94, 12
	s_cselect_b32 s65, s36, s59
	s_cselect_b32 s64, s37, s58
	v_add_u32_e32 v140, s84, v146
	s_cselect_b32 s59, s51, s93
	s_cselect_b32 s58, s53, s92
	s_add_i32 s96, 0, 0x14000
	ds_read_b128 v[142:145], v140
	ds_read_b128 v[150:153], v140 offset:1024
	ds_read_b128 v[154:157], v140 offset:2048
	ds_read_b128 v[158:161], v140 offset:3072
	v_add_u32_e32 v140, s96, v146
	ds_read_b128 v[162:165], v140
	ds_read_b128 v[166:169], v140 offset:1024
	ds_read_b128 v[170:173], v140 offset:2048
	ds_read_b128 v[174:177], v140 offset:3072
	v_lshl_add_u64 v[186:187], s[72:73], 0, v[136:137]
	s_add_i32 m0, s19, 0xc000
	ds_read_b128 v[178:181], v148
	ds_read_b128 v[182:185], v148 offset:1024
	ds_read_b128 v[190:193], v148 offset:2048
	ds_read_b128 v[194:197], v148 offset:3072
	ds_read_b128 v[198:201], v148 offset:4096
	ds_read_b128 v[202:205], v148 offset:5120
	ds_read_b128 v[206:209], v148 offset:6144
	ds_read_b128 v[228:231], v148 offset:7168
	global_load_lds_dwordx4 v[186:187], off
	v_lshl_add_u64 v[186:187], s[72:73], 0, v[138:139]
	s_add_i32 m0, s19, 0xe000
	s_nop 0
	global_load_lds_dwordx4 v[186:187], off
	s_waitcnt vmcnt(8)
	s_waitcnt lgkmcnt(0)
	s_barrier
	s_waitcnt lgkmcnt(0)
	v_mfma_f32_16x16x32_bf16 v[124:127], v[142:145], v[178:181], v[124:127]
	v_mfma_f32_16x16x32_bf16 v[120:123], v[154:157], v[178:181], v[120:123]
	v_mfma_f32_16x16x32_bf16 v[116:119], v[142:145], v[190:193], v[116:119]
	v_mfma_f32_16x16x32_bf16 v[112:115], v[154:157], v[190:193], v[112:115]
	v_mfma_f32_16x16x32_bf16 v[108:111], v[142:145], v[198:201], v[108:111]
	v_mfma_f32_16x16x32_bf16 v[104:107], v[154:157], v[198:201], v[104:107]
	v_mfma_f32_16x16x32_bf16 v[100:103], v[142:145], v[206:209], v[100:103]
	v_mfma_f32_16x16x32_bf16 v[96:99], v[154:157], v[206:209], v[96:99]
	v_mfma_f32_16x16x32_bf16 v[124:127], v[150:153], v[182:185], v[124:127]
	v_mfma_f32_16x16x32_bf16 v[120:123], v[158:161], v[182:185], v[120:123]
	v_mfma_f32_16x16x32_bf16 v[116:119], v[150:153], v[194:197], v[116:119]
	v_mfma_f32_16x16x32_bf16 v[112:115], v[158:161], v[194:197], v[112:115]
	v_mfma_f32_16x16x32_bf16 v[108:111], v[150:153], v[202:205], v[108:111]
	v_mfma_f32_16x16x32_bf16 v[104:107], v[158:161], v[202:205], v[104:107]
	v_mfma_f32_16x16x32_bf16 v[100:103], v[150:153], v[228:231], v[100:103]
	v_mfma_f32_16x16x32_bf16 v[96:99], v[158:161], v[228:231], v[96:99]
	v_mfma_f32_16x16x32_bf16 v[92:95], v[162:165], v[178:181], v[92:95]
	v_mfma_f32_16x16x32_bf16 v[88:91], v[170:173], v[178:181], v[88:91]
	v_mfma_f32_16x16x32_bf16 v[84:87], v[162:165], v[190:193], v[84:87]
	v_mfma_f32_16x16x32_bf16 v[80:83], v[170:173], v[190:193], v[80:83]
	v_mfma_f32_16x16x32_bf16 v[76:79], v[162:165], v[198:201], v[76:79]
	v_mfma_f32_16x16x32_bf16 v[72:75], v[170:173], v[198:201], v[72:75]
	v_mfma_f32_16x16x32_bf16 v[68:71], v[162:165], v[206:209], v[68:71]
	v_mfma_f32_16x16x32_bf16 v[64:67], v[170:173], v[206:209], v[64:67]
	v_mfma_f32_16x16x32_bf16 v[92:95], v[166:169], v[182:185], v[92:95]
	v_mfma_f32_16x16x32_bf16 v[88:91], v[174:177], v[182:185], v[88:91]
	v_mfma_f32_16x16x32_bf16 v[84:87], v[166:169], v[194:197], v[84:87]
	v_mfma_f32_16x16x32_bf16 v[80:83], v[174:177], v[194:197], v[80:83]
	v_mfma_f32_16x16x32_bf16 v[76:79], v[166:169], v[202:205], v[76:79]
	v_mfma_f32_16x16x32_bf16 v[72:75], v[174:177], v[202:205], v[72:75]
	v_mfma_f32_16x16x32_bf16 v[68:71], v[166:169], v[228:231], v[68:71]
	v_mfma_f32_16x16x32_bf16 v[64:67], v[174:177], v[228:231], v[64:67]
	s_barrier
; #define PG8_STAGE(bufoff, gbase, voff) do { _Pragma("unroll") for (int _i = 0; _i < 2; ++_i) \
;         __builtin_amdgcn_global_load_lds((const unsigned*)((const char*)(gbase) + (voff)[_i]), (PG8_LAS unsigned*)(lds + (bufoff) + ldsw + _i * 8192), 16, 0, 0); } while (0)
; #define PG8_LDA(dst, b, h) do { _Pragma("unroll") for (int m = 0; m < 4; ++m) _Pragma("unroll") for (int k = 0; k < 2; ++k) dst[m][k] = *(const PG8_LAS bf16x8*)(lds + PG8_SA(b, h) + aoff + m * 2048 + k * 1024); } while (0)
; #define PG8_LDB(dst, b, h) do { _Pragma("unroll") for (int n = 0; n < 2; ++n) _Pragma("unroll") for (int k = 0; k < 2; ++k) dst[n][k] = *(const PG8_LAS bf16x8*)(lds + PG8_SB(b, h) + boff + n * 2048 + k * 1024); } while (0)
; #define PG8_MMA(ai, bj, At, Bt) do { __builtin_amdgcn_s_setprio(1); _Pragma("unroll") for (int m = 0; m < 4; ++m) _Pragma("unroll") for (int n = 0; n < 2; ++n) _Pragma("unroll") for (int k = 0; k < 2; ++k) \
;         acc[ai][bj][m][n] = __builtin_amdgcn_mfma_f32_16x16x32_bf16(Bt[n][k], At[m][k], acc[ai][bj][m][n], 0, 0, 0); __builtin_amdgcn_s_setprio(0); } while (0)
; #define PG8_WAIT_V(n) asm volatile("s_waitcnt vmcnt(" #n ")" ::: "memory")
; #define PG8_WAIT_L(n) asm volatile("s_waitcnt lgkmcnt(" #n ")" ::: "memory")
; #define PG8_BAR __builtin_amdgcn_s_barrier()
; #define PG8_SCHED __builtin_amdgcn_sched_barrier(0)
; template <class Epi, class Sched, bool ALIGN_EPI = false, bool SP2 = false>
; __device__ __forceinline__ void gemm_phase(PG8_LAS unsigned char* lds, const Gemm g, const Sched& S, const Epi& E) {
;     ...
;             PG8_LDA(At, 0, 1); PG8_STAGE(PG8_SB(0, 0), b2, voffB); PG8_STAGE(PG8_SB(0, 1), b2 + hstep, voffB); PG8_STAGE(PG8_SA(0, 0), a2, voffA);
;             PG8_WAIT_V(8); PG8_WAIT_L(0); PG8_BAR; PG8_MMA(1, 0, At, B0); PG8_MMA(1, 1, At, B1); PG8_BAR; PG8_SCHED;
;             PG8_LDB(B0, 1, 0); PG8_LDB(B1, 1, 1); PG8_SCHED; PG8_LDA(At, 1, 0); PG8_STAGE(PG8_SA(0, 1), a2 + hstep, voffA);
;             PG8_WAIT_V(8); PG8_WAIT_L(0); PG8_BAR; PG8_MMA(0, 0, At, B0); PG8_MMA(0, 1, At, B1); PG8_BAR; PG8_SCHED;
	s_add_i32 s84, s84, s18
	v_lshl_add_u64 v[186:187], s[58:59], 0, v[128:129]
	s_mov_b32 m0, s84
	ds_read_b128 v[178:181], v148 offset:16384
	ds_read_b128 v[182:185], v148 offset:17408
	ds_read_b128 v[190:193], v148 offset:18432
	ds_read_b128 v[194:197], v148 offset:19456
	ds_read_b128 v[198:201], v148 offset:20480
	ds_read_b128 v[202:205], v148 offset:21504
	ds_read_b128 v[206:209], v148 offset:22528
	ds_read_b128 v[228:231], v148 offset:23552
	global_load_lds_dwordx4 v[186:187], off
	s_add_i32 m0, s84, 0x2000
	s_add_u32 s84, s58, 0x40000
	v_lshl_add_u64 v[188:189], s[58:59], 0, v[130:131]
	s_addc_u32 s85, s59, 0
	s_add_i32 s96, s96, s18
	global_load_lds_dwordx4 v[188:189], off
	v_lshl_add_u64 v[210:211], s[84:85], 0, v[128:129]
	s_mov_b32 m0, s96
	v_lshl_add_u64 v[232:233], s[64:65], 0, v[132:133]
	global_load_lds_dwordx4 v[210:211], off
	v_lshl_add_u64 v[210:211], s[84:85], 0, v[130:131]
	s_add_i32 m0, s96, 0x2000
	s_nop 0
	global_load_lds_dwordx4 v[210:211], off
	v_lshl_add_u64 v[210:211], s[64:65], 0, v[134:135]
	s_mov_b32 m0, s19
	s_nop 0
	global_load_lds_dwordx4 v[210:211], off
	s_mov_b32 m0, s20
	s_nop 0
	global_load_lds_dwordx4 v[232:233], off
	s_waitcnt vmcnt(8)
	s_waitcnt lgkmcnt(0)
	s_barrier
	s_waitcnt lgkmcnt(0)
	v_mfma_f32_16x16x32_bf16 v[60:63], v[142:145], v[178:181], v[60:63]
	v_mfma_f32_16x16x32_bf16 v[56:59], v[154:157], v[178:181], v[56:59]
	v_mfma_f32_16x16x32_bf16 v[52:55], v[142:145], v[190:193], v[52:55]
	v_mfma_f32_16x16x32_bf16 v[48:51], v[154:157], v[190:193], v[48:51]
	v_mfma_f32_16x16x32_bf16 v[44:47], v[142:145], v[198:201], v[44:47]
	v_mfma_f32_16x16x32_bf16 v[40:43], v[154:157], v[198:201], v[40:43]
	v_mfma_f32_16x16x32_bf16 v[36:39], v[142:145], v[206:209], v[36:39]
	v_mfma_f32_16x16x32_bf16 v[32:35], v[154:157], v[206:209], v[32:35]
	v_mfma_f32_16x16x32_bf16 v[60:63], v[150:153], v[182:185], v[60:63]
	v_mfma_f32_16x16x32_bf16 v[56:59], v[158:161], v[182:185], v[56:59]
	v_mfma_f32_16x16x32_bf16 v[52:55], v[150:153], v[194:197], v[52:55]
	v_mfma_f32_16x16x32_bf16 v[48:51], v[158:161], v[194:197], v[48:51]
	v_mfma_f32_16x16x32_bf16 v[44:47], v[150:153], v[202:205], v[44:47]
	v_mfma_f32_16x16x32_bf16 v[40:43], v[158:161], v[202:205], v[40:43]
	v_mfma_f32_16x16x32_bf16 v[36:39], v[150:153], v[228:231], v[36:39]
	v_mfma_f32_16x16x32_bf16 v[32:35], v[158:161], v[228:231], v[32:35]
	v_mfma_f32_16x16x32_bf16 v[28:31], v[162:165], v[178:181], v[28:31]
	v_mfma_f32_16x16x32_bf16 v[24:27], v[170:173], v[178:181], v[24:27]
	v_mfma_f32_16x16x32_bf16 v[20:23], v[162:165], v[190:193], v[20:23]
	v_mfma_f32_16x16x32_bf16 v[16:19], v[170:173], v[190:193], v[16:19]
	v_mfma_f32_16x16x32_bf16 v[12:15], v[162:165], v[198:201], v[12:15]
	v_mfma_f32_16x16x32_bf16 v[8:11], v[170:173], v[198:201], v[8:11]
	v_mfma_f32_16x16x32_bf16 v[4:7], v[162:165], v[206:209], v[4:7]
	v_mfma_f32_16x16x32_bf16 v[0:3], v[170:173], v[206:209], v[0:3]
	v_mfma_f32_16x16x32_bf16 v[28:31], v[166:169], v[182:185], v[28:31]
	v_mfma_f32_16x16x32_bf16 v[24:27], v[174:177], v[182:185], v[24:27]
	v_mfma_f32_16x16x32_bf16 v[20:23], v[166:169], v[194:197], v[20:23]
	v_mfma_f32_16x16x32_bf16 v[16:19], v[174:177], v[194:197], v[16:19]
	v_mfma_f32_16x16x32_bf16 v[12:15], v[166:169], v[202:205], v[12:15]
	v_mfma_f32_16x16x32_bf16 v[8:11], v[174:177], v[202:205], v[8:11]
	v_mfma_f32_16x16x32_bf16 v[4:7], v[166:169], v[228:231], v[4:7]
	v_mfma_f32_16x16x32_bf16 v[0:3], v[174:177], v[228:231], v[0:3]
	s_barrier
	s_add_i32 s84, 0, 0x18000
	v_add_u32_e32 v140, s84, v146
	s_add_i32 s85, 0, 0x1c000
	ds_read_b128 v[142:145], v140
	ds_read_b128 v[150:153], v140 offset:1024
	ds_read_b128 v[154:157], v140 offset:2048
	ds_read_b128 v[158:161], v140 offset:3072
	v_add_u32_e32 v140, s85, v146
	ds_read_b128 v[162:165], v140
	ds_read_b128 v[166:169], v140 offset:1024
	ds_read_b128 v[170:173], v140 offset:2048
	ds_read_b128 v[174:177], v140 offset:3072
	s_add_u32 s64, s64, 0x40000
	s_addc_u32 s65, s65, 0
	s_mov_b32 m0, s21
	v_lshl_add_u64 v[234:235], s[64:65], 0, v[134:135]
	ds_read_b128 v[178:181], v148 offset:32768
	ds_read_b128 v[182:185], v148 offset:33792
	ds_read_b128 v[190:193], v148 offset:34816
	ds_read_b128 v[194:197], v148 offset:35840
	ds_read_b128 v[198:201], v148 offset:36864
	ds_read_b128 v[202:205], v148 offset:37888
	ds_read_b128 v[206:209], v148 offset:38912
	ds_read_b128 v[228:231], v148 offset:39936
	global_load_lds_dwordx4 v[234:235], off
	v_lshl_add_u64 v[234:235], s[64:65], 0, v[132:133]
	s_mov_b32 m0, s22
	s_nop 0
	global_load_lds_dwordx4 v[234:235], off
	s_waitcnt vmcnt(8)
	s_waitcnt lgkmcnt(0)
	s_barrier
; #define PG8_STAGE(bufoff, gbase, voff) do { _Pragma("unroll") for (int _i = 0; _i < 2; ++_i) \
;         __builtin_amdgcn_global_load_lds((const unsigned*)((const char*)(gbase) + (voff)[_i]), (PG8_LAS unsigned*)(lds + (bufoff) + ldsw + _i * 8192), 16, 0, 0); } while (0)
; #define PG8_LDA(dst, b, h) do { _Pragma("unroll") for (int m = 0; m < 4; ++m) _Pragma("unroll") for (int k = 0; k < 2; ++k) dst[m][k] = *(const PG8_LAS bf16x8*)(lds + PG8_SA(b, h) + aoff + m * 2048 + k * 1024); } while (0)
; #define PG8_MMA(ai, bj, At, Bt) do { __builtin_amdgcn_s_setprio(1); _Pragma("unroll") for (int m = 0; m < 4; ++m) _Pragma("unroll") for (int n = 0; n < 2; ++n) _Pragma("unroll") for (int k = 0; k < 2; ++k) \
;         acc[ai][bj][m][n] = __builtin_amdgcn_mfma_f32_16x16x32_bf16(Bt[n][k], At[m][k], acc[ai][bj][m][n], 0, 0, 0); __builtin_amdgcn_s_setprio(0); } while (0)
; #define PG8_WAIT_V(n) asm volatile("s_waitcnt vmcnt(" #n ")" ::: "memory")
; #define PG8_WAIT_L(n) asm volatile("s_waitcnt lgkmcnt(" #n ")" ::: "memory")
; #define PG8_BAR __builtin_amdgcn_s_barrier()
; #define PG8_SCHED __builtin_amdgcn_sched_barrier(0)
; template <class Epi, class Sched, bool ALIGN_EPI = false, bool SP2 = false>
; __device__ __forceinline__ void gemm_phase(PG8_LAS unsigned char* lds, const Gemm g, const Sched& S, const Epi& E) {
;     ...
;             PG8_WAIT_V(8); PG8_WAIT_L(0); PG8_BAR; PG8_MMA(0, 0, At, B0); PG8_MMA(0, 1, At, B1); PG8_BAR; PG8_SCHED;
;             PG8_LDA(At, 1, 1); PG8_STAGE(PG8_SB(1, 0), b3, voffB); PG8_STAGE(PG8_SB(1, 1), b3 + hstep, voffB); PG8_STAGE(PG8_SA(1, 0), a3, voffA);
;             PG8_WAIT_V(8); PG8_WAIT_L(0); PG8_BAR; PG8_MMA(1, 0, At, B0); PG8_MMA(1, 1, At, B1); PG8_BAR; PG8_SCHED;
;     ...
;         if constexpr (ALIGN_EPI) { if (wr == 0) PG8_BAR; }
	s_waitcnt lgkmcnt(0)
	v_mfma_f32_16x16x32_bf16 v[124:127], v[142:145], v[178:181], v[124:127]
	v_mfma_f32_16x16x32_bf16 v[120:123], v[154:157], v[178:181], v[120:123]
	v_mfma_f32_16x16x32_bf16 v[116:119], v[142:145], v[190:193], v[116:119]
	v_mfma_f32_16x16x32_bf16 v[112:115], v[154:157], v[190:193], v[112:115]
	v_mfma_f32_16x16x32_bf16 v[108:111], v[142:145], v[198:201], v[108:111]
	v_mfma_f32_16x16x32_bf16 v[104:107], v[154:157], v[198:201], v[104:107]
	v_mfma_f32_16x16x32_bf16 v[100:103], v[142:145], v[206:209], v[100:103]
	v_mfma_f32_16x16x32_bf16 v[96:99], v[154:157], v[206:209], v[96:99]
	v_mfma_f32_16x16x32_bf16 v[124:127], v[150:153], v[182:185], v[124:127]
	v_mfma_f32_16x16x32_bf16 v[120:123], v[158:161], v[182:185], v[120:123]
	v_mfma_f32_16x16x32_bf16 v[116:119], v[150:153], v[194:197], v[116:119]
	v_mfma_f32_16x16x32_bf16 v[112:115], v[158:161], v[194:197], v[112:115]
	v_mfma_f32_16x16x32_bf16 v[108:111], v[150:153], v[202:205], v[108:111]
	v_mfma_f32_16x16x32_bf16 v[104:107], v[158:161], v[202:205], v[104:107]
	v_mfma_f32_16x16x32_bf16 v[100:103], v[150:153], v[228:231], v[100:103]
	v_mfma_f32_16x16x32_bf16 v[96:99], v[158:161], v[228:231], v[96:99]
	v_mfma_f32_16x16x32_bf16 v[92:95], v[162:165], v[178:181], v[92:95]
	v_mfma_f32_16x16x32_bf16 v[88:91], v[170:173], v[178:181], v[88:91]
	v_mfma_f32_16x16x32_bf16 v[84:87], v[162:165], v[190:193], v[84:87]
	v_mfma_f32_16x16x32_bf16 v[80:83], v[170:173], v[190:193], v[80:83]
	v_mfma_f32_16x16x32_bf16 v[76:79], v[162:165], v[198:201], v[76:79]
	v_mfma_f32_16x16x32_bf16 v[72:75], v[170:173], v[198:201], v[72:75]
	v_mfma_f32_16x16x32_bf16 v[68:71], v[162:165], v[206:209], v[68:71]
	v_mfma_f32_16x16x32_bf16 v[64:67], v[170:173], v[206:209], v[64:67]
	v_mfma_f32_16x16x32_bf16 v[92:95], v[166:169], v[182:185], v[92:95]
	v_mfma_f32_16x16x32_bf16 v[88:91], v[174:177], v[182:185], v[88:91]
	v_mfma_f32_16x16x32_bf16 v[84:87], v[166:169], v[194:197], v[84:87]
	v_mfma_f32_16x16x32_bf16 v[80:83], v[174:177], v[194:197], v[80:83]
	v_mfma_f32_16x16x32_bf16 v[76:79], v[166:169], v[202:205], v[76:79]
	v_mfma_f32_16x16x32_bf16 v[72:75], v[174:177], v[202:205], v[72:75]
	v_mfma_f32_16x16x32_bf16 v[68:71], v[166:169], v[228:231], v[68:71]
	v_mfma_f32_16x16x32_bf16 v[64:67], v[174:177], v[228:231], v[64:67]
	s_barrier
	s_add_i32 s64, s84, s18
	v_lshl_add_u64 v[186:187], v[186:187], 0, s[90:91]
	s_mov_b32 m0, s64
	ds_read_b128 v[178:181], v148 offset:49152
	ds_read_b128 v[182:185], v148 offset:50176
	ds_read_b128 v[190:193], v148 offset:51200
	ds_read_b128 v[194:197], v148 offset:52224
	ds_read_b128 v[198:201], v148 offset:53248
	ds_read_b128 v[202:205], v148 offset:54272
	ds_read_b128 v[206:209], v148 offset:55296
	ds_read_b128 v[228:231], v148 offset:56320
	global_load_lds_dwordx4 v[186:187], off
	s_add_i32 m0, s64, 0x2000
	s_add_u32 s58, s58, 0x40080
	v_lshl_add_u64 v[186:187], v[188:189], 0, s[90:91]
	s_addc_u32 s59, s59, 0
	s_add_i32 s64, s85, s18
	global_load_lds_dwordx4 v[186:187], off
	v_lshl_add_u64 v[186:187], s[58:59], 0, v[128:129]
	s_mov_b32 m0, s64
	s_nop 0
	global_load_lds_dwordx4 v[186:187], off
	v_lshl_add_u64 v[186:187], s[58:59], 0, v[130:131]
	s_add_i32 m0, s64, 0x2000
	s_nop 0
	global_load_lds_dwordx4 v[186:187], off
	v_lshl_add_u64 v[186:187], v[210:211], 0, s[90:91]
	s_mov_b32 m0, s28
	s_nop 0
	global_load_lds_dwordx4 v[186:187], off
	v_lshl_add_u64 v[186:187], v[232:233], 0, s[90:91]
	s_mov_b32 m0, s29
	s_nop 0
	global_load_lds_dwordx4 v[186:187], off
	s_waitcnt vmcnt(8)
	s_waitcnt lgkmcnt(0)
	s_barrier
	s_waitcnt lgkmcnt(0)
	v_mfma_f32_16x16x32_bf16 v[60:63], v[142:145], v[178:181], v[60:63]
	v_mfma_f32_16x16x32_bf16 v[56:59], v[154:157], v[178:181], v[56:59]
	v_mfma_f32_16x16x32_bf16 v[52:55], v[142:145], v[190:193], v[52:55]
	v_mfma_f32_16x16x32_bf16 v[48:51], v[154:157], v[190:193], v[48:51]
	v_mfma_f32_16x16x32_bf16 v[44:47], v[142:145], v[198:201], v[44:47]
	v_mfma_f32_16x16x32_bf16 v[40:43], v[154:157], v[198:201], v[40:43]
	v_mfma_f32_16x16x32_bf16 v[36:39], v[142:145], v[206:209], v[36:39]
	v_mfma_f32_16x16x32_bf16 v[32:35], v[154:157], v[206:209], v[32:35]
	v_mfma_f32_16x16x32_bf16 v[60:63], v[150:153], v[182:185], v[60:63]
	v_mfma_f32_16x16x32_bf16 v[56:59], v[158:161], v[182:185], v[56:59]
	v_mfma_f32_16x16x32_bf16 v[52:55], v[150:153], v[194:197], v[52:55]
	v_mfma_f32_16x16x32_bf16 v[48:51], v[158:161], v[194:197], v[48:51]
	v_mfma_f32_16x16x32_bf16 v[44:47], v[150:153], v[202:205], v[44:47]
	v_mfma_f32_16x16x32_bf16 v[40:43], v[158:161], v[202:205], v[40:43]
	v_mfma_f32_16x16x32_bf16 v[36:39], v[150:153], v[228:231], v[36:39]
	v_mfma_f32_16x16x32_bf16 v[32:35], v[158:161], v[228:231], v[32:35]
	v_mfma_f32_16x16x32_bf16 v[28:31], v[162:165], v[178:181], v[28:31]
	v_mfma_f32_16x16x32_bf16 v[24:27], v[170:173], v[178:181], v[24:27]
	v_mfma_f32_16x16x32_bf16 v[20:23], v[162:165], v[190:193], v[20:23]
	v_mfma_f32_16x16x32_bf16 v[16:19], v[170:173], v[190:193], v[16:19]
	v_mfma_f32_16x16x32_bf16 v[12:15], v[162:165], v[198:201], v[12:15]
	v_mfma_f32_16x16x32_bf16 v[8:11], v[170:173], v[198:201], v[8:11]
	v_mfma_f32_16x16x32_bf16 v[4:7], v[162:165], v[206:209], v[4:7]
	v_mfma_f32_16x16x32_bf16 v[0:3], v[170:173], v[206:209], v[0:3]
	v_mfma_f32_16x16x32_bf16 v[28:31], v[166:169], v[182:185], v[28:31]
	v_mfma_f32_16x16x32_bf16 v[24:27], v[174:177], v[182:185], v[24:27]
	v_mfma_f32_16x16x32_bf16 v[20:23], v[166:169], v[194:197], v[20:23]
	v_mfma_f32_16x16x32_bf16 v[16:19], v[174:177], v[194:197], v[16:19]
	v_mfma_f32_16x16x32_bf16 v[12:15], v[166:169], v[202:205], v[12:15]
	v_mfma_f32_16x16x32_bf16 v[8:11], v[174:177], v[202:205], v[8:11]
	v_mfma_f32_16x16x32_bf16 v[4:7], v[166:169], v[228:231], v[4:7]
	v_mfma_f32_16x16x32_bf16 v[0:3], v[174:177], v[228:231], v[0:3]
	s_barrier
	s_add_i32 s94, s94, 2
	s_add_u32 s72, s72, 0x100
	s_addc_u32 s73, s73, 0
	s_add_u32 s92, s92, 0x100
	s_addc_u32 s93, s93, 0
	s_cmp_gt_u32 s94, 13
	s_cbranch_scc0 .LBB0_164
	s_setprio 0
	s_and_b64 vcc, exec, s[48:49]
	s_cbranch_vccz .LBB0_167
	s_barrier

; #define PG8_STAGE(bufoff, gbase, voff) do { _Pragma("unroll") for (int _i = 0; _i < 2; ++_i) \
;         __builtin_amdgcn_global_load_lds((const unsigned*)((const char*)(gbase) + (voff)[_i]), (PG8_LAS unsigned*)(lds + (bufoff) + ldsw + _i * 8192), 16, 0, 0); } while (0)
; #define PG8_LDA(dst, b, h) do { _Pragma("unroll") for (int m = 0; m < 4; ++m) _Pragma("unroll") for (int k = 0; k < 2; ++k) dst[m][k] = *(const PG8_LAS bf16x8*)(lds + PG8_SA(b, h) + aoff + m * 2048 + k * 1024); } while (0)
; #define PG8_LDB(dst, b, h) do { _Pragma("unroll") for (int n = 0; n < 2; ++n) _Pragma("unroll") for (int k = 0; k < 2; ++k) dst[n][k] = *(const PG8_LAS bf16x8*)(lds + PG8_SB(b, h) + boff + n * 2048 + k * 1024); } while (0)
; #define PG8_WAIT_V(n) asm volatile("s_waitcnt vmcnt(" #n ")" ::: "memory")
; #define PG8_WAIT_L(n) asm volatile("s_waitcnt lgkmcnt(" #n ")" ::: "memory")
; #define PG8_BAR __builtin_amdgcn_s_barrier()
; template <class Epi, class Sched, bool ALIGN_EPI = false, bool SP2 = false>
; __device__ __forceinline__ void gemm_phase(PG8_LAS unsigned char* lds, const Gemm g, const Sched& S, const Epi& E) {
;     ...
;     for (;;) {
;         const bool has_next = S.next(ui + 1, nxt);
;         const char* nA = has_next ? (const char*)g.A + (size_t)nxt.pm * tstep : cA; const char* nB = has_next ? (const char*)g.Bt + (size_t)nxt.pn * tstep : cB;
;         for (int t = 0; t < nt; t += 2) {
;             const bool last = (t == nt - 2);
;             const char* a1 = cA + (size_t)(t + 1) * kstep;
;             const char* a2 = last ? nA : cA + (size_t)(t + 2) * kstep; const char* b2 = last ? nB : cB + (size_t)(t + 2) * kstep;
;             const char* a3 = a2 + kstep; const char* b3 = b2 + kstep;
;             if (last && has_next) S.a_ready(nxt);
;             if constexpr (SP2) {
;             PG8_LDB(B0, 0, 0); PG8_LDB(B1, 0, 1); PG8_SCHED; PG8_LDA(At, 0, 0); PG8_STAGE(PG8_SA(1, 1), a1 + hstep, voffA);
;             PG8_WAIT_V(8); PG8_WAIT_L(0); PG8_BAR; PG8_MMA(0, 0, At, B0); PG8_MMA(0, 1, At, B1); PG8_BAR; PG8_SCHED;
;     ...
; #pragma unroll
;         for (int a = 0; a < 2; ++a)
; #pragma unroll
;             for (int b = 0; b < 2; ++b)
; #pragma unroll
;                 for (int m = 0; m < 4; ++m)
; #pragma unroll
;                     for (int n = 0; n < 2; ++n) acc[a][b][m][n] = (f32x4){0.f, 0.f, 0.f, 0.f};
;         cur = nxt; cA = nA; cB = nB; ++ui;
.LBB0_563:
	s_ashr_i32 s67, s66, 31
	s_lshl_b64 s[36:37], s[66:67], 19
	s_add_u32 s64, s2, s36
	s_addc_u32 s65, s25, s37
	s_and_b64 s[36:37], s[40:41], exec
	s_cselect_b32 s36, s65, s93
	s_cselect_b32 s37, s64, s92
	s_ashr_i32 s73, s72, 31
	s_lshl_b64 s[84:85], s[72:73], 19
	s_add_u32 s96, s70, s84
	s_addc_u32 s97, s16, s85
	s_and_b64 s[84:85], s[40:41], exec
	s_cselect_b32 s67, s97, s59
	s_cselect_b32 s73, s96, s58
	s_add_u32 vcc_lo, s92, 0x40080
	s_addc_u32 vcc_hi, s93, 0
	s_add_u32 s88, s58, 0x100
	v_mov_b64_e32 v[0:1], 0
	s_addc_u32 s94, s59, 0
	s_mov_b32 s84, -2
	v_mov_b64_e32 v[2:3], 0
	v_mov_b64_e32 v[4:5], 0
	v_mov_b64_e32 v[6:7], 0
	v_mov_b64_e32 v[16:17], 0
	v_mov_b64_e32 v[18:19], 0
	v_mov_b64_e32 v[20:21], 0
	v_mov_b64_e32 v[22:23], 0
	v_mov_b64_e32 v[32:33], 0
	v_mov_b64_e32 v[34:35], 0
	v_mov_b64_e32 v[36:37], 0
	v_mov_b64_e32 v[38:39], 0
	v_mov_b64_e32 v[48:49], 0
	v_mov_b64_e32 v[50:51], 0
	v_mov_b64_e32 v[52:53], 0
	v_mov_b64_e32 v[54:55], 0
	v_mov_b64_e32 v[8:9], 0
	v_mov_b64_e32 v[10:11], 0
	v_mov_b64_e32 v[12:13], 0
	v_mov_b64_e32 v[14:15], 0
	v_mov_b64_e32 v[24:25], 0
	v_mov_b64_e32 v[26:27], 0
	v_mov_b64_e32 v[28:29], 0
	v_mov_b64_e32 v[30:31], 0
	v_mov_b64_e32 v[40:41], 0
	v_mov_b64_e32 v[42:43], 0
	v_mov_b64_e32 v[44:45], 0
	v_mov_b64_e32 v[46:47], 0
	v_mov_b64_e32 v[56:57], 0
	v_mov_b64_e32 v[58:59], 0
	v_mov_b64_e32 v[60:61], 0
	v_mov_b64_e32 v[62:63], 0
	v_mov_b64_e32 v[64:65], 0
	v_mov_b64_e32 v[66:67], 0
	v_mov_b64_e32 v[68:69], 0
	v_mov_b64_e32 v[70:71], 0
	v_mov_b64_e32 v[80:81], 0
	v_mov_b64_e32 v[82:83], 0
	v_mov_b64_e32 v[84:85], 0
	v_mov_b64_e32 v[86:87], 0
	v_mov_b64_e32 v[96:97], 0
	v_mov_b64_e32 v[98:99], 0
	v_mov_b64_e32 v[100:101], 0
	v_mov_b64_e32 v[102:103], 0
	v_mov_b64_e32 v[112:113], 0
	v_mov_b64_e32 v[114:115], 0
	v_mov_b64_e32 v[116:117], 0
	v_mov_b64_e32 v[118:119], 0
	v_mov_b64_e32 v[72:73], 0
	v_mov_b64_e32 v[74:75], 0
	v_mov_b64_e32 v[76:77], 0
	v_mov_b64_e32 v[78:79], 0
	v_mov_b64_e32 v[88:89], 0
	v_mov_b64_e32 v[90:91], 0
	v_mov_b64_e32 v[92:93], 0
	v_mov_b64_e32 v[94:95], 0
	v_mov_b64_e32 v[104:105], 0
	v_mov_b64_e32 v[106:107], 0
	v_mov_b64_e32 v[108:109], 0
	v_mov_b64_e32 v[110:111], 0
	v_mov_b64_e32 v[120:121], 0
	v_mov_b64_e32 v[122:123], 0
	v_mov_b64_e32 v[124:125], 0
	v_mov_b64_e32 v[126:127], 0
	s_and_b64 s[98:99], exec, s[62:63]
	s_cbranch_scc1 .Lsp_2
	s_setprio 1
.Lsp_2:
.LBB0_564:
	s_add_u32 s44, vcc_lo, 0xfffc0080
	s_addc_u32 s45, vcc_hi, -1
	s_add_i32 s85, 0, 0x10000
	s_cmp_eq_u32 s84, 12
	s_cselect_b32 s93, s36, s45
	s_cselect_b32 s92, s37, s44
	s_cselect_b32 s59, s67, s94
	s_cselect_b32 s58, s73, s88
	s_add_i32 s8, 0, 0x14000
	v_add_u32_e32 v142, s85, v201
	v_add_u32_e32 v168, s8, v201
	ds_read_b128 v[130:133], v142
	ds_read_b128 v[134:137], v142 offset:1024
	ds_read_b128 v[138:141], v142 offset:2048
	ds_read_b128 v[142:145], v142 offset:3072
	ds_read_b128 v[156:159], v168
	ds_read_b128 v[160:163], v168 offset:1024
	ds_read_b128 v[164:167], v168 offset:2048
	ds_read_b128 v[168:171], v168 offset:3072
	v_lshl_add_u64 v[208:209], vcc, 0, v[152:153]
	s_add_i32 m0, s15, 0xc000
	ds_read_b128 v[172:175], v203
	ds_read_b128 v[176:179], v203 offset:1024
	ds_read_b128 v[180:183], v203 offset:2048
	ds_read_b128 v[184:187], v203 offset:3072
	ds_read_b128 v[188:191], v203 offset:4096
	ds_read_b128 v[192:195], v203 offset:5120
	ds_read_b128 v[196:199], v203 offset:6144
	ds_read_b128 v[204:207], v203 offset:7168
	global_load_lds_dwordx4 v[208:209], off
	v_lshl_add_u64 v[208:209], vcc, 0, v[154:155]
	s_add_i32 m0, s15, 0xe000
	s_nop 0
	global_load_lds_dwordx4 v[208:209], off
	s_waitcnt vmcnt(8)
	s_waitcnt lgkmcnt(0)
	s_barrier
	s_waitcnt lgkmcnt(0)
	v_mfma_f32_16x16x32_bf16 v[124:127], v[130:133], v[172:175], v[124:127]
	v_mfma_f32_16x16x32_bf16 v[120:123], v[138:141], v[172:175], v[120:123]
	v_mfma_f32_16x16x32_bf16 v[108:111], v[130:133], v[180:183], v[108:111]
	v_mfma_f32_16x16x32_bf16 v[104:107], v[138:141], v[180:183], v[104:107]
	v_mfma_f32_16x16x32_bf16 v[92:95], v[130:133], v[188:191], v[92:95]
	v_mfma_f32_16x16x32_bf16 v[88:91], v[138:141], v[188:191], v[88:91]
	v_mfma_f32_16x16x32_bf16 v[76:79], v[130:133], v[196:199], v[76:79]
	v_mfma_f32_16x16x32_bf16 v[72:75], v[138:141], v[196:199], v[72:75]
	v_mfma_f32_16x16x32_bf16 v[124:127], v[134:137], v[176:179], v[124:127]
	v_mfma_f32_16x16x32_bf16 v[120:123], v[142:145], v[176:179], v[120:123]
	v_mfma_f32_16x16x32_bf16 v[108:111], v[134:137], v[184:187], v[108:111]
	v_mfma_f32_16x16x32_bf16 v[104:107], v[142:145], v[184:187], v[104:107]
	v_mfma_f32_16x16x32_bf16 v[92:95], v[134:137], v[192:195], v[92:95]
	v_mfma_f32_16x16x32_bf16 v[88:91], v[142:145], v[192:195], v[88:91]
	v_mfma_f32_16x16x32_bf16 v[76:79], v[134:137], v[204:207], v[76:79]
	v_mfma_f32_16x16x32_bf16 v[72:75], v[142:145], v[204:207], v[72:75]
	v_mfma_f32_16x16x32_bf16 v[116:119], v[156:159], v[172:175], v[116:119]
	v_mfma_f32_16x16x32_bf16 v[112:115], v[164:167], v[172:175], v[112:115]
	v_mfma_f32_16x16x32_bf16 v[100:103], v[156:159], v[180:183], v[100:103]
	v_mfma_f32_16x16x32_bf16 v[96:99], v[164:167], v[180:183], v[96:99]
	v_mfma_f32_16x16x32_bf16 v[84:87], v[156:159], v[188:191], v[84:87]
	v_mfma_f32_16x16x32_bf16 v[80:83], v[164:167], v[188:191], v[80:83]
	v_mfma_f32_16x16x32_bf16 v[68:71], v[156:159], v[196:199], v[68:71]
	v_mfma_f32_16x16x32_bf16 v[64:67], v[164:167], v[196:199], v[64:67]
	v_mfma_f32_16x16x32_bf16 v[116:119], v[160:163], v[176:179], v[116:119]
	v_mfma_f32_16x16x32_bf16 v[112:115], v[168:171], v[176:179], v[112:115]
	v_mfma_f32_16x16x32_bf16 v[100:103], v[160:163], v[184:187], v[100:103]
	v_mfma_f32_16x16x32_bf16 v[96:99], v[168:171], v[184:187], v[96:99]
	v_mfma_f32_16x16x32_bf16 v[84:87], v[160:163], v[192:195], v[84:87]
	v_mfma_f32_16x16x32_bf16 v[80:83], v[168:171], v[192:195], v[80:83]
	v_mfma_f32_16x16x32_bf16 v[68:71], v[160:163], v[204:207], v[68:71]
	v_mfma_f32_16x16x32_bf16 v[64:67], v[168:171], v[204:207], v[64:67]
	s_barrier
; #define PG8_STAGE(bufoff, gbase, voff) do { _Pragma("unroll") for (int _i = 0; _i < 2; ++_i) \
;         __builtin_amdgcn_global_load_lds((const unsigned*)((const char*)(gbase) + (voff)[_i]), (PG8_LAS unsigned*)(lds + (bufoff) + ldsw + _i * 8192), 16, 0, 0); } while (0)
; #define PG8_LDA(dst, b, h) do { _Pragma("unroll") for (int m = 0; m < 4; ++m) _Pragma("unroll") for (int k = 0; k < 2; ++k) dst[m][k] = *(const PG8_LAS bf16x8*)(lds + PG8_SA(b, h) + aoff + m * 2048 + k * 1024); } while (0)
; #define PG8_LDB(dst, b, h) do { _Pragma("unroll") for (int n = 0; n < 2; ++n) _Pragma("unroll") for (int k = 0; k < 2; ++k) dst[n][k] = *(const PG8_LAS bf16x8*)(lds + PG8_SB(b, h) + boff + n * 2048 + k * 1024); } while (0)
; #define PG8_MMA(ai, bj, At, Bt) do { __builtin_amdgcn_s_setprio(1); _Pragma("unroll") for (int m = 0; m < 4; ++m) _Pragma("unroll") for (int n = 0; n < 2; ++n) _Pragma("unroll") for (int k = 0; k < 2; ++k) \
;         acc[ai][bj][m][n] = __builtin_amdgcn_mfma_f32_16x16x32_bf16(Bt[n][k], At[m][k], acc[ai][bj][m][n], 0, 0, 0); __builtin_amdgcn_s_setprio(0); } while (0)
; #define PG8_WAIT_V(n) asm volatile("s_waitcnt vmcnt(" #n ")" ::: "memory")
; #define PG8_WAIT_L(n) asm volatile("s_waitcnt lgkmcnt(" #n ")" ::: "memory")
; #define PG8_BAR __builtin_amdgcn_s_barrier()
; #define PG8_SCHED __builtin_amdgcn_sched_barrier(0)
; template <class Epi, class Sched, bool ALIGN_EPI = false, bool SP2 = false>
; __device__ __forceinline__ void gemm_phase(PG8_LAS unsigned char* lds, const Gemm g, const Sched& S, const Epi& E) {
;     ...
;             PG8_LDA(At, 0, 1); PG8_STAGE(PG8_SB(0, 0), b2, voffB); PG8_STAGE(PG8_SB(0, 1), b2 + hstep, voffB); PG8_STAGE(PG8_SA(0, 0), a2, voffA);
;             PG8_WAIT_V(8); PG8_WAIT_L(0); PG8_BAR; PG8_MMA(1, 0, At, B0); PG8_MMA(1, 1, At, B1); PG8_BAR; PG8_SCHED;
;             PG8_LDB(B0, 1, 0); PG8_LDB(B1, 1, 1); PG8_SCHED; PG8_LDA(At, 1, 0); PG8_STAGE(PG8_SA(0, 1), a2 + hstep, voffA);
;             PG8_WAIT_V(8); PG8_WAIT_L(0); PG8_BAR; PG8_MMA(0, 0, At, B0); PG8_MMA(0, 1, At, B1); PG8_BAR; PG8_SCHED;
	s_add_i32 s44, s85, s14
	v_lshl_add_u64 v[208:209], s[58:59], 0, v[128:129]
	s_mov_b32 m0, s44
	ds_read_b128 v[172:175], v203 offset:16384
	ds_read_b128 v[176:179], v203 offset:17408
	ds_read_b128 v[180:183], v203 offset:18432
	ds_read_b128 v[184:187], v203 offset:19456
	ds_read_b128 v[188:191], v203 offset:20480
	ds_read_b128 v[192:195], v203 offset:21504
	ds_read_b128 v[196:199], v203 offset:22528
	ds_read_b128 v[204:207], v203 offset:23552
	global_load_lds_dwordx4 v[208:209], off
	s_add_i32 m0, s44, 0x2000
	s_add_u32 s44, s58, 0x40000
	v_lshl_add_u64 v[210:211], s[58:59], 0, v[146:147]
	s_addc_u32 s45, s59, 0
	s_add_i32 s8, s8, s14
	global_load_lds_dwordx4 v[210:211], off
	v_lshl_add_u64 v[214:215], s[44:45], 0, v[128:129]
	s_mov_b32 m0, s8
	v_lshl_add_u64 v[222:223], s[92:93], 0, v[148:149]
	global_load_lds_dwordx4 v[214:215], off
	v_lshl_add_u64 v[214:215], s[44:45], 0, v[146:147]
	s_add_i32 m0, s8, 0x2000
	s_nop 0
	global_load_lds_dwordx4 v[214:215], off
	v_lshl_add_u64 v[214:215], s[92:93], 0, v[150:151]
	s_mov_b32 m0, s15
	s_nop 0
	global_load_lds_dwordx4 v[214:215], off
	s_mov_b32 m0, s17
	s_nop 0
	global_load_lds_dwordx4 v[222:223], off
	s_waitcnt vmcnt(8)
	s_waitcnt lgkmcnt(0)
	s_barrier
	s_waitcnt lgkmcnt(0)
	v_mfma_f32_16x16x32_bf16 v[60:63], v[130:133], v[172:175], v[60:63]
	v_mfma_f32_16x16x32_bf16 v[56:59], v[138:141], v[172:175], v[56:59]
	v_mfma_f32_16x16x32_bf16 v[44:47], v[130:133], v[180:183], v[44:47]
	v_mfma_f32_16x16x32_bf16 v[40:43], v[138:141], v[180:183], v[40:43]
	v_mfma_f32_16x16x32_bf16 v[28:31], v[130:133], v[188:191], v[28:31]
	v_mfma_f32_16x16x32_bf16 v[24:27], v[138:141], v[188:191], v[24:27]
	v_mfma_f32_16x16x32_bf16 v[12:15], v[130:133], v[196:199], v[12:15]
	v_mfma_f32_16x16x32_bf16 v[8:11], v[138:141], v[196:199], v[8:11]
	v_mfma_f32_16x16x32_bf16 v[60:63], v[134:137], v[176:179], v[60:63]
	v_mfma_f32_16x16x32_bf16 v[56:59], v[142:145], v[176:179], v[56:59]
	v_mfma_f32_16x16x32_bf16 v[44:47], v[134:137], v[184:187], v[44:47]
	v_mfma_f32_16x16x32_bf16 v[40:43], v[142:145], v[184:187], v[40:43]
	v_mfma_f32_16x16x32_bf16 v[28:31], v[134:137], v[192:195], v[28:31]
	v_mfma_f32_16x16x32_bf16 v[24:27], v[142:145], v[192:195], v[24:27]
	v_mfma_f32_16x16x32_bf16 v[12:15], v[134:137], v[204:207], v[12:15]
	v_mfma_f32_16x16x32_bf16 v[8:11], v[142:145], v[204:207], v[8:11]
	v_mfma_f32_16x16x32_bf16 v[52:55], v[156:159], v[172:175], v[52:55]
	v_mfma_f32_16x16x32_bf16 v[48:51], v[164:167], v[172:175], v[48:51]
	v_mfma_f32_16x16x32_bf16 v[36:39], v[156:159], v[180:183], v[36:39]
	v_mfma_f32_16x16x32_bf16 v[32:35], v[164:167], v[180:183], v[32:35]
	v_mfma_f32_16x16x32_bf16 v[20:23], v[156:159], v[188:191], v[20:23]
	v_mfma_f32_16x16x32_bf16 v[16:19], v[164:167], v[188:191], v[16:19]
	v_mfma_f32_16x16x32_bf16 v[4:7], v[156:159], v[196:199], v[4:7]
	v_mfma_f32_16x16x32_bf16 v[0:3], v[164:167], v[196:199], v[0:3]
	v_mfma_f32_16x16x32_bf16 v[52:55], v[160:163], v[176:179], v[52:55]
	v_mfma_f32_16x16x32_bf16 v[48:51], v[168:171], v[176:179], v[48:51]
	v_mfma_f32_16x16x32_bf16 v[36:39], v[160:163], v[184:187], v[36:39]
	v_mfma_f32_16x16x32_bf16 v[32:35], v[168:171], v[184:187], v[32:35]
	v_mfma_f32_16x16x32_bf16 v[20:23], v[160:163], v[192:195], v[20:23]
	v_mfma_f32_16x16x32_bf16 v[16:19], v[168:171], v[192:195], v[16:19]
	v_mfma_f32_16x16x32_bf16 v[4:7], v[160:163], v[204:207], v[4:7]
	v_mfma_f32_16x16x32_bf16 v[0:3], v[168:171], v[204:207], v[0:3]
	s_barrier
	s_add_i32 s8, 0, 0x18000
	s_add_i32 s85, 0, 0x1c000
	v_add_u32_e32 v142, s8, v201
	v_add_u32_e32 v168, s85, v201
	ds_read_b128 v[130:133], v142
	ds_read_b128 v[134:137], v142 offset:1024
	ds_read_b128 v[138:141], v142 offset:2048
	ds_read_b128 v[142:145], v142 offset:3072
	ds_read_b128 v[156:159], v168
	ds_read_b128 v[160:163], v168 offset:1024
	ds_read_b128 v[164:167], v168 offset:2048
	ds_read_b128 v[168:171], v168 offset:3072
	s_add_u32 s44, s92, 0x40000
	s_addc_u32 s45, s93, 0
	s_mov_b32 m0, s18
	v_lshl_add_u64 v[228:229], s[44:45], 0, v[150:151]
	ds_read_b128 v[172:175], v203 offset:32768
	ds_read_b128 v[176:179], v203 offset:33792
	ds_read_b128 v[180:183], v203 offset:34816
	ds_read_b128 v[184:187], v203 offset:35840
	ds_read_b128 v[188:191], v203 offset:36864
	ds_read_b128 v[192:195], v203 offset:37888
	ds_read_b128 v[196:199], v203 offset:38912
	ds_read_b128 v[204:207], v203 offset:39936
	global_load_lds_dwordx4 v[228:229], off
	v_lshl_add_u64 v[228:229], s[44:45], 0, v[148:149]
	s_mov_b32 m0, s19
	s_nop 0
	global_load_lds_dwordx4 v[228:229], off
	s_waitcnt vmcnt(8)
	s_waitcnt lgkmcnt(0)
	s_barrier
; #define PG8_STAGE(bufoff, gbase, voff) do { _Pragma("unroll") for (int _i = 0; _i < 2; ++_i) \
;         __builtin_amdgcn_global_load_lds((const unsigned*)((const char*)(gbase) + (voff)[_i]), (PG8_LAS unsigned*)(lds + (bufoff) + ldsw + _i * 8192), 16, 0, 0); } while (0)
; #define PG8_LDA(dst, b, h) do { _Pragma("unroll") for (int m = 0; m < 4; ++m) _Pragma("unroll") for (int k = 0; k < 2; ++k) dst[m][k] = *(const PG8_LAS bf16x8*)(lds + PG8_SA(b, h) + aoff + m * 2048 + k * 1024); } while (0)
; #define PG8_MMA(ai, bj, At, Bt) do { __builtin_amdgcn_s_setprio(1); _Pragma("unroll") for (int m = 0; m < 4; ++m) _Pragma("unroll") for (int n = 0; n < 2; ++n) _Pragma("unroll") for (int k = 0; k < 2; ++k) \
;         acc[ai][bj][m][n] = __builtin_amdgcn_mfma_f32_16x16x32_bf16(Bt[n][k], At[m][k], acc[ai][bj][m][n], 0, 0, 0); __builtin_amdgcn_s_setprio(0); } while (0)
; #define PG8_WAIT_V(n) asm volatile("s_waitcnt vmcnt(" #n ")" ::: "memory")
; #define PG8_WAIT_L(n) asm volatile("s_waitcnt lgkmcnt(" #n ")" ::: "memory")
; #define PG8_BAR __builtin_amdgcn_s_barrier()
; #define PG8_SCHED __builtin_amdgcn_sched_barrier(0)
; template <class Epi, class Sched, bool ALIGN_EPI = false, bool SP2 = false>
; __device__ __forceinline__ void gemm_phase(PG8_LAS unsigned char* lds, const Gemm g, const Sched& S, const Epi& E) {
;     ...
;             PG8_WAIT_V(8); PG8_WAIT_L(0); PG8_BAR; PG8_MMA(0, 0, At, B0); PG8_MMA(0, 1, At, B1); PG8_BAR; PG8_SCHED;
;             PG8_LDA(At, 1, 1); PG8_STAGE(PG8_SB(1, 0), b3, voffB); PG8_STAGE(PG8_SB(1, 1), b3 + hstep, voffB); PG8_STAGE(PG8_SA(1, 0), a3, voffA);
;             PG8_WAIT_V(8); PG8_WAIT_L(0); PG8_BAR; PG8_MMA(1, 0, At, B0); PG8_MMA(1, 1, At, B1); PG8_BAR; PG8_SCHED;
;     ...
;         if constexpr (ALIGN_EPI) { if (wr == 0) PG8_BAR; }
	s_waitcnt lgkmcnt(0)
	v_mfma_f32_16x16x32_bf16 v[124:127], v[130:133], v[172:175], v[124:127]
	v_mfma_f32_16x16x32_bf16 v[120:123], v[138:141], v[172:175], v[120:123]
	v_mfma_f32_16x16x32_bf16 v[108:111], v[130:133], v[180:183], v[108:111]
	v_mfma_f32_16x16x32_bf16 v[104:107], v[138:141], v[180:183], v[104:107]
	v_mfma_f32_16x16x32_bf16 v[92:95], v[130:133], v[188:191], v[92:95]
	v_mfma_f32_16x16x32_bf16 v[88:91], v[138:141], v[188:191], v[88:91]
	v_mfma_f32_16x16x32_bf16 v[76:79], v[130:133], v[196:199], v[76:79]
	v_mfma_f32_16x16x32_bf16 v[72:75], v[138:141], v[196:199], v[72:75]
	v_mfma_f32_16x16x32_bf16 v[124:127], v[134:137], v[176:179], v[124:127]
	v_mfma_f32_16x16x32_bf16 v[120:123], v[142:145], v[176:179], v[120:123]
	v_mfma_f32_16x16x32_bf16 v[108:111], v[134:137], v[184:187], v[108:111]
	v_mfma_f32_16x16x32_bf16 v[104:107], v[142:145], v[184:187], v[104:107]
	v_mfma_f32_16x16x32_bf16 v[92:95], v[134:137], v[192:195], v[92:95]
	v_mfma_f32_16x16x32_bf16 v[88:91], v[142:145], v[192:195], v[88:91]
	v_mfma_f32_16x16x32_bf16 v[76:79], v[134:137], v[204:207], v[76:79]
	v_mfma_f32_16x16x32_bf16 v[72:75], v[142:145], v[204:207], v[72:75]
	v_mfma_f32_16x16x32_bf16 v[116:119], v[156:159], v[172:175], v[116:119]
	v_mfma_f32_16x16x32_bf16 v[112:115], v[164:167], v[172:175], v[112:115]
	v_mfma_f32_16x16x32_bf16 v[100:103], v[156:159], v[180:183], v[100:103]
	v_mfma_f32_16x16x32_bf16 v[96:99], v[164:167], v[180:183], v[96:99]
	v_mfma_f32_16x16x32_bf16 v[84:87], v[156:159], v[188:191], v[84:87]
	v_mfma_f32_16x16x32_bf16 v[80:83], v[164:167], v[188:191], v[80:83]
	v_mfma_f32_16x16x32_bf16 v[68:71], v[156:159], v[196:199], v[68:71]
	v_mfma_f32_16x16x32_bf16 v[64:67], v[164:167], v[196:199], v[64:67]
	v_mfma_f32_16x16x32_bf16 v[116:119], v[160:163], v[176:179], v[116:119]
	v_mfma_f32_16x16x32_bf16 v[112:115], v[168:171], v[176:179], v[112:115]
	v_mfma_f32_16x16x32_bf16 v[100:103], v[160:163], v[184:187], v[100:103]
	v_mfma_f32_16x16x32_bf16 v[96:99], v[168:171], v[184:187], v[96:99]
	v_mfma_f32_16x16x32_bf16 v[84:87], v[160:163], v[192:195], v[84:87]
	v_mfma_f32_16x16x32_bf16 v[80:83], v[168:171], v[192:195], v[80:83]
	v_mfma_f32_16x16x32_bf16 v[68:71], v[160:163], v[204:207], v[68:71]
	v_mfma_f32_16x16x32_bf16 v[64:67], v[168:171], v[204:207], v[64:67]
	s_barrier
	s_add_i32 s8, s8, s14
	v_lshl_add_u64 v[208:209], v[208:209], 0, s[90:91]
	s_mov_b32 m0, s8
	ds_read_b128 v[172:175], v203 offset:49152
	ds_read_b128 v[176:179], v203 offset:50176
	ds_read_b128 v[180:183], v203 offset:51200
	ds_read_b128 v[184:187], v203 offset:52224
	ds_read_b128 v[188:191], v203 offset:53248
	ds_read_b128 v[192:195], v203 offset:54272
	ds_read_b128 v[196:199], v203 offset:55296
	ds_read_b128 v[204:207], v203 offset:56320
	global_load_lds_dwordx4 v[208:209], off
	s_add_i32 m0, s8, 0x2000
	s_add_u32 s44, s58, 0x40080
	v_lshl_add_u64 v[208:209], v[210:211], 0, s[90:91]
	s_addc_u32 s45, s59, 0
	s_add_i32 s8, s85, s14
	global_load_lds_dwordx4 v[208:209], off
	v_lshl_add_u64 v[208:209], s[44:45], 0, v[128:129]
	s_mov_b32 m0, s8
	s_nop 0
	global_load_lds_dwordx4 v[208:209], off
	v_lshl_add_u64 v[208:209], s[44:45], 0, v[146:147]
	s_add_i32 m0, s8, 0x2000
	s_nop 0
	global_load_lds_dwordx4 v[208:209], off
	v_lshl_add_u64 v[208:209], v[214:215], 0, s[90:91]
	s_mov_b32 m0, s30
	s_nop 0
	global_load_lds_dwordx4 v[208:209], off
	v_lshl_add_u64 v[208:209], v[222:223], 0, s[90:91]
	s_mov_b32 m0, s31
	s_nop 0
	global_load_lds_dwordx4 v[208:209], off
	s_waitcnt vmcnt(8)
	s_waitcnt lgkmcnt(0)
	s_barrier
	s_waitcnt lgkmcnt(0)
	v_mfma_f32_16x16x32_bf16 v[60:63], v[130:133], v[172:175], v[60:63]
	v_mfma_f32_16x16x32_bf16 v[56:59], v[138:141], v[172:175], v[56:59]
	v_mfma_f32_16x16x32_bf16 v[44:47], v[130:133], v[180:183], v[44:47]
	v_mfma_f32_16x16x32_bf16 v[40:43], v[138:141], v[180:183], v[40:43]
	v_mfma_f32_16x16x32_bf16 v[28:31], v[130:133], v[188:191], v[28:31]
	v_mfma_f32_16x16x32_bf16 v[24:27], v[138:141], v[188:191], v[24:27]
	v_mfma_f32_16x16x32_bf16 v[12:15], v[130:133], v[196:199], v[12:15]
	v_mfma_f32_16x16x32_bf16 v[8:11], v[138:141], v[196:199], v[8:11]
	v_mfma_f32_16x16x32_bf16 v[60:63], v[134:137], v[176:179], v[60:63]
	v_mfma_f32_16x16x32_bf16 v[56:59], v[142:145], v[176:179], v[56:59]
	v_mfma_f32_16x16x32_bf16 v[44:47], v[134:137], v[184:187], v[44:47]
	v_mfma_f32_16x16x32_bf16 v[40:43], v[142:145], v[184:187], v[40:43]
	v_mfma_f32_16x16x32_bf16 v[28:31], v[134:137], v[192:195], v[28:31]
	v_mfma_f32_16x16x32_bf16 v[24:27], v[142:145], v[192:195], v[24:27]
	v_mfma_f32_16x16x32_bf16 v[12:15], v[134:137], v[204:207], v[12:15]
	v_mfma_f32_16x16x32_bf16 v[8:11], v[142:145], v[204:207], v[8:11]
	v_mfma_f32_16x16x32_bf16 v[52:55], v[156:159], v[172:175], v[52:55]
	v_mfma_f32_16x16x32_bf16 v[48:51], v[164:167], v[172:175], v[48:51]
	v_mfma_f32_16x16x32_bf16 v[36:39], v[156:159], v[180:183], v[36:39]
	v_mfma_f32_16x16x32_bf16 v[32:35], v[164:167], v[180:183], v[32:35]
	v_mfma_f32_16x16x32_bf16 v[20:23], v[156:159], v[188:191], v[20:23]
	v_mfma_f32_16x16x32_bf16 v[16:19], v[164:167], v[188:191], v[16:19]
	v_mfma_f32_16x16x32_bf16 v[4:7], v[156:159], v[196:199], v[4:7]
	v_mfma_f32_16x16x32_bf16 v[0:3], v[164:167], v[196:199], v[0:3]
	v_mfma_f32_16x16x32_bf16 v[52:55], v[160:163], v[176:179], v[52:55]
	v_mfma_f32_16x16x32_bf16 v[48:51], v[168:171], v[176:179], v[48:51]
	v_mfma_f32_16x16x32_bf16 v[36:39], v[160:163], v[184:187], v[36:39]
	v_mfma_f32_16x16x32_bf16 v[32:35], v[168:171], v[184:187], v[32:35]
	v_mfma_f32_16x16x32_bf16 v[20:23], v[160:163], v[192:195], v[20:23]
	v_mfma_f32_16x16x32_bf16 v[16:19], v[168:171], v[192:195], v[16:19]
	v_mfma_f32_16x16x32_bf16 v[4:7], v[160:163], v[204:207], v[4:7]
	v_mfma_f32_16x16x32_bf16 v[0:3], v[168:171], v[204:207], v[0:3]
	s_barrier
	s_add_i32 s84, s84, 2
	s_add_u32 vcc_lo, vcc_lo, 0x100
	s_addc_u32 vcc_hi, vcc_hi, 0
	s_add_u32 s88, s88, 0x100
	s_addc_u32 s94, s94, 0
	s_cmp_gt_u32 s84, 13
	s_cbranch_scc0 .LBB0_564
	s_setprio 0
	s_and_b64 vcc, exec, s[62:63]
	s_cbranch_vccz .LBB0_567
	s_barrier

; #define PG8_STAGE(bufoff, gbase, voff) do { _Pragma("unroll") for (int _i = 0; _i < 2; ++_i) \
;         __builtin_amdgcn_global_load_lds((const unsigned*)((const char*)(gbase) + (voff)[_i]), (PG8_LAS unsigned*)(lds + (bufoff) + ldsw + _i * 8192), 16, 0, 0); } while (0)
; #define PG8_LDA(dst, b, h) do { _Pragma("unroll") for (int m = 0; m < 4; ++m) _Pragma("unroll") for (int k = 0; k < 2; ++k) dst[m][k] = *(const PG8_LAS bf16x8*)(lds + PG8_SA(b, h) + aoff + m * 2048 + k * 1024); } while (0)
; #define PG8_LDB(dst, b, h) do { _Pragma("unroll") for (int n = 0; n < 2; ++n) _Pragma("unroll") for (int k = 0; k < 2; ++k) dst[n][k] = *(const PG8_LAS bf16x8*)(lds + PG8_SB(b, h) + boff + n * 2048 + k * 1024); } while (0)
; #define PG8_WAIT_V(n) asm volatile("s_waitcnt vmcnt(" #n ")" ::: "memory")
; #define PG8_WAIT_L(n) asm volatile("s_waitcnt lgkmcnt(" #n ")" ::: "memory")
; #define PG8_BAR __builtin_amdgcn_s_barrier()
; template <class Epi, class Sched, bool ALIGN_EPI = false, bool SP2 = false>
; __device__ __forceinline__ void gemm_phase(PG8_LAS unsigned char* lds, const Gemm g, const Sched& S, const Epi& E) {
;     ...
;     for (;;) {
;         const bool has_next = S.next(ui + 1, nxt);
;         const char* nA = has_next ? (const char*)g.A + (size_t)nxt.pm * tstep : cA; const char* nB = has_next ? (const char*)g.Bt + (size_t)nxt.pn * tstep : cB;
;         for (int t = 0; t < nt; t += 2) {
;             const bool last = (t == nt - 2);
;             const char* a1 = cA + (size_t)(t + 1) * kstep;
;             const char* a2 = last ? nA : cA + (size_t)(t + 2) * kstep; const char* b2 = last ? nB : cB + (size_t)(t + 2) * kstep;
;             const char* a3 = a2 + kstep; const char* b3 = b2 + kstep;
;             if (last && has_next) S.a_ready(nxt);
;             if constexpr (SP2) {
;             PG8_LDB(B0, 0, 0); PG8_LDB(B1, 0, 1); PG8_SCHED; PG8_LDA(At, 0, 0); PG8_STAGE(PG8_SA(1, 1), a1 + hstep, voffA);
;             PG8_WAIT_V(8); PG8_WAIT_L(0); PG8_BAR; PG8_MMA(0, 0, At, B0); PG8_MMA(0, 1, At, B1); PG8_BAR; PG8_SCHED;
;     ...
; #pragma unroll
;         for (int a = 0; a < 2; ++a)
; #pragma unroll
;             for (int b = 0; b < 2; ++b)
; #pragma unroll
;                 for (int m = 0; m < 4; ++m)
; #pragma unroll
;                     for (int n = 0; n < 2; ++n) acc[a][b][m][n] = (f32x4){0.f, 0.f, 0.f, 0.f};
;         cur = nxt; cA = nA; cB = nB; ++ui;
.LBB0_597:
	s_ashr_i32 s93, s92, 31
	s_lshl_b64 s[36:37], s[92:93], 19
	s_add_u32 s44, s2, s36
	s_addc_u32 s45, s25, s37
	s_and_b64 s[36:37], s[40:41], exec
	s_cselect_b32 s35, s45, s65
	s_cselect_b32 s36, s44, s64
	s_ashr_i32 s97, s96, 31
	s_lshl_b64 s[62:63], s[96:97], 19
	s_add_u32 s62, s70, s62
	s_addc_u32 s63, s16, s63
	s_and_b64 s[84:85], s[40:41], exec
	s_cselect_b32 s37, s63, s59
	s_cselect_b32 s43, s62, s58
	s_add_u32 vcc_lo, s64, 0x40080
	s_addc_u32 vcc_hi, s65, 0
	s_add_u32 s88, s58, 0x100
	v_mov_b64_e32 v[0:1], 0
	s_addc_u32 s93, s59, 0
	s_mov_b32 s94, -2
	v_mov_b64_e32 v[2:3], 0
	v_mov_b64_e32 v[4:5], 0
	v_mov_b64_e32 v[6:7], 0
	v_mov_b64_e32 v[16:17], 0
	v_mov_b64_e32 v[18:19], 0
	v_mov_b64_e32 v[20:21], 0
	v_mov_b64_e32 v[22:23], 0
	v_mov_b64_e32 v[32:33], 0
	v_mov_b64_e32 v[34:35], 0
	v_mov_b64_e32 v[36:37], 0
	v_mov_b64_e32 v[38:39], 0
	v_mov_b64_e32 v[40:41], 0
	v_mov_b64_e32 v[42:43], 0
	v_mov_b64_e32 v[48:49], 0
	v_mov_b64_e32 v[50:51], 0
	v_mov_b64_e32 v[8:9], 0
	v_mov_b64_e32 v[10:11], 0
	v_mov_b64_e32 v[12:13], 0
	v_mov_b64_e32 v[14:15], 0
	v_mov_b64_e32 v[24:25], 0
	v_mov_b64_e32 v[26:27], 0
	v_mov_b64_e32 v[28:29], 0
	v_mov_b64_e32 v[30:31], 0
	v_mov_b64_e32 v[44:45], 0
	v_mov_b64_e32 v[46:47], 0
	v_mov_b64_e32 v[52:53], 0
	v_mov_b64_e32 v[54:55], 0
	v_mov_b64_e32 v[56:57], 0
	v_mov_b64_e32 v[58:59], 0
	v_mov_b64_e32 v[60:61], 0
	v_mov_b64_e32 v[62:63], 0
	v_mov_b64_e32 v[80:81], 0
	v_mov_b64_e32 v[82:83], 0
	v_mov_b64_e32 v[84:85], 0
	v_mov_b64_e32 v[86:87], 0
	v_mov_b64_e32 v[88:89], 0
	v_mov_b64_e32 v[90:91], 0
	v_mov_b64_e32 v[96:97], 0
	v_mov_b64_e32 v[98:99], 0
	v_mov_b64_e32 v[112:113], 0
	v_mov_b64_e32 v[114:115], 0
	v_mov_b64_e32 v[116:117], 0
	v_mov_b64_e32 v[118:119], 0
	v_mov_b64_e32 v[120:121], 0
	v_mov_b64_e32 v[122:123], 0
	v_mov_b64_e32 v[130:131], 0
	v_mov_b64_e32 v[132:133], 0
	v_mov_b64_e32 v[92:93], 0
	v_mov_b64_e32 v[94:95], 0
	v_mov_b64_e32 v[100:101], 0
	v_mov_b64_e32 v[102:103], 0
	v_mov_b64_e32 v[104:105], 0
	v_mov_b64_e32 v[106:107], 0
	v_mov_b64_e32 v[108:109], 0
	v_mov_b64_e32 v[110:111], 0
	v_mov_b64_e32 v[124:125], 0
	v_mov_b64_e32 v[126:127], 0
	v_mov_b64_e32 v[134:135], 0
	v_mov_b64_e32 v[136:137], 0
	v_mov_b64_e32 v[138:139], 0
	v_mov_b64_e32 v[140:141], 0
	v_mov_b64_e32 v[142:143], 0
	v_mov_b64_e32 v[144:145], 0
	s_and_b64 s[98:99], exec, s[72:73]
	s_cbranch_scc1 .Lsp_3
	s_setprio 1
.Lsp_3:
.LBB0_598:
	s_add_u32 s58, vcc_lo, 0xfffc0080
	s_addc_u32 s59, vcc_hi, -1
	s_add_i32 s84, 0, 0x10000
	s_cmp_eq_u32 s94, 12
	s_cselect_b32 s65, s35, s59
	s_cselect_b32 s64, s36, s58
	s_cselect_b32 s59, s37, s93
	s_cselect_b32 s58, s43, s88
	s_add_i32 s97, 0, 0x14000
	v_add_u32_e32 v76, s84, v228
	v_add_u32_e32 v168, s97, v228
	ds_read_b128 v[64:67], v76
	ds_read_b128 v[68:71], v76 offset:1024
	ds_read_b128 v[72:75], v76 offset:2048
	ds_read_b128 v[76:79], v76 offset:3072
	ds_read_b128 v[156:159], v168
	ds_read_b128 v[160:163], v168 offset:1024
	ds_read_b128 v[164:167], v168 offset:2048
	ds_read_b128 v[168:171], v168 offset:3072
	v_lshl_add_u64 v[204:205], vcc, 0, v[152:153]
	s_add_i32 m0, s18, 0xc000
	ds_read_b128 v[172:175], v230
	ds_read_b128 v[176:179], v230 offset:1024
	ds_read_b128 v[180:183], v230 offset:2048
	ds_read_b128 v[184:187], v230 offset:3072
	ds_read_b128 v[188:191], v230 offset:4096
	ds_read_b128 v[192:195], v230 offset:5120
	ds_read_b128 v[196:199], v230 offset:6144
	ds_read_b128 v[200:203], v230 offset:7168
	global_load_lds_dwordx4 v[204:205], off
	v_lshl_add_u64 v[204:205], vcc, 0, v[154:155]
	s_add_i32 m0, s18, 0xe000
	s_nop 0
	global_load_lds_dwordx4 v[204:205], off
	s_waitcnt vmcnt(8)
	s_waitcnt lgkmcnt(0)
	s_barrier
	s_waitcnt lgkmcnt(0)
	v_mfma_f32_16x16x32_bf16 v[142:145], v[64:67], v[172:175], v[142:145]
	v_mfma_f32_16x16x32_bf16 v[138:141], v[72:75], v[172:175], v[138:141]
	v_mfma_f32_16x16x32_bf16 v[134:137], v[64:67], v[180:183], v[134:137]
	v_mfma_f32_16x16x32_bf16 v[124:127], v[72:75], v[180:183], v[124:127]
	v_mfma_f32_16x16x32_bf16 v[108:111], v[64:67], v[188:191], v[108:111]
	v_mfma_f32_16x16x32_bf16 v[104:107], v[72:75], v[188:191], v[104:107]
	v_mfma_f32_16x16x32_bf16 v[100:103], v[64:67], v[196:199], v[100:103]
	v_mfma_f32_16x16x32_bf16 v[92:95], v[72:75], v[196:199], v[92:95]
	v_mfma_f32_16x16x32_bf16 v[142:145], v[68:71], v[176:179], v[142:145]
	v_mfma_f32_16x16x32_bf16 v[138:141], v[76:79], v[176:179], v[138:141]
	v_mfma_f32_16x16x32_bf16 v[134:137], v[68:71], v[184:187], v[134:137]
	v_mfma_f32_16x16x32_bf16 v[124:127], v[76:79], v[184:187], v[124:127]
	v_mfma_f32_16x16x32_bf16 v[108:111], v[68:71], v[192:195], v[108:111]
	v_mfma_f32_16x16x32_bf16 v[104:107], v[76:79], v[192:195], v[104:107]
	v_mfma_f32_16x16x32_bf16 v[100:103], v[68:71], v[200:203], v[100:103]
	v_mfma_f32_16x16x32_bf16 v[92:95], v[76:79], v[200:203], v[92:95]
	v_mfma_f32_16x16x32_bf16 v[130:133], v[156:159], v[172:175], v[130:133]
	v_mfma_f32_16x16x32_bf16 v[120:123], v[164:167], v[172:175], v[120:123]
	v_mfma_f32_16x16x32_bf16 v[116:119], v[156:159], v[180:183], v[116:119]
	v_mfma_f32_16x16x32_bf16 v[112:115], v[164:167], v[180:183], v[112:115]
	v_mfma_f32_16x16x32_bf16 v[96:99], v[156:159], v[188:191], v[96:99]
	v_mfma_f32_16x16x32_bf16 v[88:91], v[164:167], v[188:191], v[88:91]
	v_mfma_f32_16x16x32_bf16 v[84:87], v[156:159], v[196:199], v[84:87]
	v_mfma_f32_16x16x32_bf16 v[80:83], v[164:167], v[196:199], v[80:83]
	v_mfma_f32_16x16x32_bf16 v[130:133], v[160:163], v[176:179], v[130:133]
	v_mfma_f32_16x16x32_bf16 v[120:123], v[168:171], v[176:179], v[120:123]
	v_mfma_f32_16x16x32_bf16 v[116:119], v[160:163], v[184:187], v[116:119]
	v_mfma_f32_16x16x32_bf16 v[112:115], v[168:171], v[184:187], v[112:115]
	v_mfma_f32_16x16x32_bf16 v[96:99], v[160:163], v[192:195], v[96:99]
	v_mfma_f32_16x16x32_bf16 v[88:91], v[168:171], v[192:195], v[88:91]
	v_mfma_f32_16x16x32_bf16 v[84:87], v[160:163], v[200:203], v[84:87]
	v_mfma_f32_16x16x32_bf16 v[80:83], v[168:171], v[200:203], v[80:83]
	s_barrier
; #define PG8_STAGE(bufoff, gbase, voff) do { _Pragma("unroll") for (int _i = 0; _i < 2; ++_i) \
;         __builtin_amdgcn_global_load_lds((const unsigned*)((const char*)(gbase) + (voff)[_i]), (PG8_LAS unsigned*)(lds + (bufoff) + ldsw + _i * 8192), 16, 0, 0); } while (0)
; #define PG8_LDA(dst, b, h) do { _Pragma("unroll") for (int m = 0; m < 4; ++m) _Pragma("unroll") for (int k = 0; k < 2; ++k) dst[m][k] = *(const PG8_LAS bf16x8*)(lds + PG8_SA(b, h) + aoff + m * 2048 + k * 1024); } while (0)
; #define PG8_LDB(dst, b, h) do { _Pragma("unroll") for (int n = 0; n < 2; ++n) _Pragma("unroll") for (int k = 0; k < 2; ++k) dst[n][k] = *(const PG8_LAS bf16x8*)(lds + PG8_SB(b, h) + boff + n * 2048 + k * 1024); } while (0)
; #define PG8_MMA(ai, bj, At, Bt) do { __builtin_amdgcn_s_setprio(1); _Pragma("unroll") for (int m = 0; m < 4; ++m) _Pragma("unroll") for (int n = 0; n < 2; ++n) _Pragma("unroll") for (int k = 0; k < 2; ++k) \
;         acc[ai][bj][m][n] = __builtin_amdgcn_mfma_f32_16x16x32_bf16(Bt[n][k], At[m][k], acc[ai][bj][m][n], 0, 0, 0); __builtin_amdgcn_s_setprio(0); } while (0)
; #define PG8_WAIT_V(n) asm volatile("s_waitcnt vmcnt(" #n ")" ::: "memory")
; #define PG8_WAIT_L(n) asm volatile("s_waitcnt lgkmcnt(" #n ")" ::: "memory")
; #define PG8_BAR __builtin_amdgcn_s_barrier()
; #define PG8_SCHED __builtin_amdgcn_sched_barrier(0)
; template <class Epi, class Sched, bool ALIGN_EPI = false, bool SP2 = false>
; __device__ __forceinline__ void gemm_phase(PG8_LAS unsigned char* lds, const Gemm g, const Sched& S, const Epi& E) {
;     ...
;             PG8_LDA(At, 0, 1); PG8_STAGE(PG8_SB(0, 0), b2, voffB); PG8_STAGE(PG8_SB(0, 1), b2 + hstep, voffB); PG8_STAGE(PG8_SA(0, 0), a2, voffA);
;             PG8_WAIT_V(8); PG8_WAIT_L(0); PG8_BAR; PG8_MMA(1, 0, At, B0); PG8_MMA(1, 1, At, B1); PG8_BAR; PG8_SCHED;
;             PG8_LDB(B0, 1, 0); PG8_LDB(B1, 1, 1); PG8_SCHED; PG8_LDA(At, 1, 0); PG8_STAGE(PG8_SA(0, 1), a2 + hstep, voffA);
;             PG8_WAIT_V(8); PG8_WAIT_L(0); PG8_BAR; PG8_MMA(0, 0, At, B0); PG8_MMA(0, 1, At, B1); PG8_BAR; PG8_SCHED;
	s_add_i32 s84, s84, s17
	v_lshl_add_u64 v[204:205], s[58:59], 0, v[128:129]
	s_mov_b32 m0, s84
	ds_read_b128 v[172:175], v230 offset:16384
	ds_read_b128 v[176:179], v230 offset:17408
	ds_read_b128 v[180:183], v230 offset:18432
	ds_read_b128 v[184:187], v230 offset:19456
	ds_read_b128 v[188:191], v230 offset:20480
	ds_read_b128 v[192:195], v230 offset:21504
	ds_read_b128 v[196:199], v230 offset:22528
	ds_read_b128 v[200:203], v230 offset:23552
	global_load_lds_dwordx4 v[204:205], off
	s_add_i32 m0, s84, 0x2000
	s_add_u32 s84, s58, 0x40000
	v_lshl_add_u64 v[206:207], s[58:59], 0, v[146:147]
	s_addc_u32 s85, s59, 0
	s_add_i32 s97, s97, s17
	global_load_lds_dwordx4 v[206:207], off
	v_lshl_add_u64 v[208:209], s[84:85], 0, v[128:129]
	s_mov_b32 m0, s97
	v_lshl_add_u64 v[210:211], s[64:65], 0, v[148:149]
	global_load_lds_dwordx4 v[208:209], off
	v_lshl_add_u64 v[208:209], s[84:85], 0, v[146:147]
	s_add_i32 m0, s97, 0x2000
	s_nop 0
	global_load_lds_dwordx4 v[208:209], off
	v_lshl_add_u64 v[208:209], s[64:65], 0, v[150:151]
	s_mov_b32 m0, s18
	s_nop 0
	global_load_lds_dwordx4 v[208:209], off
	s_mov_b32 m0, s19
	s_nop 0
	global_load_lds_dwordx4 v[210:211], off
	s_waitcnt vmcnt(8)
	s_waitcnt lgkmcnt(0)
	s_barrier
	s_waitcnt lgkmcnt(0)
	v_mfma_f32_16x16x32_bf16 v[60:63], v[64:67], v[172:175], v[60:63]
	v_mfma_f32_16x16x32_bf16 v[56:59], v[72:75], v[172:175], v[56:59]
	v_mfma_f32_16x16x32_bf16 v[52:55], v[64:67], v[180:183], v[52:55]
	v_mfma_f32_16x16x32_bf16 v[44:47], v[72:75], v[180:183], v[44:47]
	v_mfma_f32_16x16x32_bf16 v[28:31], v[64:67], v[188:191], v[28:31]
	v_mfma_f32_16x16x32_bf16 v[24:27], v[72:75], v[188:191], v[24:27]
	v_mfma_f32_16x16x32_bf16 v[12:15], v[64:67], v[196:199], v[12:15]
	v_mfma_f32_16x16x32_bf16 v[8:11], v[72:75], v[196:199], v[8:11]
	v_mfma_f32_16x16x32_bf16 v[60:63], v[68:71], v[176:179], v[60:63]
	v_mfma_f32_16x16x32_bf16 v[56:59], v[76:79], v[176:179], v[56:59]
	v_mfma_f32_16x16x32_bf16 v[52:55], v[68:71], v[184:187], v[52:55]
	v_mfma_f32_16x16x32_bf16 v[44:47], v[76:79], v[184:187], v[44:47]
	v_mfma_f32_16x16x32_bf16 v[28:31], v[68:71], v[192:195], v[28:31]
	v_mfma_f32_16x16x32_bf16 v[24:27], v[76:79], v[192:195], v[24:27]
	v_mfma_f32_16x16x32_bf16 v[12:15], v[68:71], v[200:203], v[12:15]
	v_mfma_f32_16x16x32_bf16 v[8:11], v[76:79], v[200:203], v[8:11]
	v_mfma_f32_16x16x32_bf16 v[48:51], v[156:159], v[172:175], v[48:51]
	v_mfma_f32_16x16x32_bf16 v[40:43], v[164:167], v[172:175], v[40:43]
	v_mfma_f32_16x16x32_bf16 v[36:39], v[156:159], v[180:183], v[36:39]
	v_mfma_f32_16x16x32_bf16 v[32:35], v[164:167], v[180:183], v[32:35]
	v_mfma_f32_16x16x32_bf16 v[20:23], v[156:159], v[188:191], v[20:23]
	v_mfma_f32_16x16x32_bf16 v[16:19], v[164:167], v[188:191], v[16:19]
	v_mfma_f32_16x16x32_bf16 v[4:7], v[156:159], v[196:199], v[4:7]
	v_mfma_f32_16x16x32_bf16 v[0:3], v[164:167], v[196:199], v[0:3]
	v_mfma_f32_16x16x32_bf16 v[48:51], v[160:163], v[176:179], v[48:51]
	v_mfma_f32_16x16x32_bf16 v[40:43], v[168:171], v[176:179], v[40:43]
	v_mfma_f32_16x16x32_bf16 v[36:39], v[160:163], v[184:187], v[36:39]
	v_mfma_f32_16x16x32_bf16 v[32:35], v[168:171], v[184:187], v[32:35]
	v_mfma_f32_16x16x32_bf16 v[20:23], v[160:163], v[192:195], v[20:23]
	v_mfma_f32_16x16x32_bf16 v[16:19], v[168:171], v[192:195], v[16:19]
	v_mfma_f32_16x16x32_bf16 v[4:7], v[160:163], v[200:203], v[4:7]
	v_mfma_f32_16x16x32_bf16 v[0:3], v[168:171], v[200:203], v[0:3]
	s_barrier
	s_add_i32 s84, 0, 0x18000
	s_add_i32 s85, 0, 0x1c000
	v_add_u32_e32 v76, s84, v228
	v_add_u32_e32 v168, s85, v228
	ds_read_b128 v[64:67], v76
	ds_read_b128 v[68:71], v76 offset:1024
	ds_read_b128 v[72:75], v76 offset:2048
	ds_read_b128 v[76:79], v76 offset:3072
	ds_read_b128 v[156:159], v168
	ds_read_b128 v[160:163], v168 offset:1024
	ds_read_b128 v[164:167], v168 offset:2048
	ds_read_b128 v[168:171], v168 offset:3072
	s_add_u32 s64, s64, 0x40000
	s_addc_u32 s65, s65, 0
	s_mov_b32 m0, s20
	v_lshl_add_u64 v[214:215], s[64:65], 0, v[150:151]
	ds_read_b128 v[172:175], v230 offset:32768
	ds_read_b128 v[176:179], v230 offset:33792
	ds_read_b128 v[180:183], v230 offset:34816
	ds_read_b128 v[184:187], v230 offset:35840
	ds_read_b128 v[188:191], v230 offset:36864
	ds_read_b128 v[192:195], v230 offset:37888
	ds_read_b128 v[196:199], v230 offset:38912
	ds_read_b128 v[200:203], v230 offset:39936
	global_load_lds_dwordx4 v[214:215], off
	v_lshl_add_u64 v[214:215], s[64:65], 0, v[148:149]
	s_mov_b32 m0, s21
	s_nop 0
	global_load_lds_dwordx4 v[214:215], off
	s_waitcnt vmcnt(8)
	s_waitcnt lgkmcnt(0)
	s_barrier
; #define PG8_STAGE(bufoff, gbase, voff) do { _Pragma("unroll") for (int _i = 0; _i < 2; ++_i) \
;         __builtin_amdgcn_global_load_lds((const unsigned*)((const char*)(gbase) + (voff)[_i]), (PG8_LAS unsigned*)(lds + (bufoff) + ldsw + _i * 8192), 16, 0, 0); } while (0)
; #define PG8_LDA(dst, b, h) do { _Pragma("unroll") for (int m = 0; m < 4; ++m) _Pragma("unroll") for (int k = 0; k < 2; ++k) dst[m][k] = *(const PG8_LAS bf16x8*)(lds + PG8_SA(b, h) + aoff + m * 2048 + k * 1024); } while (0)
; #define PG8_MMA(ai, bj, At, Bt) do { __builtin_amdgcn_s_setprio(1); _Pragma("unroll") for (int m = 0; m < 4; ++m) _Pragma("unroll") for (int n = 0; n < 2; ++n) _Pragma("unroll") for (int k = 0; k < 2; ++k) \
;         acc[ai][bj][m][n] = __builtin_amdgcn_mfma_f32_16x16x32_bf16(Bt[n][k], At[m][k], acc[ai][bj][m][n], 0, 0, 0); __builtin_amdgcn_s_setprio(0); } while (0)
; #define PG8_WAIT_V(n) asm volatile("s_waitcnt vmcnt(" #n ")" ::: "memory")
; #define PG8_WAIT_L(n) asm volatile("s_waitcnt lgkmcnt(" #n ")" ::: "memory")
; #define PG8_BAR __builtin_amdgcn_s_barrier()
; #define PG8_SCHED __builtin_amdgcn_sched_barrier(0)
; template <class Epi, class Sched, bool ALIGN_EPI = false, bool SP2 = false>
; __device__ __forceinline__ void gemm_phase(PG8_LAS unsigned char* lds, const Gemm g, const Sched& S, const Epi& E) {
;     ...
;             PG8_WAIT_V(8); PG8_WAIT_L(0); PG8_BAR; PG8_MMA(0, 0, At, B0); PG8_MMA(0, 1, At, B1); PG8_BAR; PG8_SCHED;
;             PG8_LDA(At, 1, 1); PG8_STAGE(PG8_SB(1, 0), b3, voffB); PG8_STAGE(PG8_SB(1, 1), b3 + hstep, voffB); PG8_STAGE(PG8_SA(1, 0), a3, voffA);
;             PG8_WAIT_V(8); PG8_WAIT_L(0); PG8_BAR; PG8_MMA(1, 0, At, B0); PG8_MMA(1, 1, At, B1); PG8_BAR; PG8_SCHED;
;     ...
;         if constexpr (ALIGN_EPI) { if (wr == 0) PG8_BAR; }
	s_waitcnt lgkmcnt(0)
	v_mfma_f32_16x16x32_bf16 v[142:145], v[64:67], v[172:175], v[142:145]
	v_mfma_f32_16x16x32_bf16 v[138:141], v[72:75], v[172:175], v[138:141]
	v_mfma_f32_16x16x32_bf16 v[134:137], v[64:67], v[180:183], v[134:137]
	v_mfma_f32_16x16x32_bf16 v[124:127], v[72:75], v[180:183], v[124:127]
	v_mfma_f32_16x16x32_bf16 v[108:111], v[64:67], v[188:191], v[108:111]
	v_mfma_f32_16x16x32_bf16 v[104:107], v[72:75], v[188:191], v[104:107]
	v_mfma_f32_16x16x32_bf16 v[100:103], v[64:67], v[196:199], v[100:103]
	v_mfma_f32_16x16x32_bf16 v[92:95], v[72:75], v[196:199], v[92:95]
	v_mfma_f32_16x16x32_bf16 v[142:145], v[68:71], v[176:179], v[142:145]
	v_mfma_f32_16x16x32_bf16 v[138:141], v[76:79], v[176:179], v[138:141]
	v_mfma_f32_16x16x32_bf16 v[134:137], v[68:71], v[184:187], v[134:137]
	v_mfma_f32_16x16x32_bf16 v[124:127], v[76:79], v[184:187], v[124:127]
	v_mfma_f32_16x16x32_bf16 v[108:111], v[68:71], v[192:195], v[108:111]
	v_mfma_f32_16x16x32_bf16 v[104:107], v[76:79], v[192:195], v[104:107]
	v_mfma_f32_16x16x32_bf16 v[100:103], v[68:71], v[200:203], v[100:103]
	v_mfma_f32_16x16x32_bf16 v[92:95], v[76:79], v[200:203], v[92:95]
	v_mfma_f32_16x16x32_bf16 v[130:133], v[156:159], v[172:175], v[130:133]
	v_mfma_f32_16x16x32_bf16 v[120:123], v[164:167], v[172:175], v[120:123]
	v_mfma_f32_16x16x32_bf16 v[116:119], v[156:159], v[180:183], v[116:119]
	v_mfma_f32_16x16x32_bf16 v[112:115], v[164:167], v[180:183], v[112:115]
	v_mfma_f32_16x16x32_bf16 v[96:99], v[156:159], v[188:191], v[96:99]
	v_mfma_f32_16x16x32_bf16 v[88:91], v[164:167], v[188:191], v[88:91]
	v_mfma_f32_16x16x32_bf16 v[84:87], v[156:159], v[196:199], v[84:87]
	v_mfma_f32_16x16x32_bf16 v[80:83], v[164:167], v[196:199], v[80:83]
	v_mfma_f32_16x16x32_bf16 v[130:133], v[160:163], v[176:179], v[130:133]
	v_mfma_f32_16x16x32_bf16 v[120:123], v[168:171], v[176:179], v[120:123]
	v_mfma_f32_16x16x32_bf16 v[116:119], v[160:163], v[184:187], v[116:119]
	v_mfma_f32_16x16x32_bf16 v[112:115], v[168:171], v[184:187], v[112:115]
	v_mfma_f32_16x16x32_bf16 v[96:99], v[160:163], v[192:195], v[96:99]
	v_mfma_f32_16x16x32_bf16 v[88:91], v[168:171], v[192:195], v[88:91]
	v_mfma_f32_16x16x32_bf16 v[84:87], v[160:163], v[200:203], v[84:87]
	v_mfma_f32_16x16x32_bf16 v[80:83], v[168:171], v[200:203], v[80:83]
	s_barrier
	s_add_i32 s64, s84, s17
	v_lshl_add_u64 v[204:205], v[204:205], 0, s[90:91]
	s_mov_b32 m0, s64
	ds_read_b128 v[172:175], v230 offset:49152
	ds_read_b128 v[176:179], v230 offset:50176
	ds_read_b128 v[180:183], v230 offset:51200
	ds_read_b128 v[184:187], v230 offset:52224
	ds_read_b128 v[188:191], v230 offset:53248
	ds_read_b128 v[192:195], v230 offset:54272
	ds_read_b128 v[196:199], v230 offset:55296
	ds_read_b128 v[200:203], v230 offset:56320
	global_load_lds_dwordx4 v[204:205], off
	s_add_i32 m0, s64, 0x2000
	s_add_u32 s58, s58, 0x40080
	v_lshl_add_u64 v[204:205], v[206:207], 0, s[90:91]
	s_addc_u32 s59, s59, 0
	s_add_i32 s64, s85, s17
	global_load_lds_dwordx4 v[204:205], off
	v_lshl_add_u64 v[204:205], s[58:59], 0, v[128:129]
	s_mov_b32 m0, s64
	s_nop 0
	global_load_lds_dwordx4 v[204:205], off
	v_lshl_add_u64 v[204:205], s[58:59], 0, v[146:147]
	s_add_i32 m0, s64, 0x2000
	s_nop 0
	global_load_lds_dwordx4 v[204:205], off
	v_lshl_add_u64 v[204:205], v[208:209], 0, s[90:91]
	s_mov_b32 m0, s28
	s_nop 0
	global_load_lds_dwordx4 v[204:205], off
	v_lshl_add_u64 v[204:205], v[210:211], 0, s[90:91]
	s_mov_b32 m0, s29
	s_nop 0
	global_load_lds_dwordx4 v[204:205], off
	s_waitcnt vmcnt(8)
	s_waitcnt lgkmcnt(0)
	s_barrier
	s_waitcnt lgkmcnt(0)
	v_mfma_f32_16x16x32_bf16 v[60:63], v[64:67], v[172:175], v[60:63]
	v_mfma_f32_16x16x32_bf16 v[56:59], v[72:75], v[172:175], v[56:59]
	v_mfma_f32_16x16x32_bf16 v[52:55], v[64:67], v[180:183], v[52:55]
	v_mfma_f32_16x16x32_bf16 v[44:47], v[72:75], v[180:183], v[44:47]
	v_mfma_f32_16x16x32_bf16 v[28:31], v[64:67], v[188:191], v[28:31]
	v_mfma_f32_16x16x32_bf16 v[24:27], v[72:75], v[188:191], v[24:27]
	v_mfma_f32_16x16x32_bf16 v[12:15], v[64:67], v[196:199], v[12:15]
	v_mfma_f32_16x16x32_bf16 v[8:11], v[72:75], v[196:199], v[8:11]
	v_mfma_f32_16x16x32_bf16 v[60:63], v[68:71], v[176:179], v[60:63]
	v_mfma_f32_16x16x32_bf16 v[56:59], v[76:79], v[176:179], v[56:59]
	v_mfma_f32_16x16x32_bf16 v[52:55], v[68:71], v[184:187], v[52:55]
	v_mfma_f32_16x16x32_bf16 v[44:47], v[76:79], v[184:187], v[44:47]
	v_mfma_f32_16x16x32_bf16 v[28:31], v[68:71], v[192:195], v[28:31]
	v_mfma_f32_16x16x32_bf16 v[24:27], v[76:79], v[192:195], v[24:27]
	v_mfma_f32_16x16x32_bf16 v[12:15], v[68:71], v[200:203], v[12:15]
	v_mfma_f32_16x16x32_bf16 v[8:11], v[76:79], v[200:203], v[8:11]
	v_mfma_f32_16x16x32_bf16 v[48:51], v[156:159], v[172:175], v[48:51]
	v_mfma_f32_16x16x32_bf16 v[40:43], v[164:167], v[172:175], v[40:43]
	v_mfma_f32_16x16x32_bf16 v[36:39], v[156:159], v[180:183], v[36:39]
	v_mfma_f32_16x16x32_bf16 v[32:35], v[164:167], v[180:183], v[32:35]
	v_mfma_f32_16x16x32_bf16 v[20:23], v[156:159], v[188:191], v[20:23]
	v_mfma_f32_16x16x32_bf16 v[16:19], v[164:167], v[188:191], v[16:19]
	v_mfma_f32_16x16x32_bf16 v[4:7], v[156:159], v[196:199], v[4:7]
	v_mfma_f32_16x16x32_bf16 v[0:3], v[164:167], v[196:199], v[0:3]
	v_mfma_f32_16x16x32_bf16 v[48:51], v[160:163], v[176:179], v[48:51]
	v_mfma_f32_16x16x32_bf16 v[40:43], v[168:171], v[176:179], v[40:43]
	v_mfma_f32_16x16x32_bf16 v[36:39], v[160:163], v[184:187], v[36:39]
	v_mfma_f32_16x16x32_bf16 v[32:35], v[168:171], v[184:187], v[32:35]
	v_mfma_f32_16x16x32_bf16 v[20:23], v[160:163], v[192:195], v[20:23]
	v_mfma_f32_16x16x32_bf16 v[16:19], v[168:171], v[192:195], v[16:19]
	v_mfma_f32_16x16x32_bf16 v[4:7], v[160:163], v[200:203], v[4:7]
	v_mfma_f32_16x16x32_bf16 v[0:3], v[168:171], v[200:203], v[0:3]
	s_barrier
	s_add_i32 s94, s94, 2
	s_add_u32 vcc_lo, vcc_lo, 0x100
	s_addc_u32 vcc_hi, vcc_hi, 0
	s_add_u32 s88, s88, 0x100
	s_addc_u32 s93, s93, 0
	s_cmp_gt_u32 s94, 13
	s_cbranch_scc0 .LBB0_598
	s_setprio 0
	s_and_b64 vcc, exec, s[72:73]
	s_cbranch_vccz .LBB0_601
	s_barrier

; #define PG8_STAGE(bufoff, gbase, voff) do { _Pragma("unroll") for (int _i = 0; _i < 2; ++_i) \
;         __builtin_amdgcn_global_load_lds((const unsigned*)((const char*)(gbase) + (voff)[_i]), (PG8_LAS unsigned*)(lds + (bufoff) + ldsw + _i * 8192), 16, 0, 0); } while (0)
; #define PG8_LDA(dst, b, h) do { _Pragma("unroll") for (int m = 0; m < 4; ++m) _Pragma("unroll") for (int k = 0; k < 2; ++k) dst[m][k] = *(const PG8_LAS bf16x8*)(lds + PG8_SA(b, h) + aoff + m * 2048 + k * 1024); } while (0)
; #define PG8_LDB(dst, b, h) do { _Pragma("unroll") for (int n = 0; n < 2; ++n) _Pragma("unroll") for (int k = 0; k < 2; ++k) dst[n][k] = *(const PG8_LAS bf16x8*)(lds + PG8_SB(b, h) + boff + n * 2048 + k * 1024); } while (0)
; #define PG8_WAIT_V(n) asm volatile("s_waitcnt vmcnt(" #n ")" ::: "memory")
; #define PG8_WAIT_L(n) asm volatile("s_waitcnt lgkmcnt(" #n ")" ::: "memory")
; #define PG8_BAR __builtin_amdgcn_s_barrier()
; template <class Epi, class Sched, bool ALIGN_EPI = false, bool SP2 = false>
; __device__ __forceinline__ void gemm_phase(PG8_LAS unsigned char* lds, const Gemm g, const Sched& S, const Epi& E) {
;     ...
;     for (;;) {
;         const bool has_next = S.next(ui + 1, nxt);
;         const char* nA = has_next ? (const char*)g.A + (size_t)nxt.pm * tstep : cA; const char* nB = has_next ? (const char*)g.Bt + (size_t)nxt.pn * tstep : cB;
;         for (int t = 0; t < nt; t += 2) {
;             const bool last = (t == nt - 2);
;             const char* a1 = cA + (size_t)(t + 1) * kstep;
;             const char* a2 = last ? nA : cA + (size_t)(t + 2) * kstep; const char* b2 = last ? nB : cB + (size_t)(t + 2) * kstep;
;             const char* a3 = a2 + kstep; const char* b3 = b2 + kstep;
;             if (last && has_next) S.a_ready(nxt);
;             if constexpr (SP2) {
;             PG8_LDB(B0, 0, 0); PG8_LDB(B1, 0, 1); PG8_SCHED; PG8_LDA(At, 0, 0); PG8_STAGE(PG8_SA(1, 1), a1 + hstep, voffA);
;             PG8_WAIT_V(8); PG8_WAIT_L(0); PG8_BAR; PG8_MMA(0, 0, At, B0); PG8_MMA(0, 1, At, B1); PG8_BAR; PG8_SCHED;
;     ...
; #pragma unroll
;         for (int a = 0; a < 2; ++a)
; #pragma unroll
;             for (int b = 0; b < 2; ++b)
; #pragma unroll
;                 for (int m = 0; m < 4; ++m)
; #pragma unroll
;                     for (int n = 0; n < 2; ++n) acc[a][b][m][n] = (f32x4){0.f, 0.f, 0.f, 0.f};
;         cur = nxt; cA = nA; cB = nB; ++ui;
.LBB0_812:
	s_ashr_i32 s49, s48, 31
	s_lshl_b64 s[28:29], s[48:49], 19
	s_add_u32 s52, s2, s28
	s_addc_u32 s53, s14, s29
	s_and_b64 s[28:29], s[38:39], exec
	s_cselect_b32 s28, s53, s65
	s_cselect_b32 s29, s52, s64
	s_ashr_i32 s51, s50, 31
	s_lshl_b64 s[30:31], s[50:51], 19
	s_add_u32 s62, s15, s30
	s_addc_u32 s63, s16, s31
	s_and_b64 s[30:31], s[38:39], exec
	s_cselect_b32 s30, s63, s59
	s_cselect_b32 s31, s62, s58
	s_add_u32 s66, s64, 0x40080
	s_addc_u32 s67, s65, 0
	s_add_u32 s34, s58, 0x100
	v_mov_b64_e32 v[0:1], 0
	s_addc_u32 s35, s59, 0
	s_mov_b32 s36, -2
	v_mov_b64_e32 v[2:3], 0
	v_mov_b64_e32 v[8:9], 0
	v_mov_b64_e32 v[10:11], 0
	v_mov_b64_e32 v[16:17], 0
	v_mov_b64_e32 v[18:19], 0
	v_mov_b64_e32 v[24:25], 0
	v_mov_b64_e32 v[26:27], 0
	v_mov_b64_e32 v[32:33], 0
	v_mov_b64_e32 v[34:35], 0
	v_mov_b64_e32 v[40:41], 0
	v_mov_b64_e32 v[42:43], 0
	v_mov_b64_e32 v[48:49], 0
	v_mov_b64_e32 v[50:51], 0
	v_mov_b64_e32 v[56:57], 0
	v_mov_b64_e32 v[58:59], 0
	v_mov_b64_e32 v[4:5], 0
	v_mov_b64_e32 v[6:7], 0
	v_mov_b64_e32 v[12:13], 0
	v_mov_b64_e32 v[14:15], 0
	v_mov_b64_e32 v[20:21], 0
	v_mov_b64_e32 v[22:23], 0
	v_mov_b64_e32 v[28:29], 0
	v_mov_b64_e32 v[30:31], 0
	v_mov_b64_e32 v[36:37], 0
	v_mov_b64_e32 v[38:39], 0
	v_mov_b64_e32 v[44:45], 0
	v_mov_b64_e32 v[46:47], 0
	v_mov_b64_e32 v[52:53], 0
	v_mov_b64_e32 v[54:55], 0
	v_mov_b64_e32 v[60:61], 0
	v_mov_b64_e32 v[62:63], 0
	v_mov_b64_e32 v[64:65], 0
	v_mov_b64_e32 v[66:67], 0
	v_mov_b64_e32 v[72:73], 0
	v_mov_b64_e32 v[74:75], 0
	v_mov_b64_e32 v[80:81], 0
	v_mov_b64_e32 v[82:83], 0
	v_mov_b64_e32 v[88:89], 0
	v_mov_b64_e32 v[90:91], 0
	v_mov_b64_e32 v[96:97], 0
	v_mov_b64_e32 v[98:99], 0
	v_mov_b64_e32 v[104:105], 0
	v_mov_b64_e32 v[106:107], 0
	v_mov_b64_e32 v[112:113], 0
	v_mov_b64_e32 v[114:115], 0
	v_mov_b64_e32 v[120:121], 0
	v_mov_b64_e32 v[122:123], 0
	v_mov_b64_e32 v[68:69], 0
	v_mov_b64_e32 v[70:71], 0
	v_mov_b64_e32 v[76:77], 0
	v_mov_b64_e32 v[78:79], 0
	v_mov_b64_e32 v[84:85], 0
	v_mov_b64_e32 v[86:87], 0
	v_mov_b64_e32 v[92:93], 0
	v_mov_b64_e32 v[94:95], 0
	v_mov_b64_e32 v[100:101], 0
	v_mov_b64_e32 v[102:103], 0
	v_mov_b64_e32 v[108:109], 0
	v_mov_b64_e32 v[110:111], 0
	v_mov_b64_e32 v[116:117], 0
	v_mov_b64_e32 v[118:119], 0
	v_mov_b64_e32 v[124:125], 0
	v_mov_b64_e32 v[126:127], 0
	s_and_b64 s[98:99], exec, s[46:47]
	s_cbranch_scc1 .Lsp_0
	s_setprio 1
.Lsp_0:
.LBB0_813:
	s_add_u32 s8, s66, 0xfffc0080
	s_addc_u32 s37, s67, -1
	s_add_i32 s49, 0, 0x10000
	s_cmp_eq_u32 s36, 12
	s_cselect_b32 s65, s28, s37
	s_cselect_b32 s64, s29, s8
	s_cselect_b32 s59, s30, s35
	s_cselect_b32 s58, s31, s34
	s_add_i32 s8, 0, 0x14000
	v_add_u32_e32 v156, s49, v145
	v_add_u32_e32 v172, s8, v145
	ds_read_b128 v[140:143], v156
	ds_read_b128 v[148:151], v156 offset:1024
	ds_read_b128 v[152:155], v156 offset:2048
	ds_read_b128 v[156:159], v156 offset:3072
	ds_read_b128 v[160:163], v172
	ds_read_b128 v[164:167], v172 offset:1024
	ds_read_b128 v[168:171], v172 offset:2048
	ds_read_b128 v[172:175], v172 offset:3072
	v_lshl_add_u64 v[208:209], s[66:67], 0, v[136:137]
	s_add_i32 m0, s18, 0xc000
	ds_read_b128 v[176:179], v147
	ds_read_b128 v[180:183], v147 offset:1024
	ds_read_b128 v[184:187], v147 offset:2048
	ds_read_b128 v[188:191], v147 offset:3072
	ds_read_b128 v[192:195], v147 offset:4096
	ds_read_b128 v[196:199], v147 offset:5120
	ds_read_b128 v[200:203], v147 offset:6144
	ds_read_b128 v[204:207], v147 offset:7168
	global_load_lds_dwordx4 v[208:209], off
	v_lshl_add_u64 v[208:209], s[66:67], 0, v[138:139]
	s_add_i32 m0, s18, 0xe000
	s_nop 0
	global_load_lds_dwordx4 v[208:209], off
	s_waitcnt vmcnt(8)
	s_waitcnt lgkmcnt(0)
	s_barrier
	s_waitcnt lgkmcnt(0)
	v_mfma_f32_16x16x32_bf16 v[124:127], v[140:143], v[176:179], v[124:127]
	v_mfma_f32_16x16x32_bf16 v[116:119], v[152:155], v[176:179], v[116:119]
	v_mfma_f32_16x16x32_bf16 v[108:111], v[140:143], v[184:187], v[108:111]
	v_mfma_f32_16x16x32_bf16 v[100:103], v[152:155], v[184:187], v[100:103]
	v_mfma_f32_16x16x32_bf16 v[92:95], v[140:143], v[192:195], v[92:95]
	v_mfma_f32_16x16x32_bf16 v[84:87], v[152:155], v[192:195], v[84:87]
	v_mfma_f32_16x16x32_bf16 v[76:79], v[140:143], v[200:203], v[76:79]
	v_mfma_f32_16x16x32_bf16 v[68:71], v[152:155], v[200:203], v[68:71]
	v_mfma_f32_16x16x32_bf16 v[124:127], v[148:151], v[180:183], v[124:127]
	v_mfma_f32_16x16x32_bf16 v[116:119], v[156:159], v[180:183], v[116:119]
	v_mfma_f32_16x16x32_bf16 v[108:111], v[148:151], v[188:191], v[108:111]
	v_mfma_f32_16x16x32_bf16 v[100:103], v[156:159], v[188:191], v[100:103]
	v_mfma_f32_16x16x32_bf16 v[92:95], v[148:151], v[196:199], v[92:95]
	v_mfma_f32_16x16x32_bf16 v[84:87], v[156:159], v[196:199], v[84:87]
	v_mfma_f32_16x16x32_bf16 v[76:79], v[148:151], v[204:207], v[76:79]
	v_mfma_f32_16x16x32_bf16 v[68:71], v[156:159], v[204:207], v[68:71]
	v_mfma_f32_16x16x32_bf16 v[120:123], v[160:163], v[176:179], v[120:123]
	v_mfma_f32_16x16x32_bf16 v[112:115], v[168:171], v[176:179], v[112:115]
	v_mfma_f32_16x16x32_bf16 v[104:107], v[160:163], v[184:187], v[104:107]
	v_mfma_f32_16x16x32_bf16 v[96:99], v[168:171], v[184:187], v[96:99]
	v_mfma_f32_16x16x32_bf16 v[88:91], v[160:163], v[192:195], v[88:91]
	v_mfma_f32_16x16x32_bf16 v[80:83], v[168:171], v[192:195], v[80:83]
	v_mfma_f32_16x16x32_bf16 v[72:75], v[160:163], v[200:203], v[72:75]
	v_mfma_f32_16x16x32_bf16 v[64:67], v[168:171], v[200:203], v[64:67]
	v_mfma_f32_16x16x32_bf16 v[120:123], v[164:167], v[180:183], v[120:123]
	v_mfma_f32_16x16x32_bf16 v[112:115], v[172:175], v[180:183], v[112:115]
	v_mfma_f32_16x16x32_bf16 v[104:107], v[164:167], v[188:191], v[104:107]
	v_mfma_f32_16x16x32_bf16 v[96:99], v[172:175], v[188:191], v[96:99]
	v_mfma_f32_16x16x32_bf16 v[88:91], v[164:167], v[196:199], v[88:91]
	v_mfma_f32_16x16x32_bf16 v[80:83], v[172:175], v[196:199], v[80:83]
	v_mfma_f32_16x16x32_bf16 v[72:75], v[164:167], v[204:207], v[72:75]
	v_mfma_f32_16x16x32_bf16 v[64:67], v[172:175], v[204:207], v[64:67]
	s_barrier
; #define PG8_STAGE(bufoff, gbase, voff) do { _Pragma("unroll") for (int _i = 0; _i < 2; ++_i) \
;         __builtin_amdgcn_global_load_lds((const unsigned*)((const char*)(gbase) + (voff)[_i]), (PG8_LAS unsigned*)(lds + (bufoff) + ldsw + _i * 8192), 16, 0, 0); } while (0)
; #define PG8_LDA(dst, b, h) do { _Pragma("unroll") for (int m = 0; m < 4; ++m) _Pragma("unroll") for (int k = 0; k < 2; ++k) dst[m][k] = *(const PG8_LAS bf16x8*)(lds + PG8_SA(b, h) + aoff + m * 2048 + k * 1024); } while (0)
; #define PG8_LDB(dst, b, h) do { _Pragma("unroll") for (int n = 0; n < 2; ++n) _Pragma("unroll") for (int k = 0; k < 2; ++k) dst[n][k] = *(const PG8_LAS bf16x8*)(lds + PG8_SB(b, h) + boff + n * 2048 + k * 1024); } while (0)
; #define PG8_MMA(ai, bj, At, Bt) do { __builtin_amdgcn_s_setprio(1); _Pragma("unroll") for (int m = 0; m < 4; ++m) _Pragma("unroll") for (int n = 0; n < 2; ++n) _Pragma("unroll") for (int k = 0; k < 2; ++k) \
;         acc[ai][bj][m][n] = __builtin_amdgcn_mfma_f32_16x16x32_bf16(Bt[n][k], At[m][k], acc[ai][bj][m][n], 0, 0, 0); __builtin_amdgcn_s_setprio(0); } while (0)
; #define PG8_WAIT_V(n) asm volatile("s_waitcnt vmcnt(" #n ")" ::: "memory")
; #define PG8_WAIT_L(n) asm volatile("s_waitcnt lgkmcnt(" #n ")" ::: "memory")
; #define PG8_BAR __builtin_amdgcn_s_barrier()
; #define PG8_SCHED __builtin_amdgcn_sched_barrier(0)
; template <class Epi, class Sched, bool ALIGN_EPI = false, bool SP2 = false>
; __device__ __forceinline__ void gemm_phase(PG8_LAS unsigned char* lds, const Gemm g, const Sched& S, const Epi& E) {
;     ...
;             PG8_LDA(At, 0, 1); PG8_STAGE(PG8_SB(0, 0), b2, voffB); PG8_STAGE(PG8_SB(0, 1), b2 + hstep, voffB); PG8_STAGE(PG8_SA(0, 0), a2, voffA);
;             PG8_WAIT_V(8); PG8_WAIT_L(0); PG8_BAR; PG8_MMA(1, 0, At, B0); PG8_MMA(1, 1, At, B1); PG8_BAR; PG8_SCHED;
;             PG8_LDB(B0, 1, 0); PG8_LDB(B1, 1, 1); PG8_SCHED; PG8_LDA(At, 1, 0); PG8_STAGE(PG8_SA(0, 1), a2 + hstep, voffA);
;             PG8_WAIT_V(8); PG8_WAIT_L(0); PG8_BAR; PG8_MMA(0, 0, At, B0); PG8_MMA(0, 1, At, B1); PG8_BAR; PG8_SCHED;
	s_add_i32 s37, s49, s17
	v_lshl_add_u64 v[208:209], s[58:59], 0, v[128:129]
	s_mov_b32 m0, s37
	ds_read_b128 v[176:179], v147 offset:16384
	ds_read_b128 v[180:183], v147 offset:17408
	ds_read_b128 v[184:187], v147 offset:18432
	ds_read_b128 v[188:191], v147 offset:19456
	ds_read_b128 v[192:195], v147 offset:20480
	ds_read_b128 v[196:199], v147 offset:21504
	ds_read_b128 v[200:203], v147 offset:22528
	ds_read_b128 v[204:207], v147 offset:23552
	global_load_lds_dwordx4 v[208:209], off
	s_add_i32 m0, s37, 0x2000
	s_add_u32 s72, s58, 0x40000
	v_lshl_add_u64 v[210:211], s[58:59], 0, v[130:131]
	s_addc_u32 s73, s59, 0
	s_add_i32 s8, s8, s17
	global_load_lds_dwordx4 v[210:211], off
	v_lshl_add_u64 v[214:215], s[72:73], 0, v[128:129]
	s_mov_b32 m0, s8
	v_lshl_add_u64 v[222:223], s[64:65], 0, v[132:133]
	global_load_lds_dwordx4 v[214:215], off
	v_lshl_add_u64 v[214:215], s[72:73], 0, v[130:131]
	s_add_i32 m0, s8, 0x2000
	s_nop 0
	global_load_lds_dwordx4 v[214:215], off
	v_lshl_add_u64 v[214:215], s[64:65], 0, v[134:135]
	s_mov_b32 m0, s18
	s_nop 0
	global_load_lds_dwordx4 v[214:215], off
	s_mov_b32 m0, s19
	s_nop 0
	global_load_lds_dwordx4 v[222:223], off
	s_waitcnt vmcnt(8)
	s_waitcnt lgkmcnt(0)
	s_barrier
	s_waitcnt lgkmcnt(0)
	v_mfma_f32_16x16x32_bf16 v[60:63], v[140:143], v[176:179], v[60:63]
	v_mfma_f32_16x16x32_bf16 v[52:55], v[152:155], v[176:179], v[52:55]
	v_mfma_f32_16x16x32_bf16 v[44:47], v[140:143], v[184:187], v[44:47]
	v_mfma_f32_16x16x32_bf16 v[36:39], v[152:155], v[184:187], v[36:39]
	v_mfma_f32_16x16x32_bf16 v[28:31], v[140:143], v[192:195], v[28:31]
	v_mfma_f32_16x16x32_bf16 v[20:23], v[152:155], v[192:195], v[20:23]
	v_mfma_f32_16x16x32_bf16 v[12:15], v[140:143], v[200:203], v[12:15]
	v_mfma_f32_16x16x32_bf16 v[4:7], v[152:155], v[200:203], v[4:7]
	v_mfma_f32_16x16x32_bf16 v[60:63], v[148:151], v[180:183], v[60:63]
	v_mfma_f32_16x16x32_bf16 v[52:55], v[156:159], v[180:183], v[52:55]
	v_mfma_f32_16x16x32_bf16 v[44:47], v[148:151], v[188:191], v[44:47]
	v_mfma_f32_16x16x32_bf16 v[36:39], v[156:159], v[188:191], v[36:39]
	v_mfma_f32_16x16x32_bf16 v[28:31], v[148:151], v[196:199], v[28:31]
	v_mfma_f32_16x16x32_bf16 v[20:23], v[156:159], v[196:199], v[20:23]
	v_mfma_f32_16x16x32_bf16 v[12:15], v[148:151], v[204:207], v[12:15]
	v_mfma_f32_16x16x32_bf16 v[4:7], v[156:159], v[204:207], v[4:7]
	v_mfma_f32_16x16x32_bf16 v[56:59], v[160:163], v[176:179], v[56:59]
	v_mfma_f32_16x16x32_bf16 v[48:51], v[168:171], v[176:179], v[48:51]
	v_mfma_f32_16x16x32_bf16 v[40:43], v[160:163], v[184:187], v[40:43]
	v_mfma_f32_16x16x32_bf16 v[32:35], v[168:171], v[184:187], v[32:35]
	v_mfma_f32_16x16x32_bf16 v[24:27], v[160:163], v[192:195], v[24:27]
	v_mfma_f32_16x16x32_bf16 v[16:19], v[168:171], v[192:195], v[16:19]
	v_mfma_f32_16x16x32_bf16 v[8:11], v[160:163], v[200:203], v[8:11]
	v_mfma_f32_16x16x32_bf16 v[0:3], v[168:171], v[200:203], v[0:3]
	v_mfma_f32_16x16x32_bf16 v[56:59], v[164:167], v[180:183], v[56:59]
	v_mfma_f32_16x16x32_bf16 v[48:51], v[172:175], v[180:183], v[48:51]
	v_mfma_f32_16x16x32_bf16 v[40:43], v[164:167], v[188:191], v[40:43]
	v_mfma_f32_16x16x32_bf16 v[32:35], v[172:175], v[188:191], v[32:35]
	v_mfma_f32_16x16x32_bf16 v[24:27], v[164:167], v[196:199], v[24:27]
	v_mfma_f32_16x16x32_bf16 v[16:19], v[172:175], v[196:199], v[16:19]
	v_mfma_f32_16x16x32_bf16 v[8:11], v[164:167], v[204:207], v[8:11]
	v_mfma_f32_16x16x32_bf16 v[0:3], v[172:175], v[204:207], v[0:3]
	s_barrier
	s_add_i32 s8, 0, 0x18000
	s_add_i32 s37, 0, 0x1c000
	v_add_u32_e32 v156, s8, v145
	v_add_u32_e32 v172, s37, v145
	ds_read_b128 v[140:143], v156
	ds_read_b128 v[148:151], v156 offset:1024
	ds_read_b128 v[152:155], v156 offset:2048
	ds_read_b128 v[156:159], v156 offset:3072
	ds_read_b128 v[160:163], v172
	ds_read_b128 v[164:167], v172 offset:1024
	ds_read_b128 v[168:171], v172 offset:2048
	ds_read_b128 v[172:175], v172 offset:3072
	s_add_u32 s64, s64, 0x40000
	s_addc_u32 s65, s65, 0
	s_mov_b32 m0, s20
	v_lshl_add_u64 v[228:229], s[64:65], 0, v[134:135]
	ds_read_b128 v[176:179], v147 offset:32768
	ds_read_b128 v[180:183], v147 offset:33792
	ds_read_b128 v[184:187], v147 offset:34816
	ds_read_b128 v[188:191], v147 offset:35840
	ds_read_b128 v[192:195], v147 offset:36864
	ds_read_b128 v[196:199], v147 offset:37888
	ds_read_b128 v[200:203], v147 offset:38912
	ds_read_b128 v[204:207], v147 offset:39936
	global_load_lds_dwordx4 v[228:229], off
	v_lshl_add_u64 v[228:229], s[64:65], 0, v[132:133]
	s_mov_b32 m0, s21
	s_nop 0
	global_load_lds_dwordx4 v[228:229], off
	s_waitcnt vmcnt(8)
	s_waitcnt lgkmcnt(0)
	s_barrier
; #define PG8_STAGE(bufoff, gbase, voff) do { _Pragma("unroll") for (int _i = 0; _i < 2; ++_i) \
;         __builtin_amdgcn_global_load_lds((const unsigned*)((const char*)(gbase) + (voff)[_i]), (PG8_LAS unsigned*)(lds + (bufoff) + ldsw + _i * 8192), 16, 0, 0); } while (0)
; #define PG8_LDA(dst, b, h) do { _Pragma("unroll") for (int m = 0; m < 4; ++m) _Pragma("unroll") for (int k = 0; k < 2; ++k) dst[m][k] = *(const PG8_LAS bf16x8*)(lds + PG8_SA(b, h) + aoff + m * 2048 + k * 1024); } while (0)
; #define PG8_MMA(ai, bj, At, Bt) do { __builtin_amdgcn_s_setprio(1); _Pragma("unroll") for (int m = 0; m < 4; ++m) _Pragma("unroll") for (int n = 0; n < 2; ++n) _Pragma("unroll") for (int k = 0; k < 2; ++k) \
;         acc[ai][bj][m][n] = __builtin_amdgcn_mfma_f32_16x16x32_bf16(Bt[n][k], At[m][k], acc[ai][bj][m][n], 0, 0, 0); __builtin_amdgcn_s_setprio(0); } while (0)
; #define PG8_WAIT_V(n) asm volatile("s_waitcnt vmcnt(" #n ")" ::: "memory")
; #define PG8_WAIT_L(n) asm volatile("s_waitcnt lgkmcnt(" #n ")" ::: "memory")
; #define PG8_BAR __builtin_amdgcn_s_barrier()
; #define PG8_SCHED __builtin_amdgcn_sched_barrier(0)
; template <class Epi, class Sched, bool ALIGN_EPI = false, bool SP2 = false>
; __device__ __forceinline__ void gemm_phase(PG8_LAS unsigned char* lds, const Gemm g, const Sched& S, const Epi& E) {
;     ...
;             PG8_WAIT_V(8); PG8_WAIT_L(0); PG8_BAR; PG8_MMA(0, 0, At, B0); PG8_MMA(0, 1, At, B1); PG8_BAR; PG8_SCHED;
;             PG8_LDA(At, 1, 1); PG8_STAGE(PG8_SB(1, 0), b3, voffB); PG8_STAGE(PG8_SB(1, 1), b3 + hstep, voffB); PG8_STAGE(PG8_SA(1, 0), a3, voffA);
;             PG8_WAIT_V(8); PG8_WAIT_L(0); PG8_BAR; PG8_MMA(1, 0, At, B0); PG8_MMA(1, 1, At, B1); PG8_BAR; PG8_SCHED;
;     ...
;         if constexpr (ALIGN_EPI) { if (wr == 0) PG8_BAR; }
	s_waitcnt lgkmcnt(0)
	v_mfma_f32_16x16x32_bf16 v[124:127], v[140:143], v[176:179], v[124:127]
	v_mfma_f32_16x16x32_bf16 v[116:119], v[152:155], v[176:179], v[116:119]
	v_mfma_f32_16x16x32_bf16 v[108:111], v[140:143], v[184:187], v[108:111]
	v_mfma_f32_16x16x32_bf16 v[100:103], v[152:155], v[184:187], v[100:103]
	v_mfma_f32_16x16x32_bf16 v[92:95], v[140:143], v[192:195], v[92:95]
	v_mfma_f32_16x16x32_bf16 v[84:87], v[152:155], v[192:195], v[84:87]
	v_mfma_f32_16x16x32_bf16 v[76:79], v[140:143], v[200:203], v[76:79]
	v_mfma_f32_16x16x32_bf16 v[68:71], v[152:155], v[200:203], v[68:71]
	v_mfma_f32_16x16x32_bf16 v[124:127], v[148:151], v[180:183], v[124:127]
	v_mfma_f32_16x16x32_bf16 v[116:119], v[156:159], v[180:183], v[116:119]
	v_mfma_f32_16x16x32_bf16 v[108:111], v[148:151], v[188:191], v[108:111]
	v_mfma_f32_16x16x32_bf16 v[100:103], v[156:159], v[188:191], v[100:103]
	v_mfma_f32_16x16x32_bf16 v[92:95], v[148:151], v[196:199], v[92:95]
	v_mfma_f32_16x16x32_bf16 v[84:87], v[156:159], v[196:199], v[84:87]
	v_mfma_f32_16x16x32_bf16 v[76:79], v[148:151], v[204:207], v[76:79]
	v_mfma_f32_16x16x32_bf16 v[68:71], v[156:159], v[204:207], v[68:71]
	v_mfma_f32_16x16x32_bf16 v[120:123], v[160:163], v[176:179], v[120:123]
	v_mfma_f32_16x16x32_bf16 v[112:115], v[168:171], v[176:179], v[112:115]
	v_mfma_f32_16x16x32_bf16 v[104:107], v[160:163], v[184:187], v[104:107]
	v_mfma_f32_16x16x32_bf16 v[96:99], v[168:171], v[184:187], v[96:99]
	v_mfma_f32_16x16x32_bf16 v[88:91], v[160:163], v[192:195], v[88:91]
	v_mfma_f32_16x16x32_bf16 v[80:83], v[168:171], v[192:195], v[80:83]
	v_mfma_f32_16x16x32_bf16 v[72:75], v[160:163], v[200:203], v[72:75]
	v_mfma_f32_16x16x32_bf16 v[64:67], v[168:171], v[200:203], v[64:67]
	v_mfma_f32_16x16x32_bf16 v[120:123], v[164:167], v[180:183], v[120:123]
	v_mfma_f32_16x16x32_bf16 v[112:115], v[172:175], v[180:183], v[112:115]
	v_mfma_f32_16x16x32_bf16 v[104:107], v[164:167], v[188:191], v[104:107]
	v_mfma_f32_16x16x32_bf16 v[96:99], v[172:175], v[188:191], v[96:99]
	v_mfma_f32_16x16x32_bf16 v[88:91], v[164:167], v[196:199], v[88:91]
	v_mfma_f32_16x16x32_bf16 v[80:83], v[172:175], v[196:199], v[80:83]
	v_mfma_f32_16x16x32_bf16 v[72:75], v[164:167], v[204:207], v[72:75]
	v_mfma_f32_16x16x32_bf16 v[64:67], v[172:175], v[204:207], v[64:67]
	s_barrier
	s_add_i32 s8, s8, s17
	v_lshl_add_u64 v[208:209], v[208:209], 0, s[90:91]
	s_mov_b32 m0, s8
	ds_read_b128 v[176:179], v147 offset:49152
	ds_read_b128 v[180:183], v147 offset:50176
	ds_read_b128 v[184:187], v147 offset:51200
	ds_read_b128 v[188:191], v147 offset:52224
	ds_read_b128 v[192:195], v147 offset:53248
	ds_read_b128 v[196:199], v147 offset:54272
	ds_read_b128 v[200:203], v147 offset:55296
	ds_read_b128 v[204:207], v147 offset:56320
	global_load_lds_dwordx4 v[208:209], off
	s_add_i32 m0, s8, 0x2000
	s_add_u32 s58, s58, 0x40080
	v_lshl_add_u64 v[208:209], v[210:211], 0, s[90:91]
	s_addc_u32 s59, s59, 0
	s_add_i32 s8, s37, s17
	global_load_lds_dwordx4 v[208:209], off
	v_lshl_add_u64 v[208:209], s[58:59], 0, v[128:129]
	s_mov_b32 m0, s8
	s_nop 0
	global_load_lds_dwordx4 v[208:209], off
	v_lshl_add_u64 v[208:209], s[58:59], 0, v[130:131]
	s_add_i32 m0, s8, 0x2000
	s_nop 0
	global_load_lds_dwordx4 v[208:209], off
	v_lshl_add_u64 v[208:209], v[214:215], 0, s[90:91]
	s_mov_b32 m0, s22
	s_nop 0
	global_load_lds_dwordx4 v[208:209], off
	v_lshl_add_u64 v[208:209], v[222:223], 0, s[90:91]
	s_mov_b32 m0, s23
	s_nop 0
	global_load_lds_dwordx4 v[208:209], off
	s_waitcnt vmcnt(8)
	s_waitcnt lgkmcnt(0)
	s_barrier
	s_waitcnt lgkmcnt(0)
	v_mfma_f32_16x16x32_bf16 v[60:63], v[140:143], v[176:179], v[60:63]
	v_mfma_f32_16x16x32_bf16 v[52:55], v[152:155], v[176:179], v[52:55]
	v_mfma_f32_16x16x32_bf16 v[44:47], v[140:143], v[184:187], v[44:47]
	v_mfma_f32_16x16x32_bf16 v[36:39], v[152:155], v[184:187], v[36:39]
	v_mfma_f32_16x16x32_bf16 v[28:31], v[140:143], v[192:195], v[28:31]
	v_mfma_f32_16x16x32_bf16 v[20:23], v[152:155], v[192:195], v[20:23]
	v_mfma_f32_16x16x32_bf16 v[12:15], v[140:143], v[200:203], v[12:15]
	v_mfma_f32_16x16x32_bf16 v[4:7], v[152:155], v[200:203], v[4:7]
	v_mfma_f32_16x16x32_bf16 v[60:63], v[148:151], v[180:183], v[60:63]
	v_mfma_f32_16x16x32_bf16 v[52:55], v[156:159], v[180:183], v[52:55]
	v_mfma_f32_16x16x32_bf16 v[44:47], v[148:151], v[188:191], v[44:47]
	v_mfma_f32_16x16x32_bf16 v[36:39], v[156:159], v[188:191], v[36:39]
	v_mfma_f32_16x16x32_bf16 v[28:31], v[148:151], v[196:199], v[28:31]
	v_mfma_f32_16x16x32_bf16 v[20:23], v[156:159], v[196:199], v[20:23]
	v_mfma_f32_16x16x32_bf16 v[12:15], v[148:151], v[204:207], v[12:15]
	v_mfma_f32_16x16x32_bf16 v[4:7], v[156:159], v[204:207], v[4:7]
	v_mfma_f32_16x16x32_bf16 v[56:59], v[160:163], v[176:179], v[56:59]
	v_mfma_f32_16x16x32_bf16 v[48:51], v[168:171], v[176:179], v[48:51]
	v_mfma_f32_16x16x32_bf16 v[40:43], v[160:163], v[184:187], v[40:43]
	v_mfma_f32_16x16x32_bf16 v[32:35], v[168:171], v[184:187], v[32:35]
	v_mfma_f32_16x16x32_bf16 v[24:27], v[160:163], v[192:195], v[24:27]
	v_mfma_f32_16x16x32_bf16 v[16:19], v[168:171], v[192:195], v[16:19]
	v_mfma_f32_16x16x32_bf16 v[8:11], v[160:163], v[200:203], v[8:11]
	v_mfma_f32_16x16x32_bf16 v[0:3], v[168:171], v[200:203], v[0:3]
	v_mfma_f32_16x16x32_bf16 v[56:59], v[164:167], v[180:183], v[56:59]
	v_mfma_f32_16x16x32_bf16 v[48:51], v[172:175], v[180:183], v[48:51]
	v_mfma_f32_16x16x32_bf16 v[40:43], v[164:167], v[188:191], v[40:43]
	v_mfma_f32_16x16x32_bf16 v[32:35], v[172:175], v[188:191], v[32:35]
	v_mfma_f32_16x16x32_bf16 v[24:27], v[164:167], v[196:199], v[24:27]
	v_mfma_f32_16x16x32_bf16 v[16:19], v[172:175], v[196:199], v[16:19]
	v_mfma_f32_16x16x32_bf16 v[8:11], v[164:167], v[204:207], v[8:11]
	v_mfma_f32_16x16x32_bf16 v[0:3], v[172:175], v[204:207], v[0:3]
	s_barrier
	s_add_i32 s36, s36, 2
	s_add_u32 s66, s66, 0x100
	s_addc_u32 s67, s67, 0
	s_add_u32 s34, s34, 0x100
	s_addc_u32 s35, s35, 0
	s_cmp_gt_u32 s36, 13
	s_cbranch_scc0 .LBB0_813
	s_setprio 0
	s_and_b64 vcc, exec, s[46:47]
	s_cbranch_vccz .LBB0_816
	s_barrier

; #define PG8_STAGE(bufoff, gbase, voff) do { _Pragma("unroll") for (int _i = 0; _i < 2; ++_i) \
;         __builtin_amdgcn_global_load_lds((const unsigned*)((const char*)(gbase) + (voff)[_i]), (PG8_LAS unsigned*)(lds + (bufoff) + ldsw + _i * 8192), 16, 0, 0); } while (0)
; #define PG8_LDA(dst, b, h) do { _Pragma("unroll") for (int m = 0; m < 4; ++m) _Pragma("unroll") for (int k = 0; k < 2; ++k) dst[m][k] = *(const PG8_LAS bf16x8*)(lds + PG8_SA(b, h) + aoff + m * 2048 + k * 1024); } while (0)
; #define PG8_LDB(dst, b, h) do { _Pragma("unroll") for (int n = 0; n < 2; ++n) _Pragma("unroll") for (int k = 0; k < 2; ++k) dst[n][k] = *(const PG8_LAS bf16x8*)(lds + PG8_SB(b, h) + boff + n * 2048 + k * 1024); } while (0)
; #define PG8_WAIT_V(n) asm volatile("s_waitcnt vmcnt(" #n ")" ::: "memory")
; #define PG8_WAIT_L(n) asm volatile("s_waitcnt lgkmcnt(" #n ")" ::: "memory")
; #define PG8_BAR __builtin_amdgcn_s_barrier()
; template <class Epi, class Sched, bool ALIGN_EPI = false, bool SP2 = false>
; __device__ __forceinline__ void gemm_phase(PG8_LAS unsigned char* lds, const Gemm g, const Sched& S, const Epi& E) {
;     ...
;     for (;;) {
;         const bool has_next = S.next(ui + 1, nxt);
;         const char* nA = has_next ? (const char*)g.A + (size_t)nxt.pm * tstep : cA; const char* nB = has_next ? (const char*)g.Bt + (size_t)nxt.pn * tstep : cB;
;         for (int t = 0; t < nt; t += 2) {
;             const bool last = (t == nt - 2);
;             const char* a1 = cA + (size_t)(t + 1) * kstep;
;             const char* a2 = last ? nA : cA + (size_t)(t + 2) * kstep; const char* b2 = last ? nB : cB + (size_t)(t + 2) * kstep;
;             const char* a3 = a2 + kstep; const char* b3 = b2 + kstep;
;             if (last && has_next) S.a_ready(nxt);
;             if constexpr (SP2) {
;             PG8_LDB(B0, 0, 0); PG8_LDB(B1, 0, 1); PG8_SCHED; PG8_LDA(At, 0, 0); PG8_STAGE(PG8_SA(1, 1), a1 + hstep, voffA);
;             PG8_WAIT_V(8); PG8_WAIT_L(0); PG8_BAR; PG8_MMA(0, 0, At, B0); PG8_MMA(0, 1, At, B1); PG8_BAR; PG8_SCHED;
;     ...
; #pragma unroll
;         for (int a = 0; a < 2; ++a)
; #pragma unroll
;             for (int b = 0; b < 2; ++b)
; #pragma unroll
;                 for (int m = 0; m < 4; ++m)
; #pragma unroll
;                     for (int n = 0; n < 2; ++n) acc[a][b][m][n] = (f32x4){0.f, 0.f, 0.f, 0.f};
;         cur = nxt; cA = nA; cB = nB; ++ui;
.LBB0_956:
	s_add_u32 s36, s46, 0x100
	v_mov_b64_e32 v[0:1], 0
	s_addc_u32 s37, s47, 0
	s_mov_b32 s70, -2
	v_mov_b64_e32 v[2:3], 0
	v_mov_b64_e32 v[4:5], 0
	v_mov_b64_e32 v[6:7], 0
	v_mov_b64_e32 v[16:17], 0
	v_mov_b64_e32 v[18:19], 0
	v_mov_b64_e32 v[20:21], 0
	v_mov_b64_e32 v[22:23], 0
	v_mov_b64_e32 v[32:33], 0
	v_mov_b64_e32 v[34:35], 0
	v_mov_b64_e32 v[36:37], 0
	v_mov_b64_e32 v[38:39], 0
	v_mov_b64_e32 v[48:49], 0
	v_mov_b64_e32 v[50:51], 0
	v_mov_b64_e32 v[52:53], 0
	v_mov_b64_e32 v[54:55], 0
	v_mov_b64_e32 v[8:9], 0
	v_mov_b64_e32 v[10:11], 0
	v_mov_b64_e32 v[12:13], 0
	v_mov_b64_e32 v[14:15], 0
	v_mov_b64_e32 v[24:25], 0
	v_mov_b64_e32 v[26:27], 0
	v_mov_b64_e32 v[28:29], 0
	v_mov_b64_e32 v[30:31], 0
	v_mov_b64_e32 v[40:41], 0
	v_mov_b64_e32 v[42:43], 0
	v_mov_b64_e32 v[44:45], 0
	v_mov_b64_e32 v[46:47], 0
	v_mov_b64_e32 v[56:57], 0
	v_mov_b64_e32 v[58:59], 0
	v_mov_b64_e32 v[60:61], 0
	v_mov_b64_e32 v[62:63], 0
	v_mov_b64_e32 v[64:65], 0
	v_mov_b64_e32 v[66:67], 0
	v_mov_b64_e32 v[68:69], 0
	v_mov_b64_e32 v[70:71], 0
	v_mov_b64_e32 v[80:81], 0
	v_mov_b64_e32 v[82:83], 0
	v_mov_b64_e32 v[84:85], 0
	v_mov_b64_e32 v[86:87], 0
	v_mov_b64_e32 v[96:97], 0
	v_mov_b64_e32 v[98:99], 0
	v_mov_b64_e32 v[100:101], 0
	v_mov_b64_e32 v[102:103], 0
	v_mov_b64_e32 v[112:113], 0
	v_mov_b64_e32 v[114:115], 0
	v_mov_b64_e32 v[116:117], 0
	v_mov_b64_e32 v[118:119], 0
	v_mov_b64_e32 v[72:73], 0
	v_mov_b64_e32 v[74:75], 0
	v_mov_b64_e32 v[76:77], 0
	v_mov_b64_e32 v[78:79], 0
	v_mov_b64_e32 v[88:89], 0
	v_mov_b64_e32 v[90:91], 0
	v_mov_b64_e32 v[92:93], 0
	v_mov_b64_e32 v[94:95], 0
	v_mov_b64_e32 v[104:105], 0
	v_mov_b64_e32 v[106:107], 0
	v_mov_b64_e32 v[108:109], 0
	v_mov_b64_e32 v[110:111], 0
	v_mov_b64_e32 v[120:121], 0
	v_mov_b64_e32 v[122:123], 0
	v_mov_b64_e32 v[124:125], 0
	v_mov_b64_e32 v[126:127], 0
	s_and_b64 s[98:99], exec, s[58:59]
	s_cbranch_scc1 .Lsp_4
	s_setprio 1
.Lsp_4:
.LBB0_957:
	s_add_u32 s44, s96, 0x100
	s_addc_u32 s45, s97, 0
	s_add_i32 s8, 0, 0x10000
	s_cmp_eq_u32 s70, 40
	s_cselect_b32 s65, s67, s45
	s_cselect_b32 s64, s66, s44
	s_cselect_b32 s47, s73, s37
	s_cselect_b32 s46, s72, s36
	s_add_i32 s88, 0, 0x14000
	v_add_u32_e32 v142, s8, v185
	v_add_u32_e32 v168, s88, v185
	ds_read_b128 v[130:133], v142
	ds_read_b128 v[134:137], v142 offset:1024
	ds_read_b128 v[138:141], v142 offset:2048
	ds_read_b128 v[142:145], v142 offset:3072
	ds_read_b128 v[156:159], v168
	ds_read_b128 v[160:163], v168 offset:1024
	ds_read_b128 v[164:167], v168 offset:2048
	ds_read_b128 v[168:171], v168 offset:3072
	v_lshl_add_u64 v[208:209], s[96:97], 0, v[152:153]
	s_add_i32 m0, s15, 0xc000
	ds_read_b128 v[172:175], v191
	ds_read_b128 v[176:179], v191 offset:1024
	ds_read_b128 v[180:183], v191 offset:2048
	ds_read_b128 v[186:189], v191 offset:3072
	ds_read_b128 v[192:195], v191 offset:4096
	ds_read_b128 v[196:199], v191 offset:5120
	ds_read_b128 v[200:203], v191 offset:6144
	ds_read_b128 v[204:207], v191 offset:7168
	global_load_lds_dwordx4 v[208:209], off
	v_lshl_add_u64 v[208:209], s[96:97], 0, v[154:155]
	s_add_i32 m0, s15, 0xe000
	s_nop 0
	global_load_lds_dwordx4 v[208:209], off
	s_waitcnt vmcnt(8)
	s_waitcnt lgkmcnt(0)
	s_barrier
	s_waitcnt lgkmcnt(0)
	v_mfma_f32_16x16x32_bf16 v[124:127], v[130:133], v[172:175], v[124:127]
	v_mfma_f32_16x16x32_bf16 v[120:123], v[138:141], v[172:175], v[120:123]
	v_mfma_f32_16x16x32_bf16 v[108:111], v[130:133], v[180:183], v[108:111]
	v_mfma_f32_16x16x32_bf16 v[104:107], v[138:141], v[180:183], v[104:107]
	v_mfma_f32_16x16x32_bf16 v[92:95], v[130:133], v[192:195], v[92:95]
	v_mfma_f32_16x16x32_bf16 v[88:91], v[138:141], v[192:195], v[88:91]
	v_mfma_f32_16x16x32_bf16 v[76:79], v[130:133], v[200:203], v[76:79]
	v_mfma_f32_16x16x32_bf16 v[72:75], v[138:141], v[200:203], v[72:75]
	v_mfma_f32_16x16x32_bf16 v[124:127], v[134:137], v[176:179], v[124:127]
	v_mfma_f32_16x16x32_bf16 v[120:123], v[142:145], v[176:179], v[120:123]
	v_mfma_f32_16x16x32_bf16 v[108:111], v[134:137], v[186:189], v[108:111]
	v_mfma_f32_16x16x32_bf16 v[104:107], v[142:145], v[186:189], v[104:107]
	v_mfma_f32_16x16x32_bf16 v[92:95], v[134:137], v[196:199], v[92:95]
	v_mfma_f32_16x16x32_bf16 v[88:91], v[142:145], v[196:199], v[88:91]
	v_mfma_f32_16x16x32_bf16 v[76:79], v[134:137], v[204:207], v[76:79]
	v_mfma_f32_16x16x32_bf16 v[72:75], v[142:145], v[204:207], v[72:75]
	v_mfma_f32_16x16x32_bf16 v[116:119], v[156:159], v[172:175], v[116:119]
	v_mfma_f32_16x16x32_bf16 v[112:115], v[164:167], v[172:175], v[112:115]
	v_mfma_f32_16x16x32_bf16 v[100:103], v[156:159], v[180:183], v[100:103]
	v_mfma_f32_16x16x32_bf16 v[96:99], v[164:167], v[180:183], v[96:99]
	v_mfma_f32_16x16x32_bf16 v[84:87], v[156:159], v[192:195], v[84:87]
	v_mfma_f32_16x16x32_bf16 v[80:83], v[164:167], v[192:195], v[80:83]
	v_mfma_f32_16x16x32_bf16 v[68:71], v[156:159], v[200:203], v[68:71]
	v_mfma_f32_16x16x32_bf16 v[64:67], v[164:167], v[200:203], v[64:67]
	v_mfma_f32_16x16x32_bf16 v[116:119], v[160:163], v[176:179], v[116:119]
	v_mfma_f32_16x16x32_bf16 v[112:115], v[168:171], v[176:179], v[112:115]
	v_mfma_f32_16x16x32_bf16 v[100:103], v[160:163], v[186:189], v[100:103]
	v_mfma_f32_16x16x32_bf16 v[96:99], v[168:171], v[186:189], v[96:99]
	v_mfma_f32_16x16x32_bf16 v[84:87], v[160:163], v[196:199], v[84:87]
	v_mfma_f32_16x16x32_bf16 v[80:83], v[168:171], v[196:199], v[80:83]
	v_mfma_f32_16x16x32_bf16 v[68:71], v[160:163], v[204:207], v[68:71]
	v_mfma_f32_16x16x32_bf16 v[64:67], v[168:171], v[204:207], v[64:67]
	s_barrier
; #define PG8_STAGE(bufoff, gbase, voff) do { _Pragma("unroll") for (int _i = 0; _i < 2; ++_i) \
;         __builtin_amdgcn_global_load_lds((const unsigned*)((const char*)(gbase) + (voff)[_i]), (PG8_LAS unsigned*)(lds + (bufoff) + ldsw + _i * 8192), 16, 0, 0); } while (0)
; #define PG8_LDA(dst, b, h) do { _Pragma("unroll") for (int m = 0; m < 4; ++m) _Pragma("unroll") for (int k = 0; k < 2; ++k) dst[m][k] = *(const PG8_LAS bf16x8*)(lds + PG8_SA(b, h) + aoff + m * 2048 + k * 1024); } while (0)
; #define PG8_LDB(dst, b, h) do { _Pragma("unroll") for (int n = 0; n < 2; ++n) _Pragma("unroll") for (int k = 0; k < 2; ++k) dst[n][k] = *(const PG8_LAS bf16x8*)(lds + PG8_SB(b, h) + boff + n * 2048 + k * 1024); } while (0)
; #define PG8_MMA(ai, bj, At, Bt) do { __builtin_amdgcn_s_setprio(1); _Pragma("unroll") for (int m = 0; m < 4; ++m) _Pragma("unroll") for (int n = 0; n < 2; ++n) _Pragma("unroll") for (int k = 0; k < 2; ++k) \
;         acc[ai][bj][m][n] = __builtin_amdgcn_mfma_f32_16x16x32_bf16(Bt[n][k], At[m][k], acc[ai][bj][m][n], 0, 0, 0); __builtin_amdgcn_s_setprio(0); } while (0)
; #define PG8_WAIT_V(n) asm volatile("s_waitcnt vmcnt(" #n ")" ::: "memory")
; #define PG8_WAIT_L(n) asm volatile("s_waitcnt lgkmcnt(" #n ")" ::: "memory")
; #define PG8_BAR __builtin_amdgcn_s_barrier()
; #define PG8_SCHED __builtin_amdgcn_sched_barrier(0)
; template <class Epi, class Sched, bool ALIGN_EPI = false, bool SP2 = false>
; __device__ __forceinline__ void gemm_phase(PG8_LAS unsigned char* lds, const Gemm g, const Sched& S, const Epi& E) {
;     ...
;             PG8_LDA(At, 0, 1); PG8_STAGE(PG8_SB(0, 0), b2, voffB); PG8_STAGE(PG8_SB(0, 1), b2 + hstep, voffB); PG8_STAGE(PG8_SA(0, 0), a2, voffA);
;             PG8_WAIT_V(8); PG8_WAIT_L(0); PG8_BAR; PG8_MMA(1, 0, At, B0); PG8_MMA(1, 1, At, B1); PG8_BAR; PG8_SCHED;
;             PG8_LDB(B0, 1, 0); PG8_LDB(B1, 1, 1); PG8_SCHED; PG8_LDA(At, 1, 0); PG8_STAGE(PG8_SA(0, 1), a2 + hstep, voffA);
;             PG8_WAIT_V(8); PG8_WAIT_L(0); PG8_BAR; PG8_MMA(0, 0, At, B0); PG8_MMA(0, 1, At, B1); PG8_BAR; PG8_SCHED;
	s_add_i32 s8, s8, s14
	v_lshl_add_u64 v[208:209], s[46:47], 0, v[128:129]
	s_mov_b32 m0, s8
	ds_read_b128 v[172:175], v191 offset:16384
	ds_read_b128 v[176:179], v191 offset:17408
	ds_read_b128 v[180:183], v191 offset:18432
	ds_read_b128 v[186:189], v191 offset:19456
	ds_read_b128 v[192:195], v191 offset:20480
	ds_read_b128 v[196:199], v191 offset:21504
	ds_read_b128 v[200:203], v191 offset:22528
	ds_read_b128 v[204:207], v191 offset:23552
	global_load_lds_dwordx4 v[208:209], off
	s_add_i32 m0, s8, 0x2000
	s_add_u32 s84, s46, 0xb0000
	v_lshl_add_u64 v[210:211], s[46:47], 0, v[146:147]
	s_addc_u32 s85, s47, 0
	s_add_i32 s8, s88, s14
	global_load_lds_dwordx4 v[210:211], off
	v_lshl_add_u64 v[214:215], s[84:85], 0, v[128:129]
	s_mov_b32 m0, s8
	v_lshl_add_u64 v[222:223], s[64:65], 0, v[148:149]
	global_load_lds_dwordx4 v[214:215], off
	v_lshl_add_u64 v[214:215], s[84:85], 0, v[146:147]
	s_add_i32 m0, s8, 0x2000
	s_nop 0
	global_load_lds_dwordx4 v[214:215], off
	v_lshl_add_u64 v[214:215], s[64:65], 0, v[150:151]
	s_mov_b32 m0, s15
	s_nop 0
	global_load_lds_dwordx4 v[214:215], off
	s_mov_b32 m0, s18
	s_nop 0
	global_load_lds_dwordx4 v[222:223], off
	s_waitcnt vmcnt(8)
	s_waitcnt lgkmcnt(0)
	s_barrier
	s_waitcnt lgkmcnt(0)
	v_mfma_f32_16x16x32_bf16 v[60:63], v[130:133], v[172:175], v[60:63]
	v_mfma_f32_16x16x32_bf16 v[56:59], v[138:141], v[172:175], v[56:59]
	v_mfma_f32_16x16x32_bf16 v[44:47], v[130:133], v[180:183], v[44:47]
	v_mfma_f32_16x16x32_bf16 v[40:43], v[138:141], v[180:183], v[40:43]
	v_mfma_f32_16x16x32_bf16 v[28:31], v[130:133], v[192:195], v[28:31]
	v_mfma_f32_16x16x32_bf16 v[24:27], v[138:141], v[192:195], v[24:27]
	v_mfma_f32_16x16x32_bf16 v[12:15], v[130:133], v[200:203], v[12:15]
	v_mfma_f32_16x16x32_bf16 v[8:11], v[138:141], v[200:203], v[8:11]
	v_mfma_f32_16x16x32_bf16 v[60:63], v[134:137], v[176:179], v[60:63]
	v_mfma_f32_16x16x32_bf16 v[56:59], v[142:145], v[176:179], v[56:59]
	v_mfma_f32_16x16x32_bf16 v[44:47], v[134:137], v[186:189], v[44:47]
	v_mfma_f32_16x16x32_bf16 v[40:43], v[142:145], v[186:189], v[40:43]
	v_mfma_f32_16x16x32_bf16 v[28:31], v[134:137], v[196:199], v[28:31]
	v_mfma_f32_16x16x32_bf16 v[24:27], v[142:145], v[196:199], v[24:27]
	v_mfma_f32_16x16x32_bf16 v[12:15], v[134:137], v[204:207], v[12:15]
	v_mfma_f32_16x16x32_bf16 v[8:11], v[142:145], v[204:207], v[8:11]
	v_mfma_f32_16x16x32_bf16 v[52:55], v[156:159], v[172:175], v[52:55]
	v_mfma_f32_16x16x32_bf16 v[48:51], v[164:167], v[172:175], v[48:51]
	v_mfma_f32_16x16x32_bf16 v[36:39], v[156:159], v[180:183], v[36:39]
	v_mfma_f32_16x16x32_bf16 v[32:35], v[164:167], v[180:183], v[32:35]
	v_mfma_f32_16x16x32_bf16 v[20:23], v[156:159], v[192:195], v[20:23]
	v_mfma_f32_16x16x32_bf16 v[16:19], v[164:167], v[192:195], v[16:19]
	v_mfma_f32_16x16x32_bf16 v[4:7], v[156:159], v[200:203], v[4:7]
	v_mfma_f32_16x16x32_bf16 v[0:3], v[164:167], v[200:203], v[0:3]
	v_mfma_f32_16x16x32_bf16 v[52:55], v[160:163], v[176:179], v[52:55]
	v_mfma_f32_16x16x32_bf16 v[48:51], v[168:171], v[176:179], v[48:51]
	v_mfma_f32_16x16x32_bf16 v[36:39], v[160:163], v[186:189], v[36:39]
	v_mfma_f32_16x16x32_bf16 v[32:35], v[168:171], v[186:189], v[32:35]
	v_mfma_f32_16x16x32_bf16 v[20:23], v[160:163], v[196:199], v[20:23]
	v_mfma_f32_16x16x32_bf16 v[16:19], v[168:171], v[196:199], v[16:19]
	v_mfma_f32_16x16x32_bf16 v[4:7], v[160:163], v[204:207], v[4:7]
	v_mfma_f32_16x16x32_bf16 v[0:3], v[168:171], v[204:207], v[0:3]
	s_barrier
	s_add_i32 s8, 0, 0x18000
	s_add_i32 s84, 0, 0x1c000
	v_add_u32_e32 v142, s8, v185
	v_add_u32_e32 v168, s84, v185
	ds_read_b128 v[130:133], v142
	ds_read_b128 v[134:137], v142 offset:1024
	ds_read_b128 v[138:141], v142 offset:2048
	ds_read_b128 v[142:145], v142 offset:3072
	ds_read_b128 v[156:159], v168
	ds_read_b128 v[160:163], v168 offset:1024
	ds_read_b128 v[164:167], v168 offset:2048
	ds_read_b128 v[168:171], v168 offset:3072
	s_add_u32 s64, s64, 0xb0000
	s_addc_u32 s65, s65, 0
	s_mov_b32 m0, s19
	v_lshl_add_u64 v[228:229], s[64:65], 0, v[150:151]
	ds_read_b128 v[172:175], v191 offset:32768
	ds_read_b128 v[176:179], v191 offset:33792
	ds_read_b128 v[180:183], v191 offset:34816
	ds_read_b128 v[186:189], v191 offset:35840
	ds_read_b128 v[192:195], v191 offset:36864
	ds_read_b128 v[196:199], v191 offset:37888
	ds_read_b128 v[200:203], v191 offset:38912
	ds_read_b128 v[204:207], v191 offset:39936
	global_load_lds_dwordx4 v[228:229], off
	v_lshl_add_u64 v[228:229], s[64:65], 0, v[148:149]
	s_mov_b32 m0, s20
	s_nop 0
	global_load_lds_dwordx4 v[228:229], off
	s_waitcnt vmcnt(8)
	s_waitcnt lgkmcnt(0)
	s_barrier
; #define PG8_STAGE(bufoff, gbase, voff) do { _Pragma("unroll") for (int _i = 0; _i < 2; ++_i) \
;         __builtin_amdgcn_global_load_lds((const unsigned*)((const char*)(gbase) + (voff)[_i]), (PG8_LAS unsigned*)(lds + (bufoff) + ldsw + _i * 8192), 16, 0, 0); } while (0)
; #define PG8_LDA(dst, b, h) do { _Pragma("unroll") for (int m = 0; m < 4; ++m) _Pragma("unroll") for (int k = 0; k < 2; ++k) dst[m][k] = *(const PG8_LAS bf16x8*)(lds + PG8_SA(b, h) + aoff + m * 2048 + k * 1024); } while (0)
; #define PG8_MMA(ai, bj, At, Bt) do { __builtin_amdgcn_s_setprio(1); _Pragma("unroll") for (int m = 0; m < 4; ++m) _Pragma("unroll") for (int n = 0; n < 2; ++n) _Pragma("unroll") for (int k = 0; k < 2; ++k) \
;         acc[ai][bj][m][n] = __builtin_amdgcn_mfma_f32_16x16x32_bf16(Bt[n][k], At[m][k], acc[ai][bj][m][n], 0, 0, 0); __builtin_amdgcn_s_setprio(0); } while (0)
; #define PG8_WAIT_V(n) asm volatile("s_waitcnt vmcnt(" #n ")" ::: "memory")
; #define PG8_WAIT_L(n) asm volatile("s_waitcnt lgkmcnt(" #n ")" ::: "memory")
; #define PG8_BAR __builtin_amdgcn_s_barrier()
; #define PG8_SCHED __builtin_amdgcn_sched_barrier(0)
; template <class Epi, class Sched, bool ALIGN_EPI = false, bool SP2 = false>
; __device__ __forceinline__ void gemm_phase(PG8_LAS unsigned char* lds, const Gemm g, const Sched& S, const Epi& E) {
;     ...
;             PG8_WAIT_V(8); PG8_WAIT_L(0); PG8_BAR; PG8_MMA(0, 0, At, B0); PG8_MMA(0, 1, At, B1); PG8_BAR; PG8_SCHED;
;             PG8_LDA(At, 1, 1); PG8_STAGE(PG8_SB(1, 0), b3, voffB); PG8_STAGE(PG8_SB(1, 1), b3 + hstep, voffB); PG8_STAGE(PG8_SA(1, 0), a3, voffA);
;             PG8_WAIT_V(8); PG8_WAIT_L(0); PG8_BAR; PG8_MMA(1, 0, At, B0); PG8_MMA(1, 1, At, B1); PG8_BAR; PG8_SCHED;
;     ...
;         if constexpr (ALIGN_EPI) { if (wr == 0) PG8_BAR; }
	s_waitcnt lgkmcnt(0)
	v_mfma_f32_16x16x32_bf16 v[124:127], v[130:133], v[172:175], v[124:127]
	v_mfma_f32_16x16x32_bf16 v[120:123], v[138:141], v[172:175], v[120:123]
	v_mfma_f32_16x16x32_bf16 v[108:111], v[130:133], v[180:183], v[108:111]
	v_mfma_f32_16x16x32_bf16 v[104:107], v[138:141], v[180:183], v[104:107]
	v_mfma_f32_16x16x32_bf16 v[92:95], v[130:133], v[192:195], v[92:95]
	v_mfma_f32_16x16x32_bf16 v[88:91], v[138:141], v[192:195], v[88:91]
	v_mfma_f32_16x16x32_bf16 v[76:79], v[130:133], v[200:203], v[76:79]
	v_mfma_f32_16x16x32_bf16 v[72:75], v[138:141], v[200:203], v[72:75]
	v_mfma_f32_16x16x32_bf16 v[124:127], v[134:137], v[176:179], v[124:127]
	v_mfma_f32_16x16x32_bf16 v[120:123], v[142:145], v[176:179], v[120:123]
	v_mfma_f32_16x16x32_bf16 v[108:111], v[134:137], v[186:189], v[108:111]
	v_mfma_f32_16x16x32_bf16 v[104:107], v[142:145], v[186:189], v[104:107]
	v_mfma_f32_16x16x32_bf16 v[92:95], v[134:137], v[196:199], v[92:95]
	v_mfma_f32_16x16x32_bf16 v[88:91], v[142:145], v[196:199], v[88:91]
	v_mfma_f32_16x16x32_bf16 v[76:79], v[134:137], v[204:207], v[76:79]
	v_mfma_f32_16x16x32_bf16 v[72:75], v[142:145], v[204:207], v[72:75]
	v_mfma_f32_16x16x32_bf16 v[116:119], v[156:159], v[172:175], v[116:119]
	v_mfma_f32_16x16x32_bf16 v[112:115], v[164:167], v[172:175], v[112:115]
	v_mfma_f32_16x16x32_bf16 v[100:103], v[156:159], v[180:183], v[100:103]
	v_mfma_f32_16x16x32_bf16 v[96:99], v[164:167], v[180:183], v[96:99]
	v_mfma_f32_16x16x32_bf16 v[84:87], v[156:159], v[192:195], v[84:87]
	v_mfma_f32_16x16x32_bf16 v[80:83], v[164:167], v[192:195], v[80:83]
	v_mfma_f32_16x16x32_bf16 v[68:71], v[156:159], v[200:203], v[68:71]
	v_mfma_f32_16x16x32_bf16 v[64:67], v[164:167], v[200:203], v[64:67]
	v_mfma_f32_16x16x32_bf16 v[116:119], v[160:163], v[176:179], v[116:119]
	v_mfma_f32_16x16x32_bf16 v[112:115], v[168:171], v[176:179], v[112:115]
	v_mfma_f32_16x16x32_bf16 v[100:103], v[160:163], v[186:189], v[100:103]
	v_mfma_f32_16x16x32_bf16 v[96:99], v[168:171], v[186:189], v[96:99]
	v_mfma_f32_16x16x32_bf16 v[84:87], v[160:163], v[196:199], v[84:87]
	v_mfma_f32_16x16x32_bf16 v[80:83], v[168:171], v[196:199], v[80:83]
	v_mfma_f32_16x16x32_bf16 v[68:71], v[160:163], v[204:207], v[68:71]
	v_mfma_f32_16x16x32_bf16 v[64:67], v[168:171], v[204:207], v[64:67]
	s_barrier
	s_add_i32 s8, s8, s14
	v_lshl_add_u64 v[208:209], v[208:209], 0, s[90:91]
	s_mov_b32 m0, s8
	ds_read_b128 v[172:175], v191 offset:49152
	ds_read_b128 v[176:179], v191 offset:50176
	ds_read_b128 v[180:183], v191 offset:51200
	ds_read_b128 v[186:189], v191 offset:52224
	ds_read_b128 v[192:195], v191 offset:53248
	ds_read_b128 v[196:199], v191 offset:54272
	ds_read_b128 v[200:203], v191 offset:55296
	ds_read_b128 v[204:207], v191 offset:56320
	global_load_lds_dwordx4 v[208:209], off
	s_add_i32 m0, s8, 0x2000
	s_add_u32 s46, s46, 0xb0080
	v_lshl_add_u64 v[208:209], v[210:211], 0, s[90:91]
	s_addc_u32 s47, s47, 0
	s_add_i32 s8, s84, s14
	global_load_lds_dwordx4 v[208:209], off
	v_lshl_add_u64 v[208:209], s[46:47], 0, v[128:129]
	s_mov_b32 m0, s8
	s_nop 0
	global_load_lds_dwordx4 v[208:209], off
	v_lshl_add_u64 v[208:209], s[46:47], 0, v[146:147]
	s_add_i32 m0, s8, 0x2000
	s_nop 0
	global_load_lds_dwordx4 v[208:209], off
	v_lshl_add_u64 v[208:209], v[214:215], 0, s[90:91]
	s_mov_b32 m0, s27
	s_nop 0
	global_load_lds_dwordx4 v[208:209], off
	v_lshl_add_u64 v[208:209], v[222:223], 0, s[90:91]
	s_mov_b32 m0, s28
	s_nop 0
	global_load_lds_dwordx4 v[208:209], off
	s_waitcnt vmcnt(8)
	s_waitcnt lgkmcnt(0)
	s_barrier
	s_waitcnt lgkmcnt(0)
	v_mfma_f32_16x16x32_bf16 v[60:63], v[130:133], v[172:175], v[60:63]
	v_mfma_f32_16x16x32_bf16 v[56:59], v[138:141], v[172:175], v[56:59]
	v_mfma_f32_16x16x32_bf16 v[44:47], v[130:133], v[180:183], v[44:47]
	v_mfma_f32_16x16x32_bf16 v[40:43], v[138:141], v[180:183], v[40:43]
	v_mfma_f32_16x16x32_bf16 v[28:31], v[130:133], v[192:195], v[28:31]
	v_mfma_f32_16x16x32_bf16 v[24:27], v[138:141], v[192:195], v[24:27]
	v_mfma_f32_16x16x32_bf16 v[12:15], v[130:133], v[200:203], v[12:15]
	v_mfma_f32_16x16x32_bf16 v[8:11], v[138:141], v[200:203], v[8:11]
	v_mfma_f32_16x16x32_bf16 v[60:63], v[134:137], v[176:179], v[60:63]
	v_mfma_f32_16x16x32_bf16 v[56:59], v[142:145], v[176:179], v[56:59]
	v_mfma_f32_16x16x32_bf16 v[44:47], v[134:137], v[186:189], v[44:47]
	v_mfma_f32_16x16x32_bf16 v[40:43], v[142:145], v[186:189], v[40:43]
	v_mfma_f32_16x16x32_bf16 v[28:31], v[134:137], v[196:199], v[28:31]
	v_mfma_f32_16x16x32_bf16 v[24:27], v[142:145], v[196:199], v[24:27]
	v_mfma_f32_16x16x32_bf16 v[12:15], v[134:137], v[204:207], v[12:15]
	v_mfma_f32_16x16x32_bf16 v[8:11], v[142:145], v[204:207], v[8:11]
	v_mfma_f32_16x16x32_bf16 v[52:55], v[156:159], v[172:175], v[52:55]
	v_mfma_f32_16x16x32_bf16 v[48:51], v[164:167], v[172:175], v[48:51]
	v_mfma_f32_16x16x32_bf16 v[36:39], v[156:159], v[180:183], v[36:39]
	v_mfma_f32_16x16x32_bf16 v[32:35], v[164:167], v[180:183], v[32:35]
	v_mfma_f32_16x16x32_bf16 v[20:23], v[156:159], v[192:195], v[20:23]
	v_mfma_f32_16x16x32_bf16 v[16:19], v[164:167], v[192:195], v[16:19]
	v_mfma_f32_16x16x32_bf16 v[4:7], v[156:159], v[200:203], v[4:7]
	v_mfma_f32_16x16x32_bf16 v[0:3], v[164:167], v[200:203], v[0:3]
	v_mfma_f32_16x16x32_bf16 v[52:55], v[160:163], v[176:179], v[52:55]
	v_mfma_f32_16x16x32_bf16 v[48:51], v[168:171], v[176:179], v[48:51]
	v_mfma_f32_16x16x32_bf16 v[36:39], v[160:163], v[186:189], v[36:39]
	v_mfma_f32_16x16x32_bf16 v[32:35], v[168:171], v[186:189], v[32:35]
	v_mfma_f32_16x16x32_bf16 v[20:23], v[160:163], v[196:199], v[20:23]
	v_mfma_f32_16x16x32_bf16 v[16:19], v[168:171], v[196:199], v[16:19]
	v_mfma_f32_16x16x32_bf16 v[4:7], v[160:163], v[204:207], v[4:7]
	v_mfma_f32_16x16x32_bf16 v[0:3], v[168:171], v[204:207], v[0:3]
	s_barrier
	s_add_i32 s70, s70, 2
	s_add_u32 s36, s36, 0x100
	s_addc_u32 s37, s37, 0
	s_cmp_gt_u32 s70, 41
	s_mov_b64 s[96:97], s[44:45]
	s_cbranch_scc0 .LBB0_957
	s_setprio 0
	s_and_b64 vcc, exec, s[58:59]
	s_cbranch_vccz .LBB0_960
	s_barrier

; #define PG8_STAGE(bufoff, gbase, voff) do { _Pragma("unroll") for (int _i = 0; _i < 2; ++_i) \
;         __builtin_amdgcn_global_load_lds((const unsigned*)((const char*)(gbase) + (voff)[_i]), (PG8_LAS unsigned*)(lds + (bufoff) + ldsw + _i * 8192), 16, 0, 0); } while (0)
; #define PG8_LDA(dst, b, h) do { _Pragma("unroll") for (int m = 0; m < 4; ++m) _Pragma("unroll") for (int k = 0; k < 2; ++k) dst[m][k] = *(const PG8_LAS bf16x8*)(lds + PG8_SA(b, h) + aoff + m * 2048 + k * 1024); } while (0)
; #define PG8_LDB(dst, b, h) do { _Pragma("unroll") for (int n = 0; n < 2; ++n) _Pragma("unroll") for (int k = 0; k < 2; ++k) dst[n][k] = *(const PG8_LAS bf16x8*)(lds + PG8_SB(b, h) + boff + n * 2048 + k * 1024); } while (0)
; #define PG8_WAIT_V(n) asm volatile("s_waitcnt vmcnt(" #n ")" ::: "memory")
; #define PG8_WAIT_L(n) asm volatile("s_waitcnt lgkmcnt(" #n ")" ::: "memory")
; #define PG8_BAR __builtin_amdgcn_s_barrier()
; template <class Epi, class Sched, bool ALIGN_EPI = false, bool SP2 = false>
; __device__ __forceinline__ void gemm_phase(PG8_LAS unsigned char* lds, const Gemm g, const Sched& S, const Epi& E) {
;     ...
;     for (;;) {
;         const bool has_next = S.next(ui + 1, nxt);
;         const char* nA = has_next ? (const char*)g.A + (size_t)nxt.pm * tstep : cA; const char* nB = has_next ? (const char*)g.Bt + (size_t)nxt.pn * tstep : cB;
;         for (int t = 0; t < nt; t += 2) {
;             const bool last = (t == nt - 2);
;             const char* a1 = cA + (size_t)(t + 1) * kstep;
;             const char* a2 = last ? nA : cA + (size_t)(t + 2) * kstep; const char* b2 = last ? nB : cB + (size_t)(t + 2) * kstep;
;             const char* a3 = a2 + kstep; const char* b3 = b2 + kstep;
;             if (last && has_next) S.a_ready(nxt);
;             if constexpr (SP2) {
;             PG8_LDB(B0, 0, 0); PG8_LDB(B1, 0, 1); PG8_SCHED; PG8_LDA(At, 0, 0); PG8_STAGE(PG8_SA(1, 1), a1 + hstep, voffA);
;             PG8_WAIT_V(8); PG8_WAIT_L(0); PG8_BAR; PG8_MMA(0, 0, At, B0); PG8_MMA(0, 1, At, B1); PG8_BAR; PG8_SCHED;
;     ...
; #pragma unroll
;         for (int a = 0; a < 2; ++a)
; #pragma unroll
;             for (int b = 0; b < 2; ++b)
; #pragma unroll
;                 for (int m = 0; m < 4; ++m)
; #pragma unroll
;                     for (int n = 0; n < 2; ++n) acc[a][b][m][n] = (f32x4){0.f, 0.f, 0.f, 0.f};
;         cur = nxt; cA = nA; cB = nB; ++ui;
.LBB0_994:
	s_add_u32 s36, s46, 0x100
	v_mov_b64_e32 v[0:1], 0
	s_addc_u32 s37, s47, 0
	s_mov_b32 s84, -2
	v_mov_b64_e32 v[2:3], 0
	v_mov_b64_e32 v[4:5], 0
	v_mov_b64_e32 v[6:7], 0
	v_mov_b64_e32 v[16:17], 0
	v_mov_b64_e32 v[18:19], 0
	v_mov_b64_e32 v[20:21], 0
	v_mov_b64_e32 v[22:23], 0
	v_mov_b64_e32 v[32:33], 0
	v_mov_b64_e32 v[34:35], 0
	v_mov_b64_e32 v[36:37], 0
	v_mov_b64_e32 v[38:39], 0
	v_mov_b64_e32 v[48:49], 0
	v_mov_b64_e32 v[50:51], 0
	v_mov_b64_e32 v[52:53], 0
	v_mov_b64_e32 v[54:55], 0
	v_mov_b64_e32 v[8:9], 0
	v_mov_b64_e32 v[10:11], 0
	v_mov_b64_e32 v[12:13], 0
	v_mov_b64_e32 v[14:15], 0
	v_mov_b64_e32 v[24:25], 0
	v_mov_b64_e32 v[26:27], 0
	v_mov_b64_e32 v[28:29], 0
	v_mov_b64_e32 v[30:31], 0
	v_mov_b64_e32 v[40:41], 0
	v_mov_b64_e32 v[42:43], 0
	v_mov_b64_e32 v[44:45], 0
	v_mov_b64_e32 v[46:47], 0
	v_mov_b64_e32 v[56:57], 0
	v_mov_b64_e32 v[58:59], 0
	v_mov_b64_e32 v[60:61], 0
	v_mov_b64_e32 v[62:63], 0
	v_mov_b64_e32 v[64:65], 0
	v_mov_b64_e32 v[66:67], 0
	v_mov_b64_e32 v[68:69], 0
	v_mov_b64_e32 v[70:71], 0
	v_mov_b64_e32 v[80:81], 0
	v_mov_b64_e32 v[82:83], 0
	v_mov_b64_e32 v[84:85], 0
	v_mov_b64_e32 v[86:87], 0
	v_mov_b64_e32 v[96:97], 0
	v_mov_b64_e32 v[98:99], 0
	v_mov_b64_e32 v[100:101], 0
	v_mov_b64_e32 v[102:103], 0
	v_mov_b64_e32 v[112:113], 0
	v_mov_b64_e32 v[114:115], 0
	v_mov_b64_e32 v[116:117], 0
	v_mov_b64_e32 v[118:119], 0
	v_mov_b64_e32 v[72:73], 0
	v_mov_b64_e32 v[74:75], 0
	v_mov_b64_e32 v[76:77], 0
	v_mov_b64_e32 v[78:79], 0
	v_mov_b64_e32 v[88:89], 0
	v_mov_b64_e32 v[90:91], 0
	v_mov_b64_e32 v[92:93], 0
	v_mov_b64_e32 v[94:95], 0
	v_mov_b64_e32 v[104:105], 0
	v_mov_b64_e32 v[106:107], 0
	v_mov_b64_e32 v[108:109], 0
	v_mov_b64_e32 v[110:111], 0
	v_mov_b64_e32 v[120:121], 0
	v_mov_b64_e32 v[122:123], 0
	v_mov_b64_e32 v[124:125], 0
	v_mov_b64_e32 v[126:127], 0
	s_and_b64 s[98:99], exec, s[62:63]
	s_cbranch_scc1 .Lsp_5
	s_setprio 1
.Lsp_5:
.LBB0_995:
	s_add_u32 s42, s96, 0x100
	s_addc_u32 s43, s97, 0
	s_add_i32 s8, 0, 0x10000
	s_cmp_eq_u32 s84, 40
	s_cselect_b32 s65, s67, s43
	s_cselect_b32 s64, s66, s42
	s_cselect_b32 s47, s73, s37
	s_cselect_b32 s46, s72, s36
	s_add_i32 s85, 0, 0x14000
	v_add_u32_e32 v142, s8, v201
	v_add_u32_e32 v168, s85, v201
	ds_read_b128 v[130:133], v142
	ds_read_b128 v[134:137], v142 offset:1024
	ds_read_b128 v[138:141], v142 offset:2048
	ds_read_b128 v[142:145], v142 offset:3072
	ds_read_b128 v[156:159], v168
	ds_read_b128 v[160:163], v168 offset:1024
	ds_read_b128 v[164:167], v168 offset:2048
	ds_read_b128 v[168:171], v168 offset:3072
	v_lshl_add_u64 v[208:209], s[96:97], 0, v[152:153]
	s_add_i32 m0, s15, 0xc000
	ds_read_b128 v[172:175], v203
	ds_read_b128 v[176:179], v203 offset:1024
	ds_read_b128 v[180:183], v203 offset:2048
	ds_read_b128 v[184:187], v203 offset:3072
	ds_read_b128 v[188:191], v203 offset:4096
	ds_read_b128 v[192:195], v203 offset:5120
	ds_read_b128 v[196:199], v203 offset:6144
	ds_read_b128 v[204:207], v203 offset:7168
	global_load_lds_dwordx4 v[208:209], off
	v_lshl_add_u64 v[208:209], s[96:97], 0, v[154:155]
	s_add_i32 m0, s15, 0xe000
	s_nop 0
	global_load_lds_dwordx4 v[208:209], off
	s_waitcnt vmcnt(8)
	s_waitcnt lgkmcnt(0)
	s_barrier
	s_waitcnt lgkmcnt(0)
	v_mfma_f32_16x16x32_bf16 v[124:127], v[130:133], v[172:175], v[124:127]
	v_mfma_f32_16x16x32_bf16 v[120:123], v[138:141], v[172:175], v[120:123]
	v_mfma_f32_16x16x32_bf16 v[108:111], v[130:133], v[180:183], v[108:111]
	v_mfma_f32_16x16x32_bf16 v[104:107], v[138:141], v[180:183], v[104:107]
	v_mfma_f32_16x16x32_bf16 v[92:95], v[130:133], v[188:191], v[92:95]
	v_mfma_f32_16x16x32_bf16 v[88:91], v[138:141], v[188:191], v[88:91]
	v_mfma_f32_16x16x32_bf16 v[76:79], v[130:133], v[196:199], v[76:79]
	v_mfma_f32_16x16x32_bf16 v[72:75], v[138:141], v[196:199], v[72:75]
	v_mfma_f32_16x16x32_bf16 v[124:127], v[134:137], v[176:179], v[124:127]
	v_mfma_f32_16x16x32_bf16 v[120:123], v[142:145], v[176:179], v[120:123]
	v_mfma_f32_16x16x32_bf16 v[108:111], v[134:137], v[184:187], v[108:111]
	v_mfma_f32_16x16x32_bf16 v[104:107], v[142:145], v[184:187], v[104:107]
	v_mfma_f32_16x16x32_bf16 v[92:95], v[134:137], v[192:195], v[92:95]
	v_mfma_f32_16x16x32_bf16 v[88:91], v[142:145], v[192:195], v[88:91]
	v_mfma_f32_16x16x32_bf16 v[76:79], v[134:137], v[204:207], v[76:79]
	v_mfma_f32_16x16x32_bf16 v[72:75], v[142:145], v[204:207], v[72:75]
	v_mfma_f32_16x16x32_bf16 v[116:119], v[156:159], v[172:175], v[116:119]
	v_mfma_f32_16x16x32_bf16 v[112:115], v[164:167], v[172:175], v[112:115]
	v_mfma_f32_16x16x32_bf16 v[100:103], v[156:159], v[180:183], v[100:103]
	v_mfma_f32_16x16x32_bf16 v[96:99], v[164:167], v[180:183], v[96:99]
	v_mfma_f32_16x16x32_bf16 v[84:87], v[156:159], v[188:191], v[84:87]
	v_mfma_f32_16x16x32_bf16 v[80:83], v[164:167], v[188:191], v[80:83]
	v_mfma_f32_16x16x32_bf16 v[68:71], v[156:159], v[196:199], v[68:71]
	v_mfma_f32_16x16x32_bf16 v[64:67], v[164:167], v[196:199], v[64:67]
	v_mfma_f32_16x16x32_bf16 v[116:119], v[160:163], v[176:179], v[116:119]
	v_mfma_f32_16x16x32_bf16 v[112:115], v[168:171], v[176:179], v[112:115]
	v_mfma_f32_16x16x32_bf16 v[100:103], v[160:163], v[184:187], v[100:103]
	v_mfma_f32_16x16x32_bf16 v[96:99], v[168:171], v[184:187], v[96:99]
	v_mfma_f32_16x16x32_bf16 v[84:87], v[160:163], v[192:195], v[84:87]
	v_mfma_f32_16x16x32_bf16 v[80:83], v[168:171], v[192:195], v[80:83]
	v_mfma_f32_16x16x32_bf16 v[68:71], v[160:163], v[204:207], v[68:71]
	v_mfma_f32_16x16x32_bf16 v[64:67], v[168:171], v[204:207], v[64:67]
	s_barrier
; #define PG8_STAGE(bufoff, gbase, voff) do { _Pragma("unroll") for (int _i = 0; _i < 2; ++_i) \
;         __builtin_amdgcn_global_load_lds((const unsigned*)((const char*)(gbase) + (voff)[_i]), (PG8_LAS unsigned*)(lds + (bufoff) + ldsw + _i * 8192), 16, 0, 0); } while (0)
; #define PG8_LDA(dst, b, h) do { _Pragma("unroll") for (int m = 0; m < 4; ++m) _Pragma("unroll") for (int k = 0; k < 2; ++k) dst[m][k] = *(const PG8_LAS bf16x8*)(lds + PG8_SA(b, h) + aoff + m * 2048 + k * 1024); } while (0)
; #define PG8_LDB(dst, b, h) do { _Pragma("unroll") for (int n = 0; n < 2; ++n) _Pragma("unroll") for (int k = 0; k < 2; ++k) dst[n][k] = *(const PG8_LAS bf16x8*)(lds + PG8_SB(b, h) + boff + n * 2048 + k * 1024); } while (0)
; #define PG8_MMA(ai, bj, At, Bt) do { __builtin_amdgcn_s_setprio(1); _Pragma("unroll") for (int m = 0; m < 4; ++m) _Pragma("unroll") for (int n = 0; n < 2; ++n) _Pragma("unroll") for (int k = 0; k < 2; ++k) \
;         acc[ai][bj][m][n] = __builtin_amdgcn_mfma_f32_16x16x32_bf16(Bt[n][k], At[m][k], acc[ai][bj][m][n], 0, 0, 0); __builtin_amdgcn_s_setprio(0); } while (0)
; #define PG8_WAIT_V(n) asm volatile("s_waitcnt vmcnt(" #n ")" ::: "memory")
; #define PG8_WAIT_L(n) asm volatile("s_waitcnt lgkmcnt(" #n ")" ::: "memory")
; #define PG8_BAR __builtin_amdgcn_s_barrier()
; #define PG8_SCHED __builtin_amdgcn_sched_barrier(0)
; template <class Epi, class Sched, bool ALIGN_EPI = false, bool SP2 = false>
; __device__ __forceinline__ void gemm_phase(PG8_LAS unsigned char* lds, const Gemm g, const Sched& S, const Epi& E) {
;     ...
;             PG8_LDA(At, 0, 1); PG8_STAGE(PG8_SB(0, 0), b2, voffB); PG8_STAGE(PG8_SB(0, 1), b2 + hstep, voffB); PG8_STAGE(PG8_SA(0, 0), a2, voffA);
;             PG8_WAIT_V(8); PG8_WAIT_L(0); PG8_BAR; PG8_MMA(1, 0, At, B0); PG8_MMA(1, 1, At, B1); PG8_BAR; PG8_SCHED;
;             PG8_LDB(B0, 1, 0); PG8_LDB(B1, 1, 1); PG8_SCHED; PG8_LDA(At, 1, 0); PG8_STAGE(PG8_SA(0, 1), a2 + hstep, voffA);
;             PG8_WAIT_V(8); PG8_WAIT_L(0); PG8_BAR; PG8_MMA(0, 0, At, B0); PG8_MMA(0, 1, At, B1); PG8_BAR; PG8_SCHED;
	s_add_i32 s8, s8, s14
	v_lshl_add_u64 v[208:209], s[46:47], 0, v[128:129]
	s_mov_b32 m0, s8
	ds_read_b128 v[172:175], v203 offset:16384
	ds_read_b128 v[176:179], v203 offset:17408
	ds_read_b128 v[180:183], v203 offset:18432
	ds_read_b128 v[184:187], v203 offset:19456
	ds_read_b128 v[188:191], v203 offset:20480
	ds_read_b128 v[192:195], v203 offset:21504
	ds_read_b128 v[196:199], v203 offset:22528
	ds_read_b128 v[204:207], v203 offset:23552
	global_load_lds_dwordx4 v[208:209], off
	s_add_i32 m0, s8, 0x2000
	s_add_u32 s96, s46, 0xb0000
	v_lshl_add_u64 v[210:211], s[46:47], 0, v[146:147]
	s_addc_u32 s97, s47, 0
	s_add_i32 s8, s85, s14
	global_load_lds_dwordx4 v[210:211], off
	v_lshl_add_u64 v[214:215], s[96:97], 0, v[128:129]
	s_mov_b32 m0, s8
	v_lshl_add_u64 v[222:223], s[64:65], 0, v[148:149]
	global_load_lds_dwordx4 v[214:215], off
	v_lshl_add_u64 v[214:215], s[96:97], 0, v[146:147]
	s_add_i32 m0, s8, 0x2000
	s_nop 0
	global_load_lds_dwordx4 v[214:215], off
	v_lshl_add_u64 v[214:215], s[64:65], 0, v[150:151]
	s_mov_b32 m0, s15
	s_nop 0
	global_load_lds_dwordx4 v[214:215], off
	s_mov_b32 m0, s18
	s_nop 0
	global_load_lds_dwordx4 v[222:223], off
	s_waitcnt vmcnt(8)
	s_waitcnt lgkmcnt(0)
	s_barrier
	s_waitcnt lgkmcnt(0)
	v_mfma_f32_16x16x32_bf16 v[60:63], v[130:133], v[172:175], v[60:63]
	v_mfma_f32_16x16x32_bf16 v[56:59], v[138:141], v[172:175], v[56:59]
	v_mfma_f32_16x16x32_bf16 v[44:47], v[130:133], v[180:183], v[44:47]
	v_mfma_f32_16x16x32_bf16 v[40:43], v[138:141], v[180:183], v[40:43]
	v_mfma_f32_16x16x32_bf16 v[28:31], v[130:133], v[188:191], v[28:31]
	v_mfma_f32_16x16x32_bf16 v[24:27], v[138:141], v[188:191], v[24:27]
	v_mfma_f32_16x16x32_bf16 v[12:15], v[130:133], v[196:199], v[12:15]
	v_mfma_f32_16x16x32_bf16 v[8:11], v[138:141], v[196:199], v[8:11]
	v_mfma_f32_16x16x32_bf16 v[60:63], v[134:137], v[176:179], v[60:63]
	v_mfma_f32_16x16x32_bf16 v[56:59], v[142:145], v[176:179], v[56:59]
	v_mfma_f32_16x16x32_bf16 v[44:47], v[134:137], v[184:187], v[44:47]
	v_mfma_f32_16x16x32_bf16 v[40:43], v[142:145], v[184:187], v[40:43]
	v_mfma_f32_16x16x32_bf16 v[28:31], v[134:137], v[192:195], v[28:31]
	v_mfma_f32_16x16x32_bf16 v[24:27], v[142:145], v[192:195], v[24:27]
	v_mfma_f32_16x16x32_bf16 v[12:15], v[134:137], v[204:207], v[12:15]
	v_mfma_f32_16x16x32_bf16 v[8:11], v[142:145], v[204:207], v[8:11]
	v_mfma_f32_16x16x32_bf16 v[52:55], v[156:159], v[172:175], v[52:55]
	v_mfma_f32_16x16x32_bf16 v[48:51], v[164:167], v[172:175], v[48:51]
	v_mfma_f32_16x16x32_bf16 v[36:39], v[156:159], v[180:183], v[36:39]
	v_mfma_f32_16x16x32_bf16 v[32:35], v[164:167], v[180:183], v[32:35]
	v_mfma_f32_16x16x32_bf16 v[20:23], v[156:159], v[188:191], v[20:23]
	v_mfma_f32_16x16x32_bf16 v[16:19], v[164:167], v[188:191], v[16:19]
	v_mfma_f32_16x16x32_bf16 v[4:7], v[156:159], v[196:199], v[4:7]
	v_mfma_f32_16x16x32_bf16 v[0:3], v[164:167], v[196:199], v[0:3]
	v_mfma_f32_16x16x32_bf16 v[52:55], v[160:163], v[176:179], v[52:55]
	v_mfma_f32_16x16x32_bf16 v[48:51], v[168:171], v[176:179], v[48:51]
	v_mfma_f32_16x16x32_bf16 v[36:39], v[160:163], v[184:187], v[36:39]
	v_mfma_f32_16x16x32_bf16 v[32:35], v[168:171], v[184:187], v[32:35]
	v_mfma_f32_16x16x32_bf16 v[20:23], v[160:163], v[192:195], v[20:23]
	v_mfma_f32_16x16x32_bf16 v[16:19], v[168:171], v[192:195], v[16:19]
	v_mfma_f32_16x16x32_bf16 v[4:7], v[160:163], v[204:207], v[4:7]
	v_mfma_f32_16x16x32_bf16 v[0:3], v[168:171], v[204:207], v[0:3]
	s_barrier
	s_add_i32 s8, 0, 0x18000
	s_add_i32 s85, 0, 0x1c000
	v_add_u32_e32 v142, s8, v201
	v_add_u32_e32 v168, s85, v201
	ds_read_b128 v[130:133], v142
	ds_read_b128 v[134:137], v142 offset:1024
	ds_read_b128 v[138:141], v142 offset:2048
	ds_read_b128 v[142:145], v142 offset:3072
	ds_read_b128 v[156:159], v168
	ds_read_b128 v[160:163], v168 offset:1024
	ds_read_b128 v[164:167], v168 offset:2048
	ds_read_b128 v[168:171], v168 offset:3072
	s_add_u32 s64, s64, 0xb0000
	s_addc_u32 s65, s65, 0
	s_mov_b32 m0, s19
	v_lshl_add_u64 v[228:229], s[64:65], 0, v[150:151]
	ds_read_b128 v[172:175], v203 offset:32768
	ds_read_b128 v[176:179], v203 offset:33792
	ds_read_b128 v[180:183], v203 offset:34816
	ds_read_b128 v[184:187], v203 offset:35840
	ds_read_b128 v[188:191], v203 offset:36864
	ds_read_b128 v[192:195], v203 offset:37888
	ds_read_b128 v[196:199], v203 offset:38912
	ds_read_b128 v[204:207], v203 offset:39936
	global_load_lds_dwordx4 v[228:229], off
	v_lshl_add_u64 v[228:229], s[64:65], 0, v[148:149]
	s_mov_b32 m0, s20
	s_nop 0
	global_load_lds_dwordx4 v[228:229], off
	s_waitcnt vmcnt(8)
	s_waitcnt lgkmcnt(0)
	s_barrier
; #define PG8_STAGE(bufoff, gbase, voff) do { _Pragma("unroll") for (int _i = 0; _i < 2; ++_i) \
;         __builtin_amdgcn_global_load_lds((const unsigned*)((const char*)(gbase) + (voff)[_i]), (PG8_LAS unsigned*)(lds + (bufoff) + ldsw + _i * 8192), 16, 0, 0); } while (0)
; #define PG8_LDA(dst, b, h) do { _Pragma("unroll") for (int m = 0; m < 4; ++m) _Pragma("unroll") for (int k = 0; k < 2; ++k) dst[m][k] = *(const PG8_LAS bf16x8*)(lds + PG8_SA(b, h) + aoff + m * 2048 + k * 1024); } while (0)
; #define PG8_MMA(ai, bj, At, Bt) do { __builtin_amdgcn_s_setprio(1); _Pragma("unroll") for (int m = 0; m < 4; ++m) _Pragma("unroll") for (int n = 0; n < 2; ++n) _Pragma("unroll") for (int k = 0; k < 2; ++k) \
;         acc[ai][bj][m][n] = __builtin_amdgcn_mfma_f32_16x16x32_bf16(Bt[n][k], At[m][k], acc[ai][bj][m][n], 0, 0, 0); __builtin_amdgcn_s_setprio(0); } while (0)
; #define PG8_WAIT_V(n) asm volatile("s_waitcnt vmcnt(" #n ")" ::: "memory")
; #define PG8_WAIT_L(n) asm volatile("s_waitcnt lgkmcnt(" #n ")" ::: "memory")
; #define PG8_BAR __builtin_amdgcn_s_barrier()
; #define PG8_SCHED __builtin_amdgcn_sched_barrier(0)
; template <class Epi, class Sched, bool ALIGN_EPI = false, bool SP2 = false>
; __device__ __forceinline__ void gemm_phase(PG8_LAS unsigned char* lds, const Gemm g, const Sched& S, const Epi& E) {
;     ...
;             PG8_WAIT_V(8); PG8_WAIT_L(0); PG8_BAR; PG8_MMA(0, 0, At, B0); PG8_MMA(0, 1, At, B1); PG8_BAR; PG8_SCHED;
;             PG8_LDA(At, 1, 1); PG8_STAGE(PG8_SB(1, 0), b3, voffB); PG8_STAGE(PG8_SB(1, 1), b3 + hstep, voffB); PG8_STAGE(PG8_SA(1, 0), a3, voffA);
;             PG8_WAIT_V(8); PG8_WAIT_L(0); PG8_BAR; PG8_MMA(1, 0, At, B0); PG8_MMA(1, 1, At, B1); PG8_BAR; PG8_SCHED;
;     ...
;         if constexpr (ALIGN_EPI) { if (wr == 0) PG8_BAR; }
	s_waitcnt lgkmcnt(0)
	v_mfma_f32_16x16x32_bf16 v[124:127], v[130:133], v[172:175], v[124:127]
	v_mfma_f32_16x16x32_bf16 v[120:123], v[138:141], v[172:175], v[120:123]
	v_mfma_f32_16x16x32_bf16 v[108:111], v[130:133], v[180:183], v[108:111]
	v_mfma_f32_16x16x32_bf16 v[104:107], v[138:141], v[180:183], v[104:107]
	v_mfma_f32_16x16x32_bf16 v[92:95], v[130:133], v[188:191], v[92:95]
	v_mfma_f32_16x16x32_bf16 v[88:91], v[138:141], v[188:191], v[88:91]
	v_mfma_f32_16x16x32_bf16 v[76:79], v[130:133], v[196:199], v[76:79]
	v_mfma_f32_16x16x32_bf16 v[72:75], v[138:141], v[196:199], v[72:75]
	v_mfma_f32_16x16x32_bf16 v[124:127], v[134:137], v[176:179], v[124:127]
	v_mfma_f32_16x16x32_bf16 v[120:123], v[142:145], v[176:179], v[120:123]
	v_mfma_f32_16x16x32_bf16 v[108:111], v[134:137], v[184:187], v[108:111]
	v_mfma_f32_16x16x32_bf16 v[104:107], v[142:145], v[184:187], v[104:107]
	v_mfma_f32_16x16x32_bf16 v[92:95], v[134:137], v[192:195], v[92:95]
	v_mfma_f32_16x16x32_bf16 v[88:91], v[142:145], v[192:195], v[88:91]
	v_mfma_f32_16x16x32_bf16 v[76:79], v[134:137], v[204:207], v[76:79]
	v_mfma_f32_16x16x32_bf16 v[72:75], v[142:145], v[204:207], v[72:75]
	v_mfma_f32_16x16x32_bf16 v[116:119], v[156:159], v[172:175], v[116:119]
	v_mfma_f32_16x16x32_bf16 v[112:115], v[164:167], v[172:175], v[112:115]
	v_mfma_f32_16x16x32_bf16 v[100:103], v[156:159], v[180:183], v[100:103]
	v_mfma_f32_16x16x32_bf16 v[96:99], v[164:167], v[180:183], v[96:99]
	v_mfma_f32_16x16x32_bf16 v[84:87], v[156:159], v[188:191], v[84:87]
	v_mfma_f32_16x16x32_bf16 v[80:83], v[164:167], v[188:191], v[80:83]
	v_mfma_f32_16x16x32_bf16 v[68:71], v[156:159], v[196:199], v[68:71]
	v_mfma_f32_16x16x32_bf16 v[64:67], v[164:167], v[196:199], v[64:67]
	v_mfma_f32_16x16x32_bf16 v[116:119], v[160:163], v[176:179], v[116:119]
	v_mfma_f32_16x16x32_bf16 v[112:115], v[168:171], v[176:179], v[112:115]
	v_mfma_f32_16x16x32_bf16 v[100:103], v[160:163], v[184:187], v[100:103]
	v_mfma_f32_16x16x32_bf16 v[96:99], v[168:171], v[184:187], v[96:99]
	v_mfma_f32_16x16x32_bf16 v[84:87], v[160:163], v[192:195], v[84:87]
	v_mfma_f32_16x16x32_bf16 v[80:83], v[168:171], v[192:195], v[80:83]
	v_mfma_f32_16x16x32_bf16 v[68:71], v[160:163], v[204:207], v[68:71]
	v_mfma_f32_16x16x32_bf16 v[64:67], v[168:171], v[204:207], v[64:67]
	s_barrier
	s_add_i32 s8, s8, s14
	v_lshl_add_u64 v[208:209], v[208:209], 0, s[90:91]
	s_mov_b32 m0, s8
	ds_read_b128 v[172:175], v203 offset:49152
	ds_read_b128 v[176:179], v203 offset:50176
	ds_read_b128 v[180:183], v203 offset:51200
	ds_read_b128 v[184:187], v203 offset:52224
	ds_read_b128 v[188:191], v203 offset:53248
	ds_read_b128 v[192:195], v203 offset:54272
	ds_read_b128 v[196:199], v203 offset:55296
	ds_read_b128 v[204:207], v203 offset:56320
	global_load_lds_dwordx4 v[208:209], off
	s_add_i32 m0, s8, 0x2000
	s_add_u32 s46, s46, 0xb0080
	v_lshl_add_u64 v[208:209], v[210:211], 0, s[90:91]
	s_addc_u32 s47, s47, 0
	s_add_i32 s8, s85, s14
	global_load_lds_dwordx4 v[208:209], off
	v_lshl_add_u64 v[208:209], s[46:47], 0, v[128:129]
	s_mov_b32 m0, s8
	s_nop 0
	global_load_lds_dwordx4 v[208:209], off
	v_lshl_add_u64 v[208:209], s[46:47], 0, v[146:147]
	s_add_i32 m0, s8, 0x2000
	s_nop 0
	global_load_lds_dwordx4 v[208:209], off
	v_lshl_add_u64 v[208:209], v[214:215], 0, s[90:91]
	s_mov_b32 m0, s29
	s_nop 0
	global_load_lds_dwordx4 v[208:209], off
	v_lshl_add_u64 v[208:209], v[222:223], 0, s[90:91]
	s_mov_b32 m0, s30
	s_nop 0
	global_load_lds_dwordx4 v[208:209], off
	s_waitcnt vmcnt(8)
	s_waitcnt lgkmcnt(0)
	s_barrier
	s_waitcnt lgkmcnt(0)
	v_mfma_f32_16x16x32_bf16 v[60:63], v[130:133], v[172:175], v[60:63]
	v_mfma_f32_16x16x32_bf16 v[56:59], v[138:141], v[172:175], v[56:59]
	v_mfma_f32_16x16x32_bf16 v[44:47], v[130:133], v[180:183], v[44:47]
	v_mfma_f32_16x16x32_bf16 v[40:43], v[138:141], v[180:183], v[40:43]
	v_mfma_f32_16x16x32_bf16 v[28:31], v[130:133], v[188:191], v[28:31]
	v_mfma_f32_16x16x32_bf16 v[24:27], v[138:141], v[188:191], v[24:27]
	v_mfma_f32_16x16x32_bf16 v[12:15], v[130:133], v[196:199], v[12:15]
	v_mfma_f32_16x16x32_bf16 v[8:11], v[138:141], v[196:199], v[8:11]
	v_mfma_f32_16x16x32_bf16 v[60:63], v[134:137], v[176:179], v[60:63]
	v_mfma_f32_16x16x32_bf16 v[56:59], v[142:145], v[176:179], v[56:59]
	v_mfma_f32_16x16x32_bf16 v[44:47], v[134:137], v[184:187], v[44:47]
	v_mfma_f32_16x16x32_bf16 v[40:43], v[142:145], v[184:187], v[40:43]
	v_mfma_f32_16x16x32_bf16 v[28:31], v[134:137], v[192:195], v[28:31]
	v_mfma_f32_16x16x32_bf16 v[24:27], v[142:145], v[192:195], v[24:27]
	v_mfma_f32_16x16x32_bf16 v[12:15], v[134:137], v[204:207], v[12:15]
	v_mfma_f32_16x16x32_bf16 v[8:11], v[142:145], v[204:207], v[8:11]
	v_mfma_f32_16x16x32_bf16 v[52:55], v[156:159], v[172:175], v[52:55]
	v_mfma_f32_16x16x32_bf16 v[48:51], v[164:167], v[172:175], v[48:51]
	v_mfma_f32_16x16x32_bf16 v[36:39], v[156:159], v[180:183], v[36:39]
	v_mfma_f32_16x16x32_bf16 v[32:35], v[164:167], v[180:183], v[32:35]
	v_mfma_f32_16x16x32_bf16 v[20:23], v[156:159], v[188:191], v[20:23]
	v_mfma_f32_16x16x32_bf16 v[16:19], v[164:167], v[188:191], v[16:19]
	v_mfma_f32_16x16x32_bf16 v[4:7], v[156:159], v[196:199], v[4:7]
	v_mfma_f32_16x16x32_bf16 v[0:3], v[164:167], v[196:199], v[0:3]
	v_mfma_f32_16x16x32_bf16 v[52:55], v[160:163], v[176:179], v[52:55]
	v_mfma_f32_16x16x32_bf16 v[48:51], v[168:171], v[176:179], v[48:51]
	v_mfma_f32_16x16x32_bf16 v[36:39], v[160:163], v[184:187], v[36:39]
	v_mfma_f32_16x16x32_bf16 v[32:35], v[168:171], v[184:187], v[32:35]
	v_mfma_f32_16x16x32_bf16 v[20:23], v[160:163], v[192:195], v[20:23]
	v_mfma_f32_16x16x32_bf16 v[16:19], v[168:171], v[192:195], v[16:19]
	v_mfma_f32_16x16x32_bf16 v[4:7], v[160:163], v[204:207], v[4:7]
	v_mfma_f32_16x16x32_bf16 v[0:3], v[168:171], v[204:207], v[0:3]
	s_barrier
	s_add_i32 s84, s84, 2
	s_add_u32 s36, s36, 0x100
	s_addc_u32 s37, s37, 0
	s_cmp_gt_u32 s84, 41
	s_mov_b64 s[96:97], s[42:43]
	s_cbranch_scc0 .LBB0_995
	s_setprio 0
	s_and_b64 vcc, exec, s[62:63]
	s_cbranch_vccz .LBB0_998
	s_barrier
